# K-loops: staged lgkmcnt waits before the first MFMA needing each fragment instead of one wait for all reads
# baseline (speedup 1.0000x reference)
.LBB0_57:
	s_add_u32 s22, s0, 0xfffc0080
	s_addc_u32 s23, s1, -1
	s_add_i32 s65, 0, 0x10000
	v_add_u32_e32 v142, s65, v178
	ds_read_b128 v[130:133], v142
	ds_read_b128 v[134:137], v142 offset:1024
	ds_read_b128 v[138:141], v142 offset:2048
	ds_read_b128 v[142:145], v142 offset:3072
	s_cmp_eq_u32 s64, 12
	s_cselect_b32 s49, s37, s23
	s_cselect_b32 s48, s60, s22
	s_cselect_b32 s23, s35, s63
	s_cselect_b32 s22, s61, s62
	v_lshl_add_u64 v[186:187], s[0:1], 0, v[168:169]
	s_add_i32 m0, s47, 0xc000
	ds_read_b128 v[172:175], v180
	ds_read_b128 v[182:185], v180 offset:1024
	ds_read_b128 v[206:209], v180 offset:2048
	ds_read_b128 v[210:213], v180 offset:3072
	ds_read_b128 v[214:217], v180 offset:4096
	ds_read_b128 v[218:221], v180 offset:5120
	ds_read_b128 v[222:225], v180 offset:6144
	ds_read_b128 v[226:229], v180 offset:7168
	global_load_lds_dwordx4 v[186:187], off
	v_lshl_add_u64 v[186:187], s[0:1], 0, v[170:171]
	s_add_i32 m0, s47, 0xe000
	s_nop 0
	global_load_lds_dwordx4 v[186:187], off
	s_waitcnt lgkmcnt(8)
	s_barrier
	s_setprio 1
	s_waitcnt lgkmcnt(7)
	v_mfma_f32_16x16x32_bf16 v[126:129], v[130:133], v[172:175], v[126:129]
	v_mfma_f32_16x16x32_bf16 v[122:125], v[138:141], v[172:175], v[122:125]
	s_waitcnt lgkmcnt(5)
	v_mfma_f32_16x16x32_bf16 v[114:117], v[130:133], v[206:209], v[114:117]
	v_mfma_f32_16x16x32_bf16 v[106:109], v[138:141], v[206:209], v[106:109]
	s_waitcnt lgkmcnt(3)
	v_mfma_f32_16x16x32_bf16 v[98:101], v[130:133], v[214:217], v[98:101]
	v_mfma_f32_16x16x32_bf16 v[90:93], v[138:141], v[214:217], v[90:93]
	s_waitcnt lgkmcnt(1)
	v_mfma_f32_16x16x32_bf16 v[82:85], v[130:133], v[222:225], v[82:85]
	v_mfma_f32_16x16x32_bf16 v[74:77], v[138:141], v[222:225], v[74:77]
	v_mfma_f32_16x16x32_bf16 v[126:129], v[134:137], v[182:185], v[126:129]
	v_mfma_f32_16x16x32_bf16 v[122:125], v[142:145], v[182:185], v[122:125]
	v_mfma_f32_16x16x32_bf16 v[114:117], v[134:137], v[210:213], v[114:117]
	v_mfma_f32_16x16x32_bf16 v[106:109], v[142:145], v[210:213], v[106:109]
	v_mfma_f32_16x16x32_bf16 v[98:101], v[134:137], v[218:221], v[98:101]
	v_mfma_f32_16x16x32_bf16 v[90:93], v[142:145], v[218:221], v[90:93]
	s_waitcnt lgkmcnt(0)
	v_mfma_f32_16x16x32_bf16 v[82:85], v[134:137], v[226:229], v[82:85]
	v_mfma_f32_16x16x32_bf16 v[74:77], v[142:145], v[226:229], v[74:77]
	s_barrier
	s_setprio 0
	s_add_i32 s68, 0, 0x14000
	s_add_i32 s65, s65, s27
	v_add_u32_e32 v181, s68, v178
	v_lshl_add_u64 v[186:187], s[22:23], 0, v[0:1]
	s_mov_b32 m0, s65
	ds_read_b128 v[230:233], v181
	ds_read_b128 v[234:237], v181 offset:1024
	ds_read_b128 v[238:241], v181 offset:2048
	ds_read_b128 v[242:245], v181 offset:3072
	global_load_lds_dwordx4 v[186:187], off
	v_lshl_add_u64 v[246:247], s[22:23], 0, v[166:167]
	s_add_i32 m0, s65, 0x2000
	s_nop 0
	global_load_lds_dwordx4 v[246:247], off
	s_barrier
	s_setprio 1
	s_waitcnt lgkmcnt(3)
	v_mfma_f32_16x16x32_bf16 v[118:121], v[230:233], v[172:175], v[118:121]
	s_waitcnt lgkmcnt(1)
	v_mfma_f32_16x16x32_bf16 v[110:113], v[238:241], v[172:175], v[110:113]
	v_mfma_f32_16x16x32_bf16 v[102:105], v[230:233], v[206:209], v[102:105]
	v_mfma_f32_16x16x32_bf16 v[94:97], v[238:241], v[206:209], v[94:97]
	v_mfma_f32_16x16x32_bf16 v[86:89], v[230:233], v[214:217], v[86:89]
	v_mfma_f32_16x16x32_bf16 v[78:81], v[238:241], v[214:217], v[78:81]
	v_mfma_f32_16x16x32_bf16 v[70:73], v[230:233], v[222:225], v[70:73]
	v_mfma_f32_16x16x32_bf16 v[66:69], v[238:241], v[222:225], v[66:69]
	v_mfma_f32_16x16x32_bf16 v[118:121], v[234:237], v[182:185], v[118:121]
	s_waitcnt lgkmcnt(0)
	v_mfma_f32_16x16x32_bf16 v[110:113], v[242:245], v[182:185], v[110:113]
	v_mfma_f32_16x16x32_bf16 v[102:105], v[234:237], v[210:213], v[102:105]
	v_mfma_f32_16x16x32_bf16 v[94:97], v[242:245], v[210:213], v[94:97]
	v_mfma_f32_16x16x32_bf16 v[86:89], v[234:237], v[218:221], v[86:89]
	v_mfma_f32_16x16x32_bf16 v[78:81], v[242:245], v[218:221], v[78:81]
	v_mfma_f32_16x16x32_bf16 v[70:73], v[234:237], v[226:229], v[70:73]
	v_mfma_f32_16x16x32_bf16 v[66:69], v[242:245], v[226:229], v[66:69]
	s_barrier
	s_setprio 0
	s_mov_b32 m0, s47
	v_lshl_add_u64 v[248:249], s[48:49], 0, v[162:163]
	ds_read_b128 v[172:175], v180 offset:16384
	ds_read_b128 v[182:185], v180 offset:17408
	ds_read_b128 v[206:209], v180 offset:18432
	ds_read_b128 v[210:213], v180 offset:19456
	ds_read_b128 v[214:217], v180 offset:20480
	ds_read_b128 v[218:221], v180 offset:21504
	ds_read_b128 v[222:225], v180 offset:22528
	ds_read_b128 v[226:229], v180 offset:23552
	global_load_lds_dwordx4 v[248:249], off
	v_lshl_add_u64 v[250:251], s[48:49], 0, v[164:165]
	s_mov_b32 m0, s50
	s_nop 0
	global_load_lds_dwordx4 v[250:251], off
	s_barrier
	s_setprio 1
	s_waitcnt lgkmcnt(7)
	v_mfma_f32_16x16x32_bf16 v[62:65], v[130:133], v[172:175], v[62:65]
	v_mfma_f32_16x16x32_bf16 v[58:61], v[138:141], v[172:175], v[58:61]
	s_waitcnt lgkmcnt(5)
	v_mfma_f32_16x16x32_bf16 v[50:53], v[130:133], v[206:209], v[50:53]
	v_mfma_f32_16x16x32_bf16 v[42:45], v[138:141], v[206:209], v[42:45]
	s_waitcnt lgkmcnt(3)
	v_mfma_f32_16x16x32_bf16 v[34:37], v[130:133], v[214:217], v[34:37]
	v_mfma_f32_16x16x32_bf16 v[26:29], v[138:141], v[214:217], v[26:29]
	s_waitcnt lgkmcnt(1)
	v_mfma_f32_16x16x32_bf16 v[18:21], v[130:133], v[222:225], v[18:21]
	v_mfma_f32_16x16x32_bf16 v[10:13], v[138:141], v[222:225], v[10:13]
	v_mfma_f32_16x16x32_bf16 v[62:65], v[134:137], v[182:185], v[62:65]
	v_mfma_f32_16x16x32_bf16 v[58:61], v[142:145], v[182:185], v[58:61]
	v_mfma_f32_16x16x32_bf16 v[50:53], v[134:137], v[210:213], v[50:53]
	v_mfma_f32_16x16x32_bf16 v[42:45], v[142:145], v[210:213], v[42:45]
	v_mfma_f32_16x16x32_bf16 v[34:37], v[134:137], v[218:221], v[34:37]
	v_mfma_f32_16x16x32_bf16 v[26:29], v[142:145], v[218:221], v[26:29]
	s_waitcnt lgkmcnt(0)
	v_mfma_f32_16x16x32_bf16 v[18:21], v[134:137], v[226:229], v[18:21]
	v_mfma_f32_16x16x32_bf16 v[10:13], v[142:145], v[226:229], v[10:13]
	s_barrier
	s_setprio 0
	s_add_u32 s66, s22, 0x40000
	s_addc_u32 s67, s23, 0
	s_add_i32 s65, s68, s27
	v_lshl_add_u64 v[130:131], s[66:67], 0, v[0:1]
	s_mov_b32 m0, s65
	s_nop 0
	global_load_lds_dwordx4 v[130:131], off
	v_lshl_add_u64 v[130:131], s[66:67], 0, v[166:167]
	s_add_i32 m0, s65, 0x2000
	s_nop 0
	global_load_lds_dwordx4 v[130:131], off
	s_waitcnt vmcnt(6)
	s_barrier
	s_setprio 1
	v_mfma_f32_16x16x32_bf16 v[54:57], v[230:233], v[172:175], v[54:57]
	v_mfma_f32_16x16x32_bf16 v[46:49], v[238:241], v[172:175], v[46:49]
	v_mfma_f32_16x16x32_bf16 v[38:41], v[230:233], v[206:209], v[38:41]
	v_mfma_f32_16x16x32_bf16 v[30:33], v[238:241], v[206:209], v[30:33]
	v_mfma_f32_16x16x32_bf16 v[22:25], v[230:233], v[214:217], v[22:25]
	v_mfma_f32_16x16x32_bf16 v[14:17], v[238:241], v[214:217], v[14:17]
	v_mfma_f32_16x16x32_bf16 v[6:9], v[230:233], v[222:225], v[6:9]
	v_mfma_f32_16x16x32_bf16 v[2:5], v[238:241], v[222:225], v[2:5]
	v_mfma_f32_16x16x32_bf16 v[54:57], v[234:237], v[182:185], v[54:57]
	v_mfma_f32_16x16x32_bf16 v[46:49], v[242:245], v[182:185], v[46:49]
	v_mfma_f32_16x16x32_bf16 v[38:41], v[234:237], v[210:213], v[38:41]
	v_mfma_f32_16x16x32_bf16 v[30:33], v[242:245], v[210:213], v[30:33]
	v_mfma_f32_16x16x32_bf16 v[22:25], v[234:237], v[218:221], v[22:25]
	v_mfma_f32_16x16x32_bf16 v[14:17], v[242:245], v[218:221], v[14:17]
	v_mfma_f32_16x16x32_bf16 v[6:9], v[234:237], v[226:229], v[6:9]
	v_mfma_f32_16x16x32_bf16 v[2:5], v[242:245], v[226:229], v[2:5]
	s_barrier
	s_setprio 0
	s_add_i32 s65, 0, 0x18000
	v_add_u32_e32 v142, s65, v178
	ds_read_b128 v[130:133], v142
	ds_read_b128 v[134:137], v142 offset:1024
	ds_read_b128 v[138:141], v142 offset:2048
	ds_read_b128 v[142:145], v142 offset:3072
	s_add_u32 s48, s48, 0x40000
	s_addc_u32 s49, s49, 0
	s_mov_b32 m0, s51
	v_lshl_add_u64 v[230:231], s[48:49], 0, v[162:163]
	ds_read_b128 v[172:175], v180 offset:32768
	ds_read_b128 v[182:185], v180 offset:33792
	ds_read_b128 v[206:209], v180 offset:34816
	ds_read_b128 v[210:213], v180 offset:35840
	ds_read_b128 v[214:217], v180 offset:36864
	ds_read_b128 v[218:221], v180 offset:37888
	ds_read_b128 v[222:225], v180 offset:38912
	ds_read_b128 v[226:229], v180 offset:39936
	global_load_lds_dwordx4 v[230:231], off
	v_lshl_add_u64 v[230:231], s[48:49], 0, v[164:165]
	s_mov_b32 m0, s54
	s_nop 0
	global_load_lds_dwordx4 v[230:231], off
	s_waitcnt lgkmcnt(8)
	s_barrier
	s_setprio 1
	s_waitcnt lgkmcnt(7)
	v_mfma_f32_16x16x32_bf16 v[126:129], v[130:133], v[172:175], v[126:129]
	v_mfma_f32_16x16x32_bf16 v[122:125], v[138:141], v[172:175], v[122:125]
	s_waitcnt lgkmcnt(5)
	v_mfma_f32_16x16x32_bf16 v[114:117], v[130:133], v[206:209], v[114:117]
	v_mfma_f32_16x16x32_bf16 v[106:109], v[138:141], v[206:209], v[106:109]
	s_waitcnt lgkmcnt(3)
	v_mfma_f32_16x16x32_bf16 v[98:101], v[130:133], v[214:217], v[98:101]
	v_mfma_f32_16x16x32_bf16 v[90:93], v[138:141], v[214:217], v[90:93]
	s_waitcnt lgkmcnt(1)
	v_mfma_f32_16x16x32_bf16 v[82:85], v[130:133], v[222:225], v[82:85]
	v_mfma_f32_16x16x32_bf16 v[74:77], v[138:141], v[222:225], v[74:77]
	v_mfma_f32_16x16x32_bf16 v[126:129], v[134:137], v[182:185], v[126:129]
	v_mfma_f32_16x16x32_bf16 v[122:125], v[142:145], v[182:185], v[122:125]
	v_mfma_f32_16x16x32_bf16 v[114:117], v[134:137], v[210:213], v[114:117]
	v_mfma_f32_16x16x32_bf16 v[106:109], v[142:145], v[210:213], v[106:109]
	v_mfma_f32_16x16x32_bf16 v[98:101], v[134:137], v[218:221], v[98:101]
	v_mfma_f32_16x16x32_bf16 v[90:93], v[142:145], v[218:221], v[90:93]
	s_waitcnt lgkmcnt(0)
	v_mfma_f32_16x16x32_bf16 v[82:85], v[134:137], v[226:229], v[82:85]
	v_mfma_f32_16x16x32_bf16 v[74:77], v[142:145], v[226:229], v[74:77]
	s_barrier
	s_setprio 0
	s_add_i32 s48, 0, 0x1c000
	s_add_i32 s49, s65, s27
	v_add_u32_e32 v181, s48, v178
	v_lshl_add_u64 v[186:187], v[186:187], 0, s[94:95]
	s_mov_b32 m0, s49
	ds_read_b128 v[230:233], v181
	ds_read_b128 v[234:237], v181 offset:1024
	ds_read_b128 v[238:241], v181 offset:2048
	ds_read_b128 v[242:245], v181 offset:3072
	global_load_lds_dwordx4 v[186:187], off
	v_lshl_add_u64 v[186:187], v[246:247], 0, s[94:95]
	s_add_i32 m0, s49, 0x2000
	s_nop 0
	global_load_lds_dwordx4 v[186:187], off
	s_barrier
	s_setprio 1
	s_waitcnt lgkmcnt(3)
	v_mfma_f32_16x16x32_bf16 v[118:121], v[230:233], v[172:175], v[118:121]
	s_waitcnt lgkmcnt(1)
	v_mfma_f32_16x16x32_bf16 v[110:113], v[238:241], v[172:175], v[110:113]
	v_mfma_f32_16x16x32_bf16 v[102:105], v[230:233], v[206:209], v[102:105]
	v_mfma_f32_16x16x32_bf16 v[94:97], v[238:241], v[206:209], v[94:97]
	v_mfma_f32_16x16x32_bf16 v[86:89], v[230:233], v[214:217], v[86:89]
	v_mfma_f32_16x16x32_bf16 v[78:81], v[238:241], v[214:217], v[78:81]
	v_mfma_f32_16x16x32_bf16 v[70:73], v[230:233], v[222:225], v[70:73]
	v_mfma_f32_16x16x32_bf16 v[66:69], v[238:241], v[222:225], v[66:69]
	v_mfma_f32_16x16x32_bf16 v[118:121], v[234:237], v[182:185], v[118:121]
	s_waitcnt lgkmcnt(0)
	v_mfma_f32_16x16x32_bf16 v[110:113], v[242:245], v[182:185], v[110:113]
	v_mfma_f32_16x16x32_bf16 v[102:105], v[234:237], v[210:213], v[102:105]
	v_mfma_f32_16x16x32_bf16 v[94:97], v[242:245], v[210:213], v[94:97]
	v_mfma_f32_16x16x32_bf16 v[86:89], v[234:237], v[218:221], v[86:89]
	v_mfma_f32_16x16x32_bf16 v[78:81], v[242:245], v[218:221], v[78:81]
	v_mfma_f32_16x16x32_bf16 v[70:73], v[234:237], v[226:229], v[70:73]
	v_mfma_f32_16x16x32_bf16 v[66:69], v[242:245], v[226:229], v[66:69]
	s_barrier
	s_setprio 0
	s_mov_b32 m0, s55
	v_lshl_add_u64 v[186:187], v[248:249], 0, s[94:95]
	ds_read_b128 v[172:175], v180 offset:49152
	ds_read_b128 v[182:185], v180 offset:50176
	ds_read_b128 v[206:209], v180 offset:51200
	ds_read_b128 v[210:213], v180 offset:52224
	ds_read_b128 v[214:217], v180 offset:53248
	ds_read_b128 v[218:221], v180 offset:54272
	ds_read_b128 v[222:225], v180 offset:55296
	ds_read_b128 v[226:229], v180 offset:56320
	global_load_lds_dwordx4 v[186:187], off
	v_lshl_add_u64 v[186:187], v[250:251], 0, s[94:95]
	s_mov_b32 m0, s56
	s_nop 0
	global_load_lds_dwordx4 v[186:187], off
	s_barrier
	s_setprio 1
	s_waitcnt lgkmcnt(7)
	v_mfma_f32_16x16x32_bf16 v[62:65], v[130:133], v[172:175], v[62:65]
	v_mfma_f32_16x16x32_bf16 v[58:61], v[138:141], v[172:175], v[58:61]
	s_waitcnt lgkmcnt(5)
	v_mfma_f32_16x16x32_bf16 v[50:53], v[130:133], v[206:209], v[50:53]
	v_mfma_f32_16x16x32_bf16 v[42:45], v[138:141], v[206:209], v[42:45]
	s_waitcnt lgkmcnt(3)
	v_mfma_f32_16x16x32_bf16 v[34:37], v[130:133], v[214:217], v[34:37]
	v_mfma_f32_16x16x32_bf16 v[26:29], v[138:141], v[214:217], v[26:29]
	s_waitcnt lgkmcnt(1)
	v_mfma_f32_16x16x32_bf16 v[18:21], v[130:133], v[222:225], v[18:21]
	v_mfma_f32_16x16x32_bf16 v[10:13], v[138:141], v[222:225], v[10:13]
	v_mfma_f32_16x16x32_bf16 v[62:65], v[134:137], v[182:185], v[62:65]
	v_mfma_f32_16x16x32_bf16 v[58:61], v[142:145], v[182:185], v[58:61]
	v_mfma_f32_16x16x32_bf16 v[50:53], v[134:137], v[210:213], v[50:53]
	v_mfma_f32_16x16x32_bf16 v[42:45], v[142:145], v[210:213], v[42:45]
	v_mfma_f32_16x16x32_bf16 v[34:37], v[134:137], v[218:221], v[34:37]
	v_mfma_f32_16x16x32_bf16 v[26:29], v[142:145], v[218:221], v[26:29]
	s_waitcnt lgkmcnt(0)
	v_mfma_f32_16x16x32_bf16 v[18:21], v[134:137], v[226:229], v[18:21]
	v_mfma_f32_16x16x32_bf16 v[10:13], v[142:145], v[226:229], v[10:13]
	s_barrier
	s_setprio 0
	s_add_u32 s22, s22, 0x40080
	s_addc_u32 s23, s23, 0
	s_add_i32 s48, s48, s27
	v_lshl_add_u64 v[130:131], s[22:23], 0, v[0:1]
	s_mov_b32 m0, s48
	s_nop 0
	global_load_lds_dwordx4 v[130:131], off
	v_lshl_add_u64 v[130:131], s[22:23], 0, v[166:167]
	s_add_i32 m0, s48, 0x2000
	s_nop 0
	global_load_lds_dwordx4 v[130:131], off
	s_waitcnt vmcnt(6)
	s_barrier
	s_setprio 1
	v_mfma_f32_16x16x32_bf16 v[54:57], v[230:233], v[172:175], v[54:57]
	v_mfma_f32_16x16x32_bf16 v[46:49], v[238:241], v[172:175], v[46:49]
	v_mfma_f32_16x16x32_bf16 v[38:41], v[230:233], v[206:209], v[38:41]
	v_mfma_f32_16x16x32_bf16 v[30:33], v[238:241], v[206:209], v[30:33]
	v_mfma_f32_16x16x32_bf16 v[22:25], v[230:233], v[214:217], v[22:25]
	v_mfma_f32_16x16x32_bf16 v[14:17], v[238:241], v[214:217], v[14:17]
	v_mfma_f32_16x16x32_bf16 v[6:9], v[230:233], v[222:225], v[6:9]
	v_mfma_f32_16x16x32_bf16 v[2:5], v[238:241], v[222:225], v[2:5]
	v_mfma_f32_16x16x32_bf16 v[54:57], v[234:237], v[182:185], v[54:57]
	v_mfma_f32_16x16x32_bf16 v[46:49], v[242:245], v[182:185], v[46:49]
	v_mfma_f32_16x16x32_bf16 v[38:41], v[234:237], v[210:213], v[38:41]
	v_mfma_f32_16x16x32_bf16 v[30:33], v[242:245], v[210:213], v[30:33]
	v_mfma_f32_16x16x32_bf16 v[22:25], v[234:237], v[218:221], v[22:25]
	v_mfma_f32_16x16x32_bf16 v[14:17], v[242:245], v[218:221], v[14:17]
	v_mfma_f32_16x16x32_bf16 v[6:9], v[234:237], v[226:229], v[6:9]
	v_mfma_f32_16x16x32_bf16 v[2:5], v[242:245], v[226:229], v[2:5]
	s_barrier
	s_setprio 0
	s_add_i32 s64, s64, 2
	s_add_u32 s0, s0, 0x100
	s_addc_u32 s1, s1, 0
	s_add_u32 s62, s62, 0x100
	s_addc_u32 s63, s63, 0
	s_cmp_gt_u32 s64, 13
	s_cbranch_scc0 .LBB0_57
	v_lshl_or_b32 v172, s59, 8, v179
	v_ashrrev_i32_e32 v173, 31, v172
	v_cndmask_b32_e64 v131, 0, 1, s[2:3]
	v_lshl_add_u64 v[174:175], v[172:173], 2, s[8:9]
	v_mov_b32_e32 v130, 0
	v_cmp_ne_u32_e64 s[0:1], 1, v131
	s_andn2_b64 vcc, exec, s[2:3]
	v_mov_b32_e32 v134, 0
	v_mov_b32_e32 v135, 0
	v_mov_b32_e32 v136, 0
	v_mov_b32_e32 v137, 0
	s_cbranch_vccnz .LBB0_60
	global_load_dwordx4 v[134:137], v[174:175], off

.LBB0_95:
	s_add_u32 s22, s8, 0xfffc0080
	s_addc_u32 s23, s9, -1
	s_add_i32 s63, 0, 0x10000
	v_add_u32_e32 v78, s63, v178
	ds_read_b128 v[58:61], v78
	ds_read_b128 v[66:69], v78 offset:1024
	ds_read_b128 v[74:77], v78 offset:2048
	ds_read_b128 v[78:81], v78 offset:3072
	s_cmp_eq_u32 s49, 12
	s_cselect_b32 s29, s25, s23
	s_cselect_b32 s28, s26, s22
	s_cselect_b32 s23, s27, s47
	s_cselect_b32 s22, s30, s31
	v_lshl_add_u64 v[186:187], s[8:9], 0, v[168:169]
	s_add_i32 m0, s3, 0xc000
	ds_read_b128 v[172:175], v180
	ds_read_b128 v[182:185], v180 offset:1024
	ds_read_b128 v[206:209], v180 offset:2048
	ds_read_b128 v[210:213], v180 offset:3072
	ds_read_b128 v[214:217], v180 offset:4096
	ds_read_b128 v[218:221], v180 offset:5120
	ds_read_b128 v[222:225], v180 offset:6144
	ds_read_b128 v[226:229], v180 offset:7168
	global_load_lds_dwordx4 v[186:187], off
	v_lshl_add_u64 v[186:187], s[8:9], 0, v[170:171]
	s_add_i32 m0, s3, 0xe000
	s_nop 0
	global_load_lds_dwordx4 v[186:187], off
	s_waitcnt lgkmcnt(8)
	s_barrier
	s_setprio 1
	s_waitcnt lgkmcnt(7)
	v_mfma_f32_16x16x32_bf16 v[142:145], v[58:61], v[172:175], v[142:145]
	v_mfma_f32_16x16x32_bf16 v[138:141], v[74:77], v[172:175], v[138:141]
	s_waitcnt lgkmcnt(5)
	v_mfma_f32_16x16x32_bf16 v[126:129], v[58:61], v[206:209], v[126:129]
	v_mfma_f32_16x16x32_bf16 v[118:121], v[74:77], v[206:209], v[118:121]
	s_waitcnt lgkmcnt(3)
	v_mfma_f32_16x16x32_bf16 v[110:113], v[58:61], v[214:217], v[110:113]
	v_mfma_f32_16x16x32_bf16 v[102:105], v[74:77], v[214:217], v[102:105]
	s_waitcnt lgkmcnt(1)
	v_mfma_f32_16x16x32_bf16 v[94:97], v[58:61], v[222:225], v[94:97]
	v_mfma_f32_16x16x32_bf16 v[86:89], v[74:77], v[222:225], v[86:89]
	v_mfma_f32_16x16x32_bf16 v[142:145], v[66:69], v[182:185], v[142:145]
	v_mfma_f32_16x16x32_bf16 v[138:141], v[78:81], v[182:185], v[138:141]
	v_mfma_f32_16x16x32_bf16 v[126:129], v[66:69], v[210:213], v[126:129]
	v_mfma_f32_16x16x32_bf16 v[118:121], v[78:81], v[210:213], v[118:121]
	v_mfma_f32_16x16x32_bf16 v[110:113], v[66:69], v[218:221], v[110:113]
	v_mfma_f32_16x16x32_bf16 v[102:105], v[78:81], v[218:221], v[102:105]
	s_waitcnt lgkmcnt(0)
	v_mfma_f32_16x16x32_bf16 v[94:97], v[66:69], v[226:229], v[94:97]
	v_mfma_f32_16x16x32_bf16 v[86:89], v[78:81], v[226:229], v[86:89]
	s_barrier
	s_setprio 0
	s_add_i32 s66, 0, 0x14000
	s_add_i32 s63, s63, s37
	v_add_u32_e32 v181, s66, v178
	v_lshl_add_u64 v[186:187], s[22:23], 0, v[0:1]
	s_mov_b32 m0, s63
	ds_read_b128 v[230:233], v181
	ds_read_b128 v[234:237], v181 offset:1024
	ds_read_b128 v[238:241], v181 offset:2048
	ds_read_b128 v[242:245], v181 offset:3072
	global_load_lds_dwordx4 v[186:187], off
	v_lshl_add_u64 v[246:247], s[22:23], 0, v[166:167]
	s_add_i32 m0, s63, 0x2000
	s_nop 0
	global_load_lds_dwordx4 v[246:247], off
	s_barrier
	s_setprio 1
	s_waitcnt lgkmcnt(3)
	v_mfma_f32_16x16x32_bf16 v[134:137], v[230:233], v[172:175], v[134:137]
	s_waitcnt lgkmcnt(1)
	v_mfma_f32_16x16x32_bf16 v[130:133], v[238:241], v[172:175], v[130:133]
	v_mfma_f32_16x16x32_bf16 v[122:125], v[230:233], v[206:209], v[122:125]
	v_mfma_f32_16x16x32_bf16 v[114:117], v[238:241], v[206:209], v[114:117]
	v_mfma_f32_16x16x32_bf16 v[106:109], v[230:233], v[214:217], v[106:109]
	v_mfma_f32_16x16x32_bf16 v[98:101], v[238:241], v[214:217], v[98:101]
	v_mfma_f32_16x16x32_bf16 v[90:93], v[230:233], v[222:225], v[90:93]
	v_mfma_f32_16x16x32_bf16 v[82:85], v[238:241], v[222:225], v[82:85]
	v_mfma_f32_16x16x32_bf16 v[134:137], v[234:237], v[182:185], v[134:137]
	s_waitcnt lgkmcnt(0)
	v_mfma_f32_16x16x32_bf16 v[130:133], v[242:245], v[182:185], v[130:133]
	v_mfma_f32_16x16x32_bf16 v[122:125], v[234:237], v[210:213], v[122:125]
	v_mfma_f32_16x16x32_bf16 v[114:117], v[242:245], v[210:213], v[114:117]
	v_mfma_f32_16x16x32_bf16 v[106:109], v[234:237], v[218:221], v[106:109]
	v_mfma_f32_16x16x32_bf16 v[98:101], v[242:245], v[218:221], v[98:101]
	v_mfma_f32_16x16x32_bf16 v[90:93], v[234:237], v[226:229], v[90:93]
	v_mfma_f32_16x16x32_bf16 v[82:85], v[242:245], v[226:229], v[82:85]
	s_barrier
	s_setprio 0
	s_mov_b32 m0, s3
	v_lshl_add_u64 v[248:249], s[28:29], 0, v[162:163]
	ds_read_b128 v[172:175], v180 offset:16384
	ds_read_b128 v[182:185], v180 offset:17408
	ds_read_b128 v[206:209], v180 offset:18432
	ds_read_b128 v[210:213], v180 offset:19456
	ds_read_b128 v[214:217], v180 offset:20480
	ds_read_b128 v[218:221], v180 offset:21504
	ds_read_b128 v[222:225], v180 offset:22528
	ds_read_b128 v[226:229], v180 offset:23552
	global_load_lds_dwordx4 v[248:249], off
	v_lshl_add_u64 v[250:251], s[28:29], 0, v[164:165]
	s_mov_b32 m0, s56
	s_nop 0
	global_load_lds_dwordx4 v[250:251], off
	s_barrier
	s_setprio 1
	s_waitcnt lgkmcnt(7)
	v_mfma_f32_16x16x32_bf16 v[70:73], v[58:61], v[172:175], v[70:73]
	v_mfma_f32_16x16x32_bf16 v[54:57], v[74:77], v[172:175], v[54:57]
	s_waitcnt lgkmcnt(5)
	v_mfma_f32_16x16x32_bf16 v[46:49], v[58:61], v[206:209], v[46:49]
	v_mfma_f32_16x16x32_bf16 v[38:41], v[74:77], v[206:209], v[38:41]
	s_waitcnt lgkmcnt(3)
	v_mfma_f32_16x16x32_bf16 v[30:33], v[58:61], v[214:217], v[30:33]
	v_mfma_f32_16x16x32_bf16 v[22:25], v[74:77], v[214:217], v[22:25]
	s_waitcnt lgkmcnt(1)
	v_mfma_f32_16x16x32_bf16 v[14:17], v[58:61], v[222:225], v[14:17]
	v_mfma_f32_16x16x32_bf16 v[6:9], v[74:77], v[222:225], v[6:9]
	v_mfma_f32_16x16x32_bf16 v[70:73], v[66:69], v[182:185], v[70:73]
	v_mfma_f32_16x16x32_bf16 v[54:57], v[78:81], v[182:185], v[54:57]
	v_mfma_f32_16x16x32_bf16 v[46:49], v[66:69], v[210:213], v[46:49]
	v_mfma_f32_16x16x32_bf16 v[38:41], v[78:81], v[210:213], v[38:41]
	v_mfma_f32_16x16x32_bf16 v[30:33], v[66:69], v[218:221], v[30:33]
	v_mfma_f32_16x16x32_bf16 v[22:25], v[78:81], v[218:221], v[22:25]
	s_waitcnt lgkmcnt(0)
	v_mfma_f32_16x16x32_bf16 v[14:17], v[66:69], v[226:229], v[14:17]
	v_mfma_f32_16x16x32_bf16 v[6:9], v[78:81], v[226:229], v[6:9]
	s_barrier
	s_setprio 0
	s_add_u32 s64, s22, 0x40000
	s_addc_u32 s65, s23, 0
	s_add_i32 s63, s66, s37
	v_lshl_add_u64 v[58:59], s[64:65], 0, v[0:1]
	s_mov_b32 m0, s63
	s_nop 0
	global_load_lds_dwordx4 v[58:59], off
	v_lshl_add_u64 v[58:59], s[64:65], 0, v[166:167]
	s_add_i32 m0, s63, 0x2000
	s_nop 0
	global_load_lds_dwordx4 v[58:59], off
	s_waitcnt vmcnt(6)
	s_barrier
	s_setprio 1
	v_mfma_f32_16x16x32_bf16 v[50:53], v[238:241], v[172:175], v[50:53]
	v_mfma_f32_16x16x32_bf16 v[42:45], v[230:233], v[206:209], v[42:45]
	v_mfma_f32_16x16x32_bf16 v[34:37], v[238:241], v[206:209], v[34:37]
	v_mfma_f32_16x16x32_bf16 v[26:29], v[230:233], v[214:217], v[26:29]
	v_mfma_f32_16x16x32_bf16 v[18:21], v[238:241], v[214:217], v[18:21]
	v_mfma_f32_16x16x32_bf16 v[10:13], v[230:233], v[222:225], v[10:13]
	v_mfma_f32_16x16x32_bf16 v[2:5], v[238:241], v[222:225], v[2:5]
	v_mfma_f32_16x16x32_bf16 v[58:61], v[230:233], v[172:175], v[62:65]
	v_mfma_f32_16x16x32_bf16 v[50:53], v[242:245], v[182:185], v[50:53]
	v_mfma_f32_16x16x32_bf16 v[42:45], v[234:237], v[210:213], v[42:45]
	v_mfma_f32_16x16x32_bf16 v[34:37], v[242:245], v[210:213], v[34:37]
	v_mfma_f32_16x16x32_bf16 v[26:29], v[234:237], v[218:221], v[26:29]
	v_mfma_f32_16x16x32_bf16 v[18:21], v[242:245], v[218:221], v[18:21]
	v_mfma_f32_16x16x32_bf16 v[10:13], v[234:237], v[226:229], v[10:13]
	v_mfma_f32_16x16x32_bf16 v[2:5], v[242:245], v[226:229], v[2:5]
	v_mfma_f32_16x16x32_bf16 v[58:61], v[234:237], v[182:185], v[58:61]
	s_barrier
	s_setprio 0
	s_add_i32 s63, 0, 0x18000
	v_add_u32_e32 v78, s63, v178
	ds_read_b128 v[62:65], v78
	ds_read_b128 v[66:69], v78 offset:1024
	ds_read_b128 v[74:77], v78 offset:2048
	ds_read_b128 v[78:81], v78 offset:3072
	s_add_u32 s28, s28, 0x40000
	s_addc_u32 s29, s29, 0
	s_mov_b32 m0, s57
	v_lshl_add_u64 v[230:231], s[28:29], 0, v[162:163]
	ds_read_b128 v[172:175], v180 offset:32768
	ds_read_b128 v[182:185], v180 offset:33792
	ds_read_b128 v[206:209], v180 offset:34816
	ds_read_b128 v[210:213], v180 offset:35840
	ds_read_b128 v[214:217], v180 offset:36864
	ds_read_b128 v[218:221], v180 offset:37888
	ds_read_b128 v[222:225], v180 offset:38912
	ds_read_b128 v[226:229], v180 offset:39936
	global_load_lds_dwordx4 v[230:231], off
	v_lshl_add_u64 v[230:231], s[28:29], 0, v[164:165]
	s_mov_b32 m0, s58
	s_nop 0
	global_load_lds_dwordx4 v[230:231], off
	s_waitcnt lgkmcnt(8)
	s_barrier
	s_setprio 1
	s_waitcnt lgkmcnt(7)
	v_mfma_f32_16x16x32_bf16 v[142:145], v[62:65], v[172:175], v[142:145]
	v_mfma_f32_16x16x32_bf16 v[138:141], v[74:77], v[172:175], v[138:141]
	s_waitcnt lgkmcnt(5)
	v_mfma_f32_16x16x32_bf16 v[126:129], v[62:65], v[206:209], v[126:129]
	v_mfma_f32_16x16x32_bf16 v[118:121], v[74:77], v[206:209], v[118:121]
	s_waitcnt lgkmcnt(3)
	v_mfma_f32_16x16x32_bf16 v[110:113], v[62:65], v[214:217], v[110:113]
	v_mfma_f32_16x16x32_bf16 v[102:105], v[74:77], v[214:217], v[102:105]
	s_waitcnt lgkmcnt(1)
	v_mfma_f32_16x16x32_bf16 v[94:97], v[62:65], v[222:225], v[94:97]
	v_mfma_f32_16x16x32_bf16 v[86:89], v[74:77], v[222:225], v[86:89]
	v_mfma_f32_16x16x32_bf16 v[142:145], v[66:69], v[182:185], v[142:145]
	v_mfma_f32_16x16x32_bf16 v[138:141], v[78:81], v[182:185], v[138:141]
	v_mfma_f32_16x16x32_bf16 v[126:129], v[66:69], v[210:213], v[126:129]
	v_mfma_f32_16x16x32_bf16 v[118:121], v[78:81], v[210:213], v[118:121]
	v_mfma_f32_16x16x32_bf16 v[110:113], v[66:69], v[218:221], v[110:113]
	v_mfma_f32_16x16x32_bf16 v[102:105], v[78:81], v[218:221], v[102:105]
	s_waitcnt lgkmcnt(0)
	v_mfma_f32_16x16x32_bf16 v[94:97], v[66:69], v[226:229], v[94:97]
	v_mfma_f32_16x16x32_bf16 v[86:89], v[78:81], v[226:229], v[86:89]
	s_barrier
	s_setprio 0
	s_add_i32 s28, 0, 0x1c000
	s_add_i32 s29, s63, s37
	v_add_u32_e32 v181, s28, v178
	v_lshl_add_u64 v[186:187], v[186:187], 0, s[94:95]
	s_mov_b32 m0, s29
	ds_read_b128 v[230:233], v181
	ds_read_b128 v[234:237], v181 offset:1024
	ds_read_b128 v[238:241], v181 offset:2048
	ds_read_b128 v[242:245], v181 offset:3072
	global_load_lds_dwordx4 v[186:187], off
	v_lshl_add_u64 v[186:187], v[246:247], 0, s[94:95]
	s_add_i32 m0, s29, 0x2000
	s_nop 0
	global_load_lds_dwordx4 v[186:187], off
	s_barrier
	s_setprio 1
	s_waitcnt lgkmcnt(3)
	v_mfma_f32_16x16x32_bf16 v[134:137], v[230:233], v[172:175], v[134:137]
	s_waitcnt lgkmcnt(1)
	v_mfma_f32_16x16x32_bf16 v[130:133], v[238:241], v[172:175], v[130:133]
	v_mfma_f32_16x16x32_bf16 v[122:125], v[230:233], v[206:209], v[122:125]
	v_mfma_f32_16x16x32_bf16 v[114:117], v[238:241], v[206:209], v[114:117]
	v_mfma_f32_16x16x32_bf16 v[106:109], v[230:233], v[214:217], v[106:109]
	v_mfma_f32_16x16x32_bf16 v[98:101], v[238:241], v[214:217], v[98:101]
	v_mfma_f32_16x16x32_bf16 v[90:93], v[230:233], v[222:225], v[90:93]
	v_mfma_f32_16x16x32_bf16 v[82:85], v[238:241], v[222:225], v[82:85]
	v_mfma_f32_16x16x32_bf16 v[134:137], v[234:237], v[182:185], v[134:137]
	s_waitcnt lgkmcnt(0)
	v_mfma_f32_16x16x32_bf16 v[130:133], v[242:245], v[182:185], v[130:133]
	v_mfma_f32_16x16x32_bf16 v[122:125], v[234:237], v[210:213], v[122:125]
	v_mfma_f32_16x16x32_bf16 v[114:117], v[242:245], v[210:213], v[114:117]
	v_mfma_f32_16x16x32_bf16 v[106:109], v[234:237], v[218:221], v[106:109]
	v_mfma_f32_16x16x32_bf16 v[98:101], v[242:245], v[218:221], v[98:101]
	v_mfma_f32_16x16x32_bf16 v[90:93], v[234:237], v[226:229], v[90:93]
	v_mfma_f32_16x16x32_bf16 v[82:85], v[242:245], v[226:229], v[82:85]
	s_barrier
	s_setprio 0
	s_mov_b32 m0, s59
	v_lshl_add_u64 v[186:187], v[248:249], 0, s[94:95]
	ds_read_b128 v[172:175], v180 offset:49152
	ds_read_b128 v[182:185], v180 offset:50176
	ds_read_b128 v[206:209], v180 offset:51200
	ds_read_b128 v[210:213], v180 offset:52224
	ds_read_b128 v[214:217], v180 offset:53248
	ds_read_b128 v[218:221], v180 offset:54272
	ds_read_b128 v[222:225], v180 offset:55296
	ds_read_b128 v[226:229], v180 offset:56320
	global_load_lds_dwordx4 v[186:187], off
	v_lshl_add_u64 v[186:187], v[250:251], 0, s[94:95]
	s_mov_b32 m0, s60
	s_nop 0
	global_load_lds_dwordx4 v[186:187], off
	s_barrier
	s_setprio 1
	s_waitcnt lgkmcnt(7)
	v_mfma_f32_16x16x32_bf16 v[70:73], v[62:65], v[172:175], v[70:73]
	v_mfma_f32_16x16x32_bf16 v[54:57], v[74:77], v[172:175], v[54:57]
	s_waitcnt lgkmcnt(5)
	v_mfma_f32_16x16x32_bf16 v[46:49], v[62:65], v[206:209], v[46:49]
	v_mfma_f32_16x16x32_bf16 v[38:41], v[74:77], v[206:209], v[38:41]
	s_waitcnt lgkmcnt(3)
	v_mfma_f32_16x16x32_bf16 v[30:33], v[62:65], v[214:217], v[30:33]
	v_mfma_f32_16x16x32_bf16 v[22:25], v[74:77], v[214:217], v[22:25]
	s_waitcnt lgkmcnt(1)
	v_mfma_f32_16x16x32_bf16 v[14:17], v[62:65], v[222:225], v[14:17]
	v_mfma_f32_16x16x32_bf16 v[6:9], v[74:77], v[222:225], v[6:9]
	v_mfma_f32_16x16x32_bf16 v[70:73], v[66:69], v[182:185], v[70:73]
	v_mfma_f32_16x16x32_bf16 v[54:57], v[78:81], v[182:185], v[54:57]
	v_mfma_f32_16x16x32_bf16 v[46:49], v[66:69], v[210:213], v[46:49]
	v_mfma_f32_16x16x32_bf16 v[38:41], v[78:81], v[210:213], v[38:41]
	v_mfma_f32_16x16x32_bf16 v[30:33], v[66:69], v[218:221], v[30:33]
	v_mfma_f32_16x16x32_bf16 v[22:25], v[78:81], v[218:221], v[22:25]
	s_waitcnt lgkmcnt(0)
	v_mfma_f32_16x16x32_bf16 v[14:17], v[66:69], v[226:229], v[14:17]
	v_mfma_f32_16x16x32_bf16 v[6:9], v[78:81], v[226:229], v[6:9]
	s_barrier
	s_setprio 0
	s_add_u32 s22, s22, 0x40080
	s_addc_u32 s23, s23, 0
	s_add_i32 s28, s28, s37
	v_lshl_add_u64 v[62:63], s[22:23], 0, v[0:1]
	s_mov_b32 m0, s28
	s_nop 0
	global_load_lds_dwordx4 v[62:63], off
	v_lshl_add_u64 v[62:63], s[22:23], 0, v[166:167]
	s_add_i32 m0, s28, 0x2000
	s_nop 0
	global_load_lds_dwordx4 v[62:63], off
	s_waitcnt vmcnt(6)
	s_barrier
	s_setprio 1
	v_mfma_f32_16x16x32_bf16 v[58:61], v[230:233], v[172:175], v[58:61]
	v_mfma_f32_16x16x32_bf16 v[50:53], v[238:241], v[172:175], v[50:53]
	v_mfma_f32_16x16x32_bf16 v[42:45], v[230:233], v[206:209], v[42:45]
	v_mfma_f32_16x16x32_bf16 v[34:37], v[238:241], v[206:209], v[34:37]
	v_mfma_f32_16x16x32_bf16 v[26:29], v[230:233], v[214:217], v[26:29]
	v_mfma_f32_16x16x32_bf16 v[18:21], v[238:241], v[214:217], v[18:21]
	v_mfma_f32_16x16x32_bf16 v[10:13], v[230:233], v[222:225], v[10:13]
	v_mfma_f32_16x16x32_bf16 v[2:5], v[238:241], v[222:225], v[2:5]
	v_mfma_f32_16x16x32_bf16 v[62:65], v[234:237], v[182:185], v[58:61]
	v_mfma_f32_16x16x32_bf16 v[50:53], v[242:245], v[182:185], v[50:53]
	v_mfma_f32_16x16x32_bf16 v[42:45], v[234:237], v[210:213], v[42:45]
	v_mfma_f32_16x16x32_bf16 v[34:37], v[242:245], v[210:213], v[34:37]
	v_mfma_f32_16x16x32_bf16 v[26:29], v[234:237], v[218:221], v[26:29]
	v_mfma_f32_16x16x32_bf16 v[18:21], v[242:245], v[218:221], v[18:21]
	v_mfma_f32_16x16x32_bf16 v[10:13], v[234:237], v[226:229], v[10:13]
	v_mfma_f32_16x16x32_bf16 v[2:5], v[242:245], v[226:229], v[2:5]
	s_barrier
	s_setprio 0
	s_add_i32 s49, s49, 2
	s_add_u32 s8, s8, 0x100
	s_addc_u32 s9, s9, 0
	s_add_u32 s31, s31, 0x100
	s_addc_u32 s47, s47, 0
	s_cmp_gt_u32 s49, 13
	s_cbranch_scc0 .LBB0_95
	v_lshl_or_b32 v172, s24, 7, v179
	v_ashrrev_i32_e32 v173, 31, v172
	v_lshlrev_b64 v[58:59], 2, v[172:173]
	v_lshl_add_u64 v[60:61], s[40:41], 0, v[58:59]
	v_lshl_add_u64 v[74:75], s[44:45], 0, v[58:59]
	global_load_dwordx4 v[66:69], v[60:61], off offset:16
	global_load_dwordx4 v[78:81], v[60:61], off
	s_nop 0
	global_load_dwordx4 v[58:61], v[74:75], off offset:16
	s_nop 0
	global_load_dwordx4 v[74:77], v[74:75], off
	v_lshl_add_u32 v174, s2, 8, v177
	v_ashrrev_i32_e32 v175, 31, v174
	v_lshl_add_u64 v[172:173], v[172:173], 1, s[20:21]
	v_lshlrev_b64 v[182:183], 11, v[174:175]
	s_mov_b32 s2, 0x50000
	s_mov_b32 s24, s46
	s_mov_b64 s[22:23], s[54:55]
	s_mov_b64 s[8:9], s[50:51]
	s_waitcnt vmcnt(0)
	v_add_f32_e32 v138, v138, v66
	v_add_f32_e32 v126, v126, v78
	v_add_f32_e32 v130, v130, v58
	v_mul_f32_e32 v130, 0xbfb8aa3b, v130
	v_add_f32_e32 v131, v131, v59
	v_add_f32_e32 v122, v122, v74
	v_exp_f32_e32 v130, v130
	v_mul_f32_e32 v131, 0xbfb8aa3b, v131
	v_mul_f32_e32 v122, 0xbfb8aa3b, v122
	v_add_f32_e32 v123, v123, v75
	v_exp_f32_e32 v131, v131
	v_exp_f32_e32 v122, v122
	v_mul_f32_e32 v123, 0xbfb8aa3b, v123
	v_add_f32_e32 v124, v124, v76
	v_exp_f32_e32 v123, v123
	v_mul_f32_e32 v124, 0xbfb8aa3b, v124
	v_add_f32_e32 v125, v125, v77
	v_add_f32_e32 v114, v114, v58
	v_exp_f32_e32 v124, v124
	v_mul_f32_e32 v125, 0xbfb8aa3b, v125
	v_mul_f32_e32 v114, 0xbfb8aa3b, v114
	v_add_f32_e32 v115, v115, v59
	v_add_f32_e32 v106, v106, v74
	v_add_f32_e32 v130, 1.0, v130
	v_exp_f32_e32 v125, v125
	v_exp_f32_e32 v114, v114
	v_mul_f32_e32 v115, 0xbfb8aa3b, v115
	v_mul_f32_e32 v106, 0xbfb8aa3b, v106
	v_add_f32_e32 v107, v107, v75
	v_rcp_f32_e32 v130, v130
	v_add_f32_e32 v131, 1.0, v131
	v_add_f32_e32 v122, 1.0, v122
	v_exp_f32_e32 v115, v115
	v_exp_f32_e32 v106, v106
	v_mul_f32_e32 v107, 0xbfb8aa3b, v107
	v_add_f32_e32 v108, v108, v76
	v_rcp_f32_e32 v131, v131
	v_rcp_f32_e32 v122, v122
	v_add_f32_e32 v123, 1.0, v123
	v_exp_f32_e32 v107, v107
	v_mul_f32_e32 v108, 0xbfb8aa3b, v108
	v_add_f32_e32 v109, v109, v77
	v_add_f32_e32 v98, v98, v58
	v_rcp_f32_e32 v123, v123
	v_add_f32_e32 v124, 1.0, v124
	v_exp_f32_e32 v108, v108
	v_mul_f32_e32 v109, 0xbfb8aa3b, v109
	v_mul_f32_e32 v98, 0xbfb8aa3b, v98
	v_add_f32_e32 v99, v99, v59
	v_add_f32_e32 v90, v90, v74
	v_rcp_f32_e32 v124, v124
	v_add_f32_e32 v125, 1.0, v125
	v_add_f32_e32 v114, 1.0, v114
	v_exp_f32_e32 v109, v109
	v_exp_f32_e32 v98, v98
	v_mul_f32_e32 v99, 0xbfb8aa3b, v99
	v_mul_f32_e32 v90, 0xbfb8aa3b, v90
	v_add_f32_e32 v91, v91, v75
	v_mul_f32_e32 v138, v138, v130
	v_add_f32_e32 v130, v139, v67
	v_rcp_f32_e32 v125, v125
	v_rcp_f32_e32 v114, v114
	v_add_f32_e32 v115, 1.0, v115
	v_add_f32_e32 v106, 1.0, v106
	v_exp_f32_e32 v99, v99
	v_exp_f32_e32 v90, v90
	v_mul_f32_e32 v91, 0xbfb8aa3b, v91
	v_add_f32_e32 v92, v92, v76
	v_mul_f32_e32 v139, v130, v131
	v_add_f32_e32 v131, v132, v60
	v_mul_f32_e32 v122, v126, v122
	v_add_f32_e32 v126, v127, v79
	v_rcp_f32_e32 v115, v115
	v_rcp_f32_e32 v106, v106
	v_add_f32_e32 v107, 1.0, v107
	v_exp_f32_e32 v91, v91
	v_mul_f32_e32 v92, 0xbfb8aa3b, v92
	v_add_f32_e32 v93, v93, v77
	v_add_f32_e32 v82, v82, v58
	v_mul_f32_e32 v131, 0xbfb8aa3b, v131
	v_mul_f32_e32 v123, v126, v123
	v_add_f32_e32 v126, v128, v80
	v_rcp_f32_e32 v107, v107
	v_add_f32_e32 v108, 1.0, v108
	v_exp_f32_e32 v92, v92
	v_mul_f32_e32 v93, 0xbfb8aa3b, v93
	v_mul_f32_e32 v82, 0xbfb8aa3b, v82
	v_add_f32_e32 v83, v83, v59
	v_add_f32_e32 v50, v50, v58
	v_exp_f32_e32 v131, v131
	v_mul_f32_e32 v124, v126, v124
	v_add_f32_e32 v126, v129, v81
	v_add_f32_e32 v118, v118, v66
	v_rcp_f32_e32 v108, v108
	v_add_f32_e32 v109, 1.0, v109
	v_add_f32_e32 v98, 1.0, v98
	v_exp_f32_e32 v93, v93
	v_exp_f32_e32 v82, v82
	v_mul_f32_e32 v83, 0xbfb8aa3b, v83
	v_mul_f32_e32 v50, 0xbfb8aa3b, v50
	v_add_f32_e32 v51, v51, v59
	v_mul_f32_e32 v125, v126, v125
	v_mul_f32_e32 v126, v118, v114
	v_add_f32_e32 v114, v119, v67
	v_add_f32_e32 v110, v110, v78
	v_rcp_f32_e32 v109, v109
	v_rcp_f32_e32 v98, v98
	v_add_f32_e32 v99, 1.0, v99
	v_add_f32_e32 v90, 1.0, v90
	v_exp_f32_e32 v83, v83
	v_exp_f32_e32 v50, v50
	v_mul_f32_e32 v51, 0xbfb8aa3b, v51
	v_add_f32_e32 v34, v34, v58
	v_mul_f32_e32 v127, v114, v115
	v_add_f32_e32 v115, v116, v60
	v_mul_f32_e32 v106, v110, v106
	v_add_f32_e32 v110, v111, v79
	v_rcp_f32_e32 v99, v99
	v_rcp_f32_e32 v90, v90
	v_add_f32_e32 v91, 1.0, v91
	v_exp_f32_e32 v51, v51
	v_mul_f32_e32 v34, 0xbfb8aa3b, v34
	v_add_f32_e32 v35, v35, v59
	v_mul_f32_e32 v115, 0xbfb8aa3b, v115
	v_mul_f32_e32 v107, v110, v107
	v_add_f32_e32 v110, v112, v80
	v_rcp_f32_e32 v91, v91
	v_add_f32_e32 v92, 1.0, v92
	v_exp_f32_e32 v34, v34
	v_mul_f32_e32 v35, 0xbfb8aa3b, v35
	v_add_f32_e32 v18, v18, v58
	v_add_f32_e32 v131, 1.0, v131
	v_exp_f32_e32 v115, v115
	v_mul_f32_e32 v108, v110, v108
	v_add_f32_e32 v110, v113, v81
	v_add_f32_e32 v102, v102, v66
	v_rcp_f32_e32 v92, v92
	v_add_f32_e32 v93, 1.0, v93
	v_add_f32_e32 v82, 1.0, v82
	v_exp_f32_e32 v35, v35
	v_mul_f32_e32 v18, 0xbfb8aa3b, v18
	v_add_f32_e32 v19, v19, v59
	v_rcp_f32_e32 v131, v131
	v_mul_f32_e32 v109, v110, v109
	v_mul_f32_e32 v110, v102, v98
	v_add_f32_e32 v98, v103, v67
	v_add_f32_e32 v94, v94, v78
	v_rcp_f32_e32 v93, v93
	v_rcp_f32_e32 v82, v82
	v_add_f32_e32 v83, 1.0, v83
	v_add_f32_e32 v50, 1.0, v50
	v_exp_f32_e32 v18, v18
	v_mul_f32_e32 v19, 0xbfb8aa3b, v19
	v_add_f32_e32 v2, v2, v58
	v_mul_f32_e32 v111, v98, v99
	v_add_f32_e32 v99, v100, v60
	v_mul_f32_e32 v90, v94, v90
	v_add_f32_e32 v94, v95, v79
	v_rcp_f32_e32 v83, v83
	v_rcp_f32_e32 v50, v50
	v_add_f32_e32 v51, 1.0, v51
	v_exp_f32_e32 v19, v19
	v_mul_f32_e32 v2, 0xbfb8aa3b, v2
	v_add_f32_e32 v3, v3, v59
	v_add_f32_e32 v134, v134, v74
	v_mul_f32_e32 v99, 0xbfb8aa3b, v99
	v_mul_f32_e32 v91, v94, v91
	v_add_f32_e32 v94, v96, v80
	v_rcp_f32_e32 v51, v51
	v_add_f32_e32 v34, 1.0, v34
	v_exp_f32_e32 v2, v2
	v_mul_f32_e32 v3, 0xbfb8aa3b, v3
	v_mul_f32_e32 v134, 0xbfb8aa3b, v134
	v_add_f32_e32 v135, v135, v75
	v_add_f32_e32 v130, v140, v68
	v_add_f32_e32 v115, 1.0, v115
	v_exp_f32_e32 v99, v99
	v_mul_f32_e32 v92, v94, v92
	v_add_f32_e32 v94, v97, v81
	v_add_f32_e32 v86, v86, v66
	v_rcp_f32_e32 v34, v34
	v_add_f32_e32 v35, 1.0, v35
	v_exp_f32_e32 v3, v3
	v_exp_f32_e32 v134, v134
	v_mul_f32_e32 v135, 0xbfb8aa3b, v135
	v_add_f32_e32 v136, v136, v76
	v_mul_f32_e32 v140, v130, v131
	v_add_f32_e32 v131, v133, v61
	v_rcp_f32_e32 v115, v115
	v_mul_f32_e32 v93, v94, v93
	v_mul_f32_e32 v94, v86, v82
	v_add_f32_e32 v82, v87, v67
	v_add_f32_e32 v54, v54, v66
	v_rcp_f32_e32 v35, v35
	v_add_f32_e32 v18, 1.0, v18
	v_exp_f32_e32 v135, v135
	v_mul_f32_e32 v136, 0xbfb8aa3b, v136
	v_add_f32_e32 v137, v137, v77
	v_mul_f32_e32 v131, 0xbfb8aa3b, v131
	v_mul_f32_e32 v95, v82, v83
	v_add_f32_e32 v83, v84, v60
	v_mul_f32_e32 v54, v54, v50
	v_add_f32_e32 v50, v55, v67
	v_rcp_f32_e32 v18, v18
	v_add_f32_e32 v19, 1.0, v19
	v_exp_f32_e32 v136, v136
	v_mul_f32_e32 v137, 0xbfb8aa3b, v137
	v_exp_f32_e32 v131, v131
	v_mul_f32_e32 v83, 0xbfb8aa3b, v83
	v_mul_f32_e32 v55, v50, v51
	v_add_f32_e32 v51, v52, v60
	v_add_f32_e32 v38, v38, v66
	v_rcp_f32_e32 v19, v19
	v_add_f32_e32 v2, 1.0, v2
	v_exp_f32_e32 v137, v137
	v_add_f32_e32 v114, v120, v68
	v_add_f32_e32 v99, 1.0, v99
	v_exp_f32_e32 v83, v83
	v_mul_f32_e32 v51, 0xbfb8aa3b, v51
	v_mul_f32_e32 v38, v38, v34
	v_add_f32_e32 v34, v39, v67
	v_rcp_f32_e32 v2, v2
	v_add_f32_e32 v3, 1.0, v3
	v_add_f32_e32 v134, 1.0, v134
	v_mul_f32_e32 v120, v114, v115
	v_add_f32_e32 v115, v117, v61
	v_rcp_f32_e32 v99, v99
	v_exp_f32_e32 v51, v51
	v_mul_f32_e32 v39, v34, v35
	v_add_f32_e32 v35, v36, v60
	v_add_f32_e32 v22, v22, v66
	v_rcp_f32_e32 v3, v3
	v_rcp_f32_e32 v134, v134
	v_add_f32_e32 v135, 1.0, v135
	v_mul_f32_e32 v115, 0xbfb8aa3b, v115
	v_mul_f32_e32 v35, 0xbfb8aa3b, v35
	v_mul_f32_e32 v22, v22, v18
	v_add_f32_e32 v18, v23, v67
	v_rcp_f32_e32 v135, v135
	v_add_f32_e32 v136, 1.0, v136
	v_add_f32_e32 v131, 1.0, v131
	v_exp_f32_e32 v115, v115
	v_exp_f32_e32 v35, v35
	v_mul_f32_e32 v23, v18, v19
	v_add_f32_e32 v19, v20, v60
	v_add_f32_e32 v6, v6, v66
	v_rcp_f32_e32 v136, v136
	v_add_f32_e32 v137, 1.0, v137
	v_rcp_f32_e32 v131, v131
	v_add_f32_e32 v98, v104, v68
	v_add_f32_e32 v83, 1.0, v83
	v_mul_f32_e32 v19, 0xbfb8aa3b, v19
	v_mul_f32_e32 v6, v6, v2
	v_add_f32_e32 v2, v7, v67
	v_add_f32_e32 v142, v142, v78
	v_rcp_f32_e32 v137, v137
	v_mul_f32_e32 v104, v98, v99
	v_add_f32_e32 v99, v101, v61
	v_rcp_f32_e32 v83, v83
	v_add_f32_e32 v51, 1.0, v51
	v_exp_f32_e32 v19, v19
	v_mul_f32_e32 v7, v2, v3
	v_add_f32_e32 v3, v4, v60
	v_mul_f32_e32 v134, v142, v134
	v_add_f32_e32 v142, v143, v79
	v_mul_f32_e32 v99, 0xbfb8aa3b, v99
	v_rcp_f32_e32 v51, v51
	v_mul_f32_e32 v3, 0xbfb8aa3b, v3
	v_mul_f32_e32 v135, v142, v135
	v_add_f32_e32 v142, v144, v80
	v_add_f32_e32 v130, v141, v69
	v_add_f32_e32 v115, 1.0, v115
	v_exp_f32_e32 v99, v99
	v_add_f32_e32 v62, v62, v74
	v_add_f32_e32 v35, 1.0, v35
	v_exp_f32_e32 v3, v3
	v_mul_f32_e32 v136, v142, v136
	v_add_f32_e32 v142, v145, v81
	v_mul_f32_e32 v141, v130, v131
	v_lshl_add_u64 v[130:131], v[172:173], 0, v[182:183]
	v_cvt_pk_bf16_f32 v132, v134, v135
	v_rcp_f32_e32 v115, v115
	v_add_f32_e32 v82, v88, v68
	v_mul_f32_e32 v62, 0xbfb8aa3b, v62
	v_add_f32_e32 v63, v63, v75
	v_rcp_f32_e32 v35, v35
	v_mul_f32_e32 v137, v142, v137
	v_cvt_pk_bf16_f32 v133, v136, v137
	v_cvt_pk_bf16_f32 v134, v138, v139
	v_cvt_pk_bf16_f32 v135, v140, v141
	global_store_dwordx4 v[130:131], v[132:135], off
	v_mul_f32_e32 v88, v82, v83
	v_add_f32_e32 v83, v85, v61
	v_or_b32_e32 v132, 16, v174
	v_exp_f32_e32 v62, v62
	v_mul_f32_e32 v63, 0xbfb8aa3b, v63
	v_add_f32_e32 v64, v64, v76
	v_add_f32_e32 v50, v56, v68
	v_add_f32_e32 v42, v42, v74
	v_add_f32_e32 v19, 1.0, v19
	v_ashrrev_i32_e32 v133, 31, v132
	v_mul_f32_e32 v83, 0xbfb8aa3b, v83
	v_exp_f32_e32 v63, v63
	v_mul_f32_e32 v64, 0xbfb8aa3b, v64
	v_add_f32_e32 v65, v65, v77
	v_mul_f32_e32 v56, v50, v51
	v_add_f32_e32 v51, v53, v61
	v_mul_f32_e32 v42, 0xbfb8aa3b, v42
	v_add_f32_e32 v43, v43, v75
	v_rcp_f32_e32 v19, v19
	v_lshlrev_b64 v[132:133], 11, v[132:133]
	v_add_f32_e32 v114, v121, v69
	v_add_f32_e32 v99, 1.0, v99
	v_exp_f32_e32 v83, v83
	v_exp_f32_e32 v64, v64
	v_mul_f32_e32 v65, 0xbfb8aa3b, v65
	v_mul_f32_e32 v51, 0xbfb8aa3b, v51
	v_exp_f32_e32 v42, v42
	v_mul_f32_e32 v43, 0xbfb8aa3b, v43
	v_add_f32_e32 v44, v44, v76
	v_add_f32_e32 v34, v40, v68
	v_add_f32_e32 v26, v26, v74
	v_add_f32_e32 v3, 1.0, v3
	v_mul_f32_e32 v117, v114, v115
	v_lshl_add_u64 v[118:119], v[172:173], 0, v[132:133]
	v_cvt_pk_bf16_f32 v114, v122, v123
	v_rcp_f32_e32 v99, v99
	v_exp_f32_e32 v65, v65
	v_exp_f32_e32 v51, v51
	v_exp_f32_e32 v43, v43
	v_mul_f32_e32 v44, 0xbfb8aa3b, v44
	v_add_f32_e32 v45, v45, v77
	v_mul_f32_e32 v40, v34, v35
	v_add_f32_e32 v35, v37, v61
	v_mul_f32_e32 v26, 0xbfb8aa3b, v26
	v_add_f32_e32 v27, v27, v75
	v_rcp_f32_e32 v3, v3
	v_cvt_pk_bf16_f32 v115, v124, v125
	v_cvt_pk_bf16_f32 v116, v126, v127
	v_cvt_pk_bf16_f32 v117, v120, v117
	global_store_dwordx4 v[118:119], v[114:117], off
	v_add_f32_e32 v62, 1.0, v62
	v_exp_f32_e32 v44, v44
	v_or_b32_e32 v114, 32, v174
	v_mul_f32_e32 v45, 0xbfb8aa3b, v45
	v_mul_f32_e32 v35, 0xbfb8aa3b, v35
	v_exp_f32_e32 v26, v26
	v_mul_f32_e32 v27, 0xbfb8aa3b, v27
	v_add_f32_e32 v28, v28, v76
	v_add_f32_e32 v18, v24, v68
	v_add_f32_e32 v10, v10, v74
	v_ashrrev_i32_e32 v115, 31, v114
	v_rcp_f32_e32 v62, v62
	v_add_f32_e32 v63, 1.0, v63
	v_exp_f32_e32 v45, v45
	v_exp_f32_e32 v35, v35
	v_exp_f32_e32 v27, v27
	v_mul_f32_e32 v28, 0xbfb8aa3b, v28
	v_add_f32_e32 v29, v29, v77
	v_mul_f32_e32 v24, v18, v19
	v_add_f32_e32 v19, v21, v61
	v_mul_f32_e32 v10, 0xbfb8aa3b, v10
	v_add_f32_e32 v11, v11, v75
	v_lshlrev_b64 v[114:115], 11, v[114:115]
	v_add_f32_e32 v98, v105, v69
	v_add_f32_e32 v83, 1.0, v83
	v_rcp_f32_e32 v63, v63
	v_add_f32_e32 v64, 1.0, v64
	v_add_f32_e32 v42, 1.0, v42
	v_exp_f32_e32 v28, v28
	v_mul_f32_e32 v29, 0xbfb8aa3b, v29
	v_mul_f32_e32 v19, 0xbfb8aa3b, v19
	v_exp_f32_e32 v10, v10
	v_mul_f32_e32 v11, 0xbfb8aa3b, v11
	v_add_f32_e32 v12, v12, v76
	v_add_f32_e32 v2, v8, v68
	v_mul_f32_e32 v101, v98, v99
	v_lshl_add_u64 v[102:103], v[172:173], 0, v[114:115]
	v_cvt_pk_bf16_f32 v98, v106, v107
	v_rcp_f32_e32 v83, v83
	v_rcp_f32_e32 v64, v64
	v_add_f32_e32 v65, 1.0, v65
	v_add_f32_e32 v51, 1.0, v51
	v_rcp_f32_e32 v42, v42
	v_add_f32_e32 v43, 1.0, v43
	v_exp_f32_e32 v29, v29
	v_exp_f32_e32 v19, v19
	v_exp_f32_e32 v11, v11
	v_mul_f32_e32 v12, 0xbfb8aa3b, v12
	v_add_f32_e32 v13, v13, v77
	v_mul_f32_e32 v8, v2, v3
	v_add_f32_e32 v3, v5, v61
	v_cvt_pk_bf16_f32 v99, v108, v109
	v_cvt_pk_bf16_f32 v100, v110, v111
	v_cvt_pk_bf16_f32 v101, v104, v101
	global_store_dwordx4 v[102:103], v[98:101], off
	v_add_f32_e32 v70, v70, v78
	v_rcp_f32_e32 v65, v65
	v_or_b32_e32 v98, 48, v174
	v_rcp_f32_e32 v51, v51
	v_rcp_f32_e32 v43, v43
	v_add_f32_e32 v44, 1.0, v44
	v_add_f32_e32 v26, 1.0, v26
	v_exp_f32_e32 v12, v12
	v_mul_f32_e32 v13, 0xbfb8aa3b, v13
	v_mul_f32_e32 v3, 0xbfb8aa3b, v3
	v_ashrrev_i32_e32 v99, 31, v98
	v_mul_f32_e32 v62, v70, v62
	v_add_f32_e32 v70, v71, v79
	v_rcp_f32_e32 v44, v44
	v_add_f32_e32 v45, 1.0, v45
	v_add_f32_e32 v35, 1.0, v35
	v_rcp_f32_e32 v26, v26
	v_add_f32_e32 v27, 1.0, v27
	v_exp_f32_e32 v13, v13
	v_exp_f32_e32 v3, v3
	v_lshlrev_b64 v[98:99], 11, v[98:99]
	v_add_f32_e32 v82, v89, v69
	v_mul_f32_e32 v63, v70, v63
	v_add_f32_e32 v70, v72, v80
	v_add_f32_e32 v46, v46, v78
	v_rcp_f32_e32 v45, v45
	v_rcp_f32_e32 v35, v35
	v_rcp_f32_e32 v27, v27
	v_add_f32_e32 v28, 1.0, v28
	v_add_f32_e32 v10, 1.0, v10
	v_mul_f32_e32 v85, v82, v83
	v_lshl_add_u64 v[86:87], v[172:173], 0, v[98:99]
	v_mul_f32_e32 v64, v70, v64
	v_add_f32_e32 v70, v73, v81
	v_add_f32_e32 v50, v57, v69
	v_mul_f32_e32 v42, v46, v42
	v_add_f32_e32 v46, v47, v79
	v_rcp_f32_e32 v28, v28
	v_add_f32_e32 v29, 1.0, v29
	v_add_f32_e32 v19, 1.0, v19
	v_rcp_f32_e32 v10, v10
	v_add_f32_e32 v11, 1.0, v11
	v_cvt_pk_bf16_f32 v82, v90, v91
	v_cvt_pk_bf16_f32 v83, v92, v93
	v_cvt_pk_bf16_f32 v84, v94, v95
	v_cvt_pk_bf16_f32 v85, v88, v85
	global_store_dwordx4 v[86:87], v[82:85], off
	v_mul_f32_e32 v65, v70, v65
	v_mul_f32_e32 v53, v50, v51
	v_cvt_pk_bf16_f32 v50, v62, v63
	v_cvt_pk_bf16_f32 v51, v64, v65
	v_cvt_pk_bf16_f32 v52, v54, v55
	v_add_co_u32_e32 v54, vcc, s67, v130
	v_mul_f32_e32 v43, v46, v43
	v_add_f32_e32 v46, v48, v80
	v_add_f32_e32 v30, v30, v78
	v_rcp_f32_e32 v29, v29
	v_rcp_f32_e32 v19, v19
	v_rcp_f32_e32 v11, v11
	v_add_f32_e32 v12, 1.0, v12
	v_addc_co_u32_e32 v55, vcc, 0, v131, vcc
	v_mul_f32_e32 v44, v46, v44
	v_add_f32_e32 v46, v49, v81
	v_add_f32_e32 v34, v41, v69
	v_mul_f32_e32 v26, v30, v26
	v_add_f32_e32 v30, v31, v79
	v_rcp_f32_e32 v12, v12
	v_add_f32_e32 v13, 1.0, v13
	v_add_f32_e32 v3, 1.0, v3
	v_cvt_pk_bf16_f32 v53, v56, v53
	global_store_dwordx4 v[54:55], v[50:53], off
	v_mul_f32_e32 v45, v46, v45
	v_mul_f32_e32 v37, v34, v35
	v_cvt_pk_bf16_f32 v34, v42, v43
	v_cvt_pk_bf16_f32 v35, v44, v45
	v_cvt_pk_bf16_f32 v36, v38, v39
	v_add_co_u32_e32 v38, vcc, s68, v130
	v_mul_f32_e32 v27, v30, v27
	v_add_f32_e32 v30, v32, v80
	v_add_f32_e32 v14, v14, v78
	v_rcp_f32_e32 v13, v13
	v_rcp_f32_e32 v3, v3
	v_addc_co_u32_e32 v39, vcc, 0, v131, vcc
	v_mul_f32_e32 v28, v30, v28
	v_add_f32_e32 v30, v33, v81
	v_add_f32_e32 v18, v25, v69
	v_mul_f32_e32 v10, v14, v10
	v_add_f32_e32 v14, v15, v79
	v_cvt_pk_bf16_f32 v37, v40, v37
	global_store_dwordx4 v[38:39], v[34:37], off
	v_mul_f32_e32 v29, v30, v29
	v_mul_f32_e32 v21, v18, v19
	v_cvt_pk_bf16_f32 v18, v26, v27
	v_cvt_pk_bf16_f32 v19, v28, v29
	v_cvt_pk_bf16_f32 v20, v22, v23
	v_add_co_u32_e32 v22, vcc, s2, v130
	v_mul_f32_e32 v11, v14, v11
	v_add_f32_e32 v14, v16, v80
	v_addc_co_u32_e32 v23, vcc, 0, v131, vcc
	v_mul_f32_e32 v12, v14, v12
	v_add_f32_e32 v14, v17, v81
	v_add_f32_e32 v2, v9, v69
	v_cvt_pk_bf16_f32 v21, v24, v21
	global_store_dwordx4 v[22:23], v[18:21], off
	v_mul_f32_e32 v13, v14, v13
	v_mul_f32_e32 v5, v2, v3
	v_cvt_pk_bf16_f32 v2, v10, v11
	v_cvt_pk_bf16_f32 v3, v12, v13
	v_cvt_pk_bf16_f32 v4, v6, v7
	v_add_co_u32_e32 v6, vcc, 0x58000, v130
	s_mov_b32 s2, s48
	s_nop 0
	v_addc_co_u32_e32 v7, vcc, 0, v131, vcc
	s_and_b64 vcc, exec, s[38:39]
	v_cvt_pk_bf16_f32 v5, v8, v5
	global_store_dwordx4 v[6:7], v[2:5], off
	s_cbranch_vccz .LBB0_88
	s_waitcnt vmcnt(8)
	s_cmpk_gt_u32 s35, 0xff
	s_cbranch_scc1 .LBB0_99
	s_barrier

.LBB0_260:
	s_add_u32 s22, s0, 0xfffc0080
	s_addc_u32 s23, s1, -1
	s_add_i32 s60, 0, 0x10000
	v_add_u32_e32 v142, s60, v178
	ds_read_b128 v[130:133], v142
	ds_read_b128 v[134:137], v142 offset:1024
	ds_read_b128 v[138:141], v142 offset:2048
	ds_read_b128 v[142:145], v142 offset:3072
	s_cmp_eq_u32 s59, 12
	s_cselect_b32 s47, s35, s23
	s_cselect_b32 s46, s55, s22
	s_cselect_b32 s23, s31, s58
	s_cselect_b32 s22, s56, s57
	v_lshl_add_u64 v[186:187], s[0:1], 0, v[168:169]
	s_add_i32 m0, s27, 0xc000
	ds_read_b128 v[172:175], v180
	ds_read_b128 v[182:185], v180 offset:1024
	ds_read_b128 v[206:209], v180 offset:2048
	ds_read_b128 v[210:213], v180 offset:3072
	ds_read_b128 v[214:217], v180 offset:4096
	ds_read_b128 v[218:221], v180 offset:5120
	ds_read_b128 v[222:225], v180 offset:6144
	ds_read_b128 v[226:229], v180 offset:7168
	global_load_lds_dwordx4 v[186:187], off
	v_lshl_add_u64 v[186:187], s[0:1], 0, v[170:171]
	s_add_i32 m0, s27, 0xe000
	s_nop 0
	global_load_lds_dwordx4 v[186:187], off
	s_waitcnt lgkmcnt(8)
	s_barrier
	s_setprio 1
	s_waitcnt lgkmcnt(7)
	v_mfma_f32_16x16x32_bf16 v[126:129], v[130:133], v[172:175], v[126:129]
	v_mfma_f32_16x16x32_bf16 v[122:125], v[138:141], v[172:175], v[122:125]
	s_waitcnt lgkmcnt(5)
	v_mfma_f32_16x16x32_bf16 v[110:113], v[130:133], v[206:209], v[110:113]
	v_mfma_f32_16x16x32_bf16 v[106:109], v[138:141], v[206:209], v[106:109]
	s_waitcnt lgkmcnt(3)
	v_mfma_f32_16x16x32_bf16 v[94:97], v[130:133], v[214:217], v[94:97]
	v_mfma_f32_16x16x32_bf16 v[90:93], v[138:141], v[214:217], v[90:93]
	s_waitcnt lgkmcnt(1)
	v_mfma_f32_16x16x32_bf16 v[78:81], v[130:133], v[222:225], v[78:81]
	v_mfma_f32_16x16x32_bf16 v[74:77], v[138:141], v[222:225], v[74:77]
	v_mfma_f32_16x16x32_bf16 v[126:129], v[134:137], v[182:185], v[126:129]
	v_mfma_f32_16x16x32_bf16 v[122:125], v[142:145], v[182:185], v[122:125]
	v_mfma_f32_16x16x32_bf16 v[110:113], v[134:137], v[210:213], v[110:113]
	v_mfma_f32_16x16x32_bf16 v[106:109], v[142:145], v[210:213], v[106:109]
	v_mfma_f32_16x16x32_bf16 v[94:97], v[134:137], v[218:221], v[94:97]
	v_mfma_f32_16x16x32_bf16 v[90:93], v[142:145], v[218:221], v[90:93]
	s_waitcnt lgkmcnt(0)
	v_mfma_f32_16x16x32_bf16 v[78:81], v[134:137], v[226:229], v[78:81]
	v_mfma_f32_16x16x32_bf16 v[74:77], v[142:145], v[226:229], v[74:77]
	s_barrier
	s_setprio 0
	s_add_i32 s62, 0, 0x14000
	s_add_i32 s60, s60, s25
	v_add_u32_e32 v181, s62, v178
	v_lshl_add_u64 v[186:187], s[22:23], 0, v[0:1]
	s_mov_b32 m0, s60
	ds_read_b128 v[230:233], v181
	ds_read_b128 v[234:237], v181 offset:1024
	ds_read_b128 v[238:241], v181 offset:2048
	ds_read_b128 v[242:245], v181 offset:3072
	global_load_lds_dwordx4 v[186:187], off
	v_lshl_add_u64 v[246:247], s[22:23], 0, v[162:163]
	s_add_i32 m0, s60, 0x2000
	s_nop 0
	global_load_lds_dwordx4 v[246:247], off
	s_barrier
	s_setprio 1
	s_waitcnt lgkmcnt(3)
	v_mfma_f32_16x16x32_bf16 v[118:121], v[230:233], v[172:175], v[118:121]
	s_waitcnt lgkmcnt(1)
	v_mfma_f32_16x16x32_bf16 v[114:117], v[238:241], v[172:175], v[114:117]
	v_mfma_f32_16x16x32_bf16 v[102:105], v[230:233], v[206:209], v[102:105]
	v_mfma_f32_16x16x32_bf16 v[98:101], v[238:241], v[206:209], v[98:101]
	v_mfma_f32_16x16x32_bf16 v[86:89], v[230:233], v[214:217], v[86:89]
	v_mfma_f32_16x16x32_bf16 v[82:85], v[238:241], v[214:217], v[82:85]
	v_mfma_f32_16x16x32_bf16 v[70:73], v[230:233], v[222:225], v[70:73]
	v_mfma_f32_16x16x32_bf16 v[66:69], v[238:241], v[222:225], v[66:69]
	v_mfma_f32_16x16x32_bf16 v[118:121], v[234:237], v[182:185], v[118:121]
	s_waitcnt lgkmcnt(0)
	v_mfma_f32_16x16x32_bf16 v[114:117], v[242:245], v[182:185], v[114:117]
	v_mfma_f32_16x16x32_bf16 v[102:105], v[234:237], v[210:213], v[102:105]
	v_mfma_f32_16x16x32_bf16 v[98:101], v[242:245], v[210:213], v[98:101]
	v_mfma_f32_16x16x32_bf16 v[86:89], v[234:237], v[218:221], v[86:89]
	v_mfma_f32_16x16x32_bf16 v[82:85], v[242:245], v[218:221], v[82:85]
	v_mfma_f32_16x16x32_bf16 v[70:73], v[234:237], v[226:229], v[70:73]
	v_mfma_f32_16x16x32_bf16 v[66:69], v[242:245], v[226:229], v[66:69]
	s_barrier
	s_setprio 0
	s_mov_b32 m0, s27
	v_lshl_add_u64 v[248:249], s[46:47], 0, v[166:167]
	ds_read_b128 v[172:175], v180 offset:16384
	ds_read_b128 v[182:185], v180 offset:17408
	ds_read_b128 v[206:209], v180 offset:18432
	ds_read_b128 v[210:213], v180 offset:19456
	ds_read_b128 v[214:217], v180 offset:20480
	ds_read_b128 v[218:221], v180 offset:21504
	ds_read_b128 v[222:225], v180 offset:22528
	ds_read_b128 v[226:229], v180 offset:23552
	global_load_lds_dwordx4 v[248:249], off
	v_lshl_add_u64 v[250:251], s[46:47], 0, v[164:165]
	s_mov_b32 m0, s45
	s_nop 0
	global_load_lds_dwordx4 v[250:251], off
	s_barrier
	s_setprio 1
	s_waitcnt lgkmcnt(7)
	v_mfma_f32_16x16x32_bf16 v[62:65], v[130:133], v[172:175], v[62:65]
	v_mfma_f32_16x16x32_bf16 v[58:61], v[138:141], v[172:175], v[58:61]
	s_waitcnt lgkmcnt(5)
	v_mfma_f32_16x16x32_bf16 v[50:53], v[130:133], v[206:209], v[50:53]
	v_mfma_f32_16x16x32_bf16 v[42:45], v[138:141], v[206:209], v[42:45]
	s_waitcnt lgkmcnt(3)
	v_mfma_f32_16x16x32_bf16 v[34:37], v[130:133], v[214:217], v[34:37]
	v_mfma_f32_16x16x32_bf16 v[26:29], v[138:141], v[214:217], v[26:29]
	s_waitcnt lgkmcnt(1)
	v_mfma_f32_16x16x32_bf16 v[18:21], v[130:133], v[222:225], v[18:21]
	v_mfma_f32_16x16x32_bf16 v[10:13], v[138:141], v[222:225], v[10:13]
	v_mfma_f32_16x16x32_bf16 v[62:65], v[134:137], v[182:185], v[62:65]
	v_mfma_f32_16x16x32_bf16 v[58:61], v[142:145], v[182:185], v[58:61]
	v_mfma_f32_16x16x32_bf16 v[50:53], v[134:137], v[210:213], v[50:53]
	v_mfma_f32_16x16x32_bf16 v[42:45], v[142:145], v[210:213], v[42:45]
	v_mfma_f32_16x16x32_bf16 v[34:37], v[134:137], v[218:221], v[34:37]
	v_mfma_f32_16x16x32_bf16 v[26:29], v[142:145], v[218:221], v[26:29]
	s_waitcnt lgkmcnt(0)
	v_mfma_f32_16x16x32_bf16 v[18:21], v[134:137], v[226:229], v[18:21]
	v_mfma_f32_16x16x32_bf16 v[10:13], v[142:145], v[226:229], v[10:13]
	s_barrier
	s_setprio 0
	s_add_u32 s60, s22, 0x40000
	s_addc_u32 s61, s23, 0
	s_add_i32 s62, s62, s25
	v_lshl_add_u64 v[130:131], s[60:61], 0, v[0:1]
	s_mov_b32 m0, s62
	s_nop 0
	global_load_lds_dwordx4 v[130:131], off
	v_lshl_add_u64 v[130:131], s[60:61], 0, v[162:163]
	s_add_i32 m0, s62, 0x2000
	s_nop 0
	global_load_lds_dwordx4 v[130:131], off
	s_waitcnt vmcnt(6)
	s_barrier
	s_setprio 1
	v_mfma_f32_16x16x32_bf16 v[54:57], v[230:233], v[172:175], v[54:57]
	v_mfma_f32_16x16x32_bf16 v[46:49], v[238:241], v[172:175], v[46:49]
	v_mfma_f32_16x16x32_bf16 v[38:41], v[230:233], v[206:209], v[38:41]
	v_mfma_f32_16x16x32_bf16 v[30:33], v[238:241], v[206:209], v[30:33]
	v_mfma_f32_16x16x32_bf16 v[22:25], v[230:233], v[214:217], v[22:25]
	v_mfma_f32_16x16x32_bf16 v[14:17], v[238:241], v[214:217], v[14:17]
	v_mfma_f32_16x16x32_bf16 v[6:9], v[230:233], v[222:225], v[6:9]
	v_mfma_f32_16x16x32_bf16 v[2:5], v[238:241], v[222:225], v[2:5]
	v_mfma_f32_16x16x32_bf16 v[54:57], v[234:237], v[182:185], v[54:57]
	v_mfma_f32_16x16x32_bf16 v[46:49], v[242:245], v[182:185], v[46:49]
	v_mfma_f32_16x16x32_bf16 v[38:41], v[234:237], v[210:213], v[38:41]
	v_mfma_f32_16x16x32_bf16 v[30:33], v[242:245], v[210:213], v[30:33]
	v_mfma_f32_16x16x32_bf16 v[22:25], v[234:237], v[218:221], v[22:25]
	v_mfma_f32_16x16x32_bf16 v[14:17], v[242:245], v[218:221], v[14:17]
	v_mfma_f32_16x16x32_bf16 v[6:9], v[234:237], v[226:229], v[6:9]
	v_mfma_f32_16x16x32_bf16 v[2:5], v[242:245], v[226:229], v[2:5]
	s_barrier
	s_setprio 0
	s_add_i32 s60, 0, 0x18000
	v_add_u32_e32 v142, s60, v178
	ds_read_b128 v[130:133], v142
	ds_read_b128 v[134:137], v142 offset:1024
	ds_read_b128 v[138:141], v142 offset:2048
	ds_read_b128 v[142:145], v142 offset:3072
	s_add_u32 s46, s46, 0x40000
	s_addc_u32 s47, s47, 0
	s_mov_b32 m0, s48
	v_lshl_add_u64 v[230:231], s[46:47], 0, v[166:167]
	ds_read_b128 v[172:175], v180 offset:32768
	ds_read_b128 v[182:185], v180 offset:33792
	ds_read_b128 v[206:209], v180 offset:34816
	ds_read_b128 v[210:213], v180 offset:35840
	ds_read_b128 v[214:217], v180 offset:36864
	ds_read_b128 v[218:221], v180 offset:37888
	ds_read_b128 v[222:225], v180 offset:38912
	ds_read_b128 v[226:229], v180 offset:39936
	global_load_lds_dwordx4 v[230:231], off
	v_lshl_add_u64 v[230:231], s[46:47], 0, v[164:165]
	s_mov_b32 m0, s49
	s_nop 0
	global_load_lds_dwordx4 v[230:231], off
	s_waitcnt lgkmcnt(8)
	s_barrier
	s_setprio 1
	s_waitcnt lgkmcnt(7)
	v_mfma_f32_16x16x32_bf16 v[126:129], v[130:133], v[172:175], v[126:129]
	v_mfma_f32_16x16x32_bf16 v[122:125], v[138:141], v[172:175], v[122:125]
	s_waitcnt lgkmcnt(5)
	v_mfma_f32_16x16x32_bf16 v[110:113], v[130:133], v[206:209], v[110:113]
	v_mfma_f32_16x16x32_bf16 v[106:109], v[138:141], v[206:209], v[106:109]
	s_waitcnt lgkmcnt(3)
	v_mfma_f32_16x16x32_bf16 v[94:97], v[130:133], v[214:217], v[94:97]
	v_mfma_f32_16x16x32_bf16 v[90:93], v[138:141], v[214:217], v[90:93]
	s_waitcnt lgkmcnt(1)
	v_mfma_f32_16x16x32_bf16 v[78:81], v[130:133], v[222:225], v[78:81]
	v_mfma_f32_16x16x32_bf16 v[74:77], v[138:141], v[222:225], v[74:77]
	v_mfma_f32_16x16x32_bf16 v[126:129], v[134:137], v[182:185], v[126:129]
	v_mfma_f32_16x16x32_bf16 v[122:125], v[142:145], v[182:185], v[122:125]
	v_mfma_f32_16x16x32_bf16 v[110:113], v[134:137], v[210:213], v[110:113]
	v_mfma_f32_16x16x32_bf16 v[106:109], v[142:145], v[210:213], v[106:109]
	v_mfma_f32_16x16x32_bf16 v[94:97], v[134:137], v[218:221], v[94:97]
	v_mfma_f32_16x16x32_bf16 v[90:93], v[142:145], v[218:221], v[90:93]
	s_waitcnt lgkmcnt(0)
	v_mfma_f32_16x16x32_bf16 v[78:81], v[134:137], v[226:229], v[78:81]
	v_mfma_f32_16x16x32_bf16 v[74:77], v[142:145], v[226:229], v[74:77]
	s_barrier
	s_setprio 0
	s_add_i32 s46, 0, 0x1c000
	s_add_i32 s47, s60, s25
	v_add_u32_e32 v181, s46, v178
	v_lshl_add_u64 v[186:187], v[186:187], 0, s[94:95]
	s_mov_b32 m0, s47
	ds_read_b128 v[230:233], v181
	ds_read_b128 v[234:237], v181 offset:1024
	ds_read_b128 v[238:241], v181 offset:2048
	ds_read_b128 v[242:245], v181 offset:3072
	global_load_lds_dwordx4 v[186:187], off
	v_lshl_add_u64 v[186:187], v[246:247], 0, s[94:95]
	s_add_i32 m0, s47, 0x2000
	s_nop 0
	global_load_lds_dwordx4 v[186:187], off
	s_barrier
	s_setprio 1
	s_waitcnt lgkmcnt(3)
	v_mfma_f32_16x16x32_bf16 v[118:121], v[230:233], v[172:175], v[118:121]
	s_waitcnt lgkmcnt(1)
	v_mfma_f32_16x16x32_bf16 v[114:117], v[238:241], v[172:175], v[114:117]
	v_mfma_f32_16x16x32_bf16 v[102:105], v[230:233], v[206:209], v[102:105]
	v_mfma_f32_16x16x32_bf16 v[98:101], v[238:241], v[206:209], v[98:101]
	v_mfma_f32_16x16x32_bf16 v[86:89], v[230:233], v[214:217], v[86:89]
	v_mfma_f32_16x16x32_bf16 v[82:85], v[238:241], v[214:217], v[82:85]
	v_mfma_f32_16x16x32_bf16 v[70:73], v[230:233], v[222:225], v[70:73]
	v_mfma_f32_16x16x32_bf16 v[66:69], v[238:241], v[222:225], v[66:69]
	v_mfma_f32_16x16x32_bf16 v[118:121], v[234:237], v[182:185], v[118:121]
	s_waitcnt lgkmcnt(0)
	v_mfma_f32_16x16x32_bf16 v[114:117], v[242:245], v[182:185], v[114:117]
	v_mfma_f32_16x16x32_bf16 v[102:105], v[234:237], v[210:213], v[102:105]
	v_mfma_f32_16x16x32_bf16 v[98:101], v[242:245], v[210:213], v[98:101]
	v_mfma_f32_16x16x32_bf16 v[86:89], v[234:237], v[218:221], v[86:89]
	v_mfma_f32_16x16x32_bf16 v[82:85], v[242:245], v[218:221], v[82:85]
	v_mfma_f32_16x16x32_bf16 v[70:73], v[234:237], v[226:229], v[70:73]
	v_mfma_f32_16x16x32_bf16 v[66:69], v[242:245], v[226:229], v[66:69]
	s_barrier
	s_setprio 0
	s_mov_b32 m0, s51
	v_lshl_add_u64 v[186:187], v[248:249], 0, s[94:95]
	ds_read_b128 v[172:175], v180 offset:49152
	ds_read_b128 v[182:185], v180 offset:50176
	ds_read_b128 v[206:209], v180 offset:51200
	ds_read_b128 v[210:213], v180 offset:52224
	ds_read_b128 v[214:217], v180 offset:53248
	ds_read_b128 v[218:221], v180 offset:54272
	ds_read_b128 v[222:225], v180 offset:55296
	ds_read_b128 v[226:229], v180 offset:56320
	global_load_lds_dwordx4 v[186:187], off
	v_lshl_add_u64 v[186:187], v[250:251], 0, s[94:95]
	s_mov_b32 m0, s52
	s_nop 0
	global_load_lds_dwordx4 v[186:187], off
	s_barrier
	s_setprio 1
	s_waitcnt lgkmcnt(7)
	v_mfma_f32_16x16x32_bf16 v[62:65], v[130:133], v[172:175], v[62:65]
	v_mfma_f32_16x16x32_bf16 v[58:61], v[138:141], v[172:175], v[58:61]
	s_waitcnt lgkmcnt(5)
	v_mfma_f32_16x16x32_bf16 v[50:53], v[130:133], v[206:209], v[50:53]
	v_mfma_f32_16x16x32_bf16 v[42:45], v[138:141], v[206:209], v[42:45]
	s_waitcnt lgkmcnt(3)
	v_mfma_f32_16x16x32_bf16 v[34:37], v[130:133], v[214:217], v[34:37]
	v_mfma_f32_16x16x32_bf16 v[26:29], v[138:141], v[214:217], v[26:29]
	s_waitcnt lgkmcnt(1)
	v_mfma_f32_16x16x32_bf16 v[18:21], v[130:133], v[222:225], v[18:21]
	v_mfma_f32_16x16x32_bf16 v[10:13], v[138:141], v[222:225], v[10:13]
	v_mfma_f32_16x16x32_bf16 v[62:65], v[134:137], v[182:185], v[62:65]
	v_mfma_f32_16x16x32_bf16 v[58:61], v[142:145], v[182:185], v[58:61]
	v_mfma_f32_16x16x32_bf16 v[50:53], v[134:137], v[210:213], v[50:53]
	v_mfma_f32_16x16x32_bf16 v[42:45], v[142:145], v[210:213], v[42:45]
	v_mfma_f32_16x16x32_bf16 v[34:37], v[134:137], v[218:221], v[34:37]
	v_mfma_f32_16x16x32_bf16 v[26:29], v[142:145], v[218:221], v[26:29]
	s_waitcnt lgkmcnt(0)
	v_mfma_f32_16x16x32_bf16 v[18:21], v[134:137], v[226:229], v[18:21]
	v_mfma_f32_16x16x32_bf16 v[10:13], v[142:145], v[226:229], v[10:13]
	s_barrier
	s_setprio 0
	s_add_u32 s22, s22, 0x40080
	s_addc_u32 s23, s23, 0
	s_add_i32 s46, s46, s25
	v_lshl_add_u64 v[130:131], s[22:23], 0, v[0:1]
	s_mov_b32 m0, s46
	s_nop 0
	global_load_lds_dwordx4 v[130:131], off
	v_lshl_add_u64 v[130:131], s[22:23], 0, v[162:163]
	s_add_i32 m0, s46, 0x2000
	s_nop 0
	global_load_lds_dwordx4 v[130:131], off
	s_waitcnt vmcnt(6)
	s_barrier
	s_setprio 1
	v_mfma_f32_16x16x32_bf16 v[54:57], v[230:233], v[172:175], v[54:57]
	v_mfma_f32_16x16x32_bf16 v[46:49], v[238:241], v[172:175], v[46:49]
	v_mfma_f32_16x16x32_bf16 v[38:41], v[230:233], v[206:209], v[38:41]
	v_mfma_f32_16x16x32_bf16 v[30:33], v[238:241], v[206:209], v[30:33]
	v_mfma_f32_16x16x32_bf16 v[22:25], v[230:233], v[214:217], v[22:25]
	v_mfma_f32_16x16x32_bf16 v[14:17], v[238:241], v[214:217], v[14:17]
	v_mfma_f32_16x16x32_bf16 v[6:9], v[230:233], v[222:225], v[6:9]
	v_mfma_f32_16x16x32_bf16 v[2:5], v[238:241], v[222:225], v[2:5]
	v_mfma_f32_16x16x32_bf16 v[54:57], v[234:237], v[182:185], v[54:57]
	v_mfma_f32_16x16x32_bf16 v[46:49], v[242:245], v[182:185], v[46:49]
	v_mfma_f32_16x16x32_bf16 v[38:41], v[234:237], v[210:213], v[38:41]
	v_mfma_f32_16x16x32_bf16 v[30:33], v[242:245], v[210:213], v[30:33]
	v_mfma_f32_16x16x32_bf16 v[22:25], v[234:237], v[218:221], v[22:25]
	v_mfma_f32_16x16x32_bf16 v[14:17], v[242:245], v[218:221], v[14:17]
	v_mfma_f32_16x16x32_bf16 v[6:9], v[234:237], v[226:229], v[6:9]
	v_mfma_f32_16x16x32_bf16 v[2:5], v[242:245], v[226:229], v[2:5]
	s_barrier
	s_setprio 0
	s_add_i32 s59, s59, 2
	s_add_u32 s0, s0, 0x100
	s_addc_u32 s1, s1, 0
	s_add_u32 s57, s57, 0x100
	s_addc_u32 s58, s58, 0
	s_cmp_gt_u32 s59, 13
	s_cbranch_scc0 .LBB0_260
	v_lshl_or_b32 v172, s54, 8, v179
	v_ashrrev_i32_e32 v173, 31, v172
	v_cndmask_b32_e64 v131, 0, 1, s[2:3]
	v_lshl_add_u64 v[174:175], v[172:173], 2, s[8:9]
	v_mov_b32_e32 v130, 0
	v_cmp_ne_u32_e64 s[0:1], 1, v131
	s_andn2_b64 vcc, exec, s[2:3]
	v_mov_b32_e32 v134, 0
	v_mov_b32_e32 v135, 0
	v_mov_b32_e32 v136, 0
	v_mov_b32_e32 v137, 0
	s_cbranch_vccnz .LBB0_263
	global_load_dwordx4 v[134:137], v[174:175], off

.LBB0_331:
	s_add_u32 s22, s24, 0x100
	s_addc_u32 s23, s25, 0
	s_add_i32 s52, 0, 0x10000
	v_add_u32_e32 v140, s52, v144
	ds_read_b128 v[164:167], v140
	ds_read_b128 v[168:171], v140 offset:1024
	ds_read_b128 v[172:175], v140 offset:2048
	ds_read_b128 v[176:179], v140 offset:3072
	s_cmp_eq_u32 s51, 40
	s_cselect_b32 s29, s3, s23
	s_cselect_b32 s28, s2, s22
	s_cselect_b32 s27, s1, s41
	s_cselect_b32 s26, s0, s40
	v_lshl_add_u64 v[140:141], s[24:25], 0, v[136:137]
	s_add_i32 m0, s35, 0xc000
	ds_read_b128 v[180:183], v162
	ds_read_b128 v[184:187], v162 offset:1024
	ds_read_b128 v[206:209], v162 offset:2048
	ds_read_b128 v[210:213], v162 offset:3072
	ds_read_b128 v[214:217], v162 offset:4096
	ds_read_b128 v[218:221], v162 offset:5120
	ds_read_b128 v[222:225], v162 offset:6144
	ds_read_b128 v[226:229], v162 offset:7168
	global_load_lds_dwordx4 v[140:141], off
	v_lshl_add_u64 v[140:141], s[24:25], 0, v[138:139]
	s_add_i32 m0, s35, 0xe000
	s_nop 0
	global_load_lds_dwordx4 v[140:141], off
	s_waitcnt lgkmcnt(8)
	s_barrier
	s_setprio 1
	s_waitcnt lgkmcnt(7)
	v_mfma_f32_16x16x32_bf16 v[126:129], v[164:167], v[180:183], v[126:129]
	v_mfma_f32_16x16x32_bf16 v[122:125], v[172:175], v[180:183], v[122:125]
	s_waitcnt lgkmcnt(5)
	v_mfma_f32_16x16x32_bf16 v[114:117], v[164:167], v[206:209], v[114:117]
	v_mfma_f32_16x16x32_bf16 v[106:109], v[172:175], v[206:209], v[106:109]
	s_waitcnt lgkmcnt(3)
	v_mfma_f32_16x16x32_bf16 v[98:101], v[164:167], v[214:217], v[98:101]
	v_mfma_f32_16x16x32_bf16 v[90:93], v[172:175], v[214:217], v[90:93]
	s_waitcnt lgkmcnt(1)
	v_mfma_f32_16x16x32_bf16 v[82:85], v[164:167], v[222:225], v[82:85]
	v_mfma_f32_16x16x32_bf16 v[74:77], v[172:175], v[222:225], v[74:77]
	v_mfma_f32_16x16x32_bf16 v[126:129], v[168:171], v[184:187], v[126:129]
	v_mfma_f32_16x16x32_bf16 v[122:125], v[176:179], v[184:187], v[122:125]
	v_mfma_f32_16x16x32_bf16 v[114:117], v[168:171], v[210:213], v[114:117]
	v_mfma_f32_16x16x32_bf16 v[106:109], v[176:179], v[210:213], v[106:109]
	v_mfma_f32_16x16x32_bf16 v[98:101], v[168:171], v[218:221], v[98:101]
	v_mfma_f32_16x16x32_bf16 v[90:93], v[176:179], v[218:221], v[90:93]
	s_waitcnt lgkmcnt(0)
	v_mfma_f32_16x16x32_bf16 v[82:85], v[168:171], v[226:229], v[82:85]
	v_mfma_f32_16x16x32_bf16 v[74:77], v[176:179], v[226:229], v[74:77]
	s_barrier
	s_setprio 0
	s_add_i32 s53, 0, 0x14000
	v_add_u32_e32 v140, s53, v144
	s_add_i32 s24, s52, s31
	ds_read_b128 v[230:233], v140
	ds_read_b128 v[234:237], v140 offset:1024
	ds_read_b128 v[238:241], v140 offset:2048
	ds_read_b128 v[242:245], v140 offset:3072
	v_lshl_add_u64 v[140:141], s[26:27], 0, v[0:1]
	s_mov_b32 m0, s24
	v_lshl_add_u64 v[246:247], s[26:27], 0, v[130:131]
	global_load_lds_dwordx4 v[140:141], off
	s_add_i32 m0, s24, 0x2000
	s_nop 0
	global_load_lds_dwordx4 v[246:247], off
	s_barrier
	s_setprio 1
	s_waitcnt lgkmcnt(3)
	v_mfma_f32_16x16x32_bf16 v[118:121], v[230:233], v[180:183], v[118:121]
	s_waitcnt lgkmcnt(1)
	v_mfma_f32_16x16x32_bf16 v[110:113], v[238:241], v[180:183], v[110:113]
	v_mfma_f32_16x16x32_bf16 v[102:105], v[230:233], v[206:209], v[102:105]
	v_mfma_f32_16x16x32_bf16 v[94:97], v[238:241], v[206:209], v[94:97]
	v_mfma_f32_16x16x32_bf16 v[86:89], v[230:233], v[214:217], v[86:89]
	v_mfma_f32_16x16x32_bf16 v[78:81], v[238:241], v[214:217], v[78:81]
	v_mfma_f32_16x16x32_bf16 v[70:73], v[230:233], v[222:225], v[70:73]
	v_mfma_f32_16x16x32_bf16 v[66:69], v[238:241], v[222:225], v[66:69]
	v_mfma_f32_16x16x32_bf16 v[118:121], v[234:237], v[184:187], v[118:121]
	s_waitcnt lgkmcnt(0)
	v_mfma_f32_16x16x32_bf16 v[110:113], v[242:245], v[184:187], v[110:113]
	v_mfma_f32_16x16x32_bf16 v[102:105], v[234:237], v[210:213], v[102:105]
	v_mfma_f32_16x16x32_bf16 v[94:97], v[242:245], v[210:213], v[94:97]
	v_mfma_f32_16x16x32_bf16 v[86:89], v[234:237], v[218:221], v[86:89]
	v_mfma_f32_16x16x32_bf16 v[78:81], v[242:245], v[218:221], v[78:81]
	v_mfma_f32_16x16x32_bf16 v[70:73], v[234:237], v[226:229], v[70:73]
	v_mfma_f32_16x16x32_bf16 v[66:69], v[242:245], v[226:229], v[66:69]
	s_barrier
	s_setprio 0
	s_mov_b32 m0, s35
	v_lshl_add_u64 v[248:249], s[28:29], 0, v[134:135]
	ds_read_b128 v[180:183], v162 offset:16384
	ds_read_b128 v[184:187], v162 offset:17408
	ds_read_b128 v[206:209], v162 offset:18432
	ds_read_b128 v[210:213], v162 offset:19456
	ds_read_b128 v[214:217], v162 offset:20480
	ds_read_b128 v[218:221], v162 offset:21504
	ds_read_b128 v[222:225], v162 offset:22528
	ds_read_b128 v[226:229], v162 offset:23552
	global_load_lds_dwordx4 v[248:249], off
	v_lshl_add_u64 v[250:251], s[28:29], 0, v[132:133]
	s_mov_b32 m0, s36
	s_nop 0
	global_load_lds_dwordx4 v[250:251], off
	s_barrier
	s_setprio 1
	s_waitcnt lgkmcnt(7)
	v_mfma_f32_16x16x32_bf16 v[62:65], v[164:167], v[180:183], v[62:65]
	v_mfma_f32_16x16x32_bf16 v[58:61], v[172:175], v[180:183], v[58:61]
	s_waitcnt lgkmcnt(5)
	v_mfma_f32_16x16x32_bf16 v[50:53], v[164:167], v[206:209], v[50:53]
	v_mfma_f32_16x16x32_bf16 v[42:45], v[172:175], v[206:209], v[42:45]
	s_waitcnt lgkmcnt(3)
	v_mfma_f32_16x16x32_bf16 v[34:37], v[164:167], v[214:217], v[34:37]
	v_mfma_f32_16x16x32_bf16 v[26:29], v[172:175], v[214:217], v[26:29]
	s_waitcnt lgkmcnt(1)
	v_mfma_f32_16x16x32_bf16 v[18:21], v[164:167], v[222:225], v[18:21]
	v_mfma_f32_16x16x32_bf16 v[10:13], v[172:175], v[222:225], v[10:13]
	v_mfma_f32_16x16x32_bf16 v[62:65], v[168:171], v[184:187], v[62:65]
	v_mfma_f32_16x16x32_bf16 v[58:61], v[176:179], v[184:187], v[58:61]
	v_mfma_f32_16x16x32_bf16 v[50:53], v[168:171], v[210:213], v[50:53]
	v_mfma_f32_16x16x32_bf16 v[42:45], v[176:179], v[210:213], v[42:45]
	v_mfma_f32_16x16x32_bf16 v[34:37], v[168:171], v[218:221], v[34:37]
	v_mfma_f32_16x16x32_bf16 v[26:29], v[176:179], v[218:221], v[26:29]
	s_waitcnt lgkmcnt(0)
	v_mfma_f32_16x16x32_bf16 v[18:21], v[168:171], v[226:229], v[18:21]
	v_mfma_f32_16x16x32_bf16 v[10:13], v[176:179], v[226:229], v[10:13]
	s_barrier
	s_setprio 0
	s_add_u32 s24, s26, 0xb0000
	s_addc_u32 s25, s27, 0
	s_add_i32 s52, s53, s31
	v_lshl_add_u64 v[164:165], s[24:25], 0, v[0:1]
	s_mov_b32 m0, s52
	s_nop 0
	global_load_lds_dwordx4 v[164:165], off
	v_lshl_add_u64 v[164:165], s[24:25], 0, v[130:131]
	s_add_i32 m0, s52, 0x2000
	s_nop 0
	global_load_lds_dwordx4 v[164:165], off
	s_waitcnt vmcnt(6)
	s_barrier
	s_setprio 1
	v_mfma_f32_16x16x32_bf16 v[54:57], v[230:233], v[180:183], v[54:57]
	v_mfma_f32_16x16x32_bf16 v[46:49], v[238:241], v[180:183], v[46:49]
	v_mfma_f32_16x16x32_bf16 v[38:41], v[230:233], v[206:209], v[38:41]
	v_mfma_f32_16x16x32_bf16 v[30:33], v[238:241], v[206:209], v[30:33]
	v_mfma_f32_16x16x32_bf16 v[22:25], v[230:233], v[214:217], v[22:25]
	v_mfma_f32_16x16x32_bf16 v[14:17], v[238:241], v[214:217], v[14:17]
	v_mfma_f32_16x16x32_bf16 v[6:9], v[230:233], v[222:225], v[6:9]
	v_mfma_f32_16x16x32_bf16 v[2:5], v[238:241], v[222:225], v[2:5]
	v_mfma_f32_16x16x32_bf16 v[54:57], v[234:237], v[184:187], v[54:57]
	v_mfma_f32_16x16x32_bf16 v[46:49], v[242:245], v[184:187], v[46:49]
	v_mfma_f32_16x16x32_bf16 v[38:41], v[234:237], v[210:213], v[38:41]
	v_mfma_f32_16x16x32_bf16 v[30:33], v[242:245], v[210:213], v[30:33]
	v_mfma_f32_16x16x32_bf16 v[22:25], v[234:237], v[218:221], v[22:25]
	v_mfma_f32_16x16x32_bf16 v[14:17], v[242:245], v[218:221], v[14:17]
	v_mfma_f32_16x16x32_bf16 v[6:9], v[234:237], v[226:229], v[6:9]
	v_mfma_f32_16x16x32_bf16 v[2:5], v[242:245], v[226:229], v[2:5]
	s_barrier
	s_setprio 0
	s_add_i32 s52, 0, 0x18000
	v_add_u32_e32 v163, s52, v144
	ds_read_b128 v[164:167], v163
	ds_read_b128 v[168:171], v163 offset:1024
	ds_read_b128 v[172:175], v163 offset:2048
	ds_read_b128 v[176:179], v163 offset:3072
	s_add_u32 s24, s28, 0xb0000
	s_addc_u32 s25, s29, 0
	s_mov_b32 m0, s37
	v_lshl_add_u64 v[230:231], s[24:25], 0, v[134:135]
	ds_read_b128 v[180:183], v162 offset:32768
	ds_read_b128 v[184:187], v162 offset:33792
	ds_read_b128 v[206:209], v162 offset:34816
	ds_read_b128 v[210:213], v162 offset:35840
	ds_read_b128 v[214:217], v162 offset:36864
	ds_read_b128 v[218:221], v162 offset:37888
	ds_read_b128 v[222:225], v162 offset:38912
	ds_read_b128 v[226:229], v162 offset:39936
	global_load_lds_dwordx4 v[230:231], off
	v_lshl_add_u64 v[230:231], s[24:25], 0, v[132:133]
	s_mov_b32 m0, s42
	s_nop 0
	global_load_lds_dwordx4 v[230:231], off
	s_waitcnt lgkmcnt(8)
	s_barrier
	s_setprio 1
	s_waitcnt lgkmcnt(7)
	v_mfma_f32_16x16x32_bf16 v[126:129], v[164:167], v[180:183], v[126:129]
	v_mfma_f32_16x16x32_bf16 v[122:125], v[172:175], v[180:183], v[122:125]
	s_waitcnt lgkmcnt(5)
	v_mfma_f32_16x16x32_bf16 v[114:117], v[164:167], v[206:209], v[114:117]
	v_mfma_f32_16x16x32_bf16 v[106:109], v[172:175], v[206:209], v[106:109]
	s_waitcnt lgkmcnt(3)
	v_mfma_f32_16x16x32_bf16 v[98:101], v[164:167], v[214:217], v[98:101]
	v_mfma_f32_16x16x32_bf16 v[90:93], v[172:175], v[214:217], v[90:93]
	s_waitcnt lgkmcnt(1)
	v_mfma_f32_16x16x32_bf16 v[82:85], v[164:167], v[222:225], v[82:85]
	v_mfma_f32_16x16x32_bf16 v[74:77], v[172:175], v[222:225], v[74:77]
	v_mfma_f32_16x16x32_bf16 v[126:129], v[168:171], v[184:187], v[126:129]
	v_mfma_f32_16x16x32_bf16 v[122:125], v[176:179], v[184:187], v[122:125]
	v_mfma_f32_16x16x32_bf16 v[114:117], v[168:171], v[210:213], v[114:117]
	v_mfma_f32_16x16x32_bf16 v[106:109], v[176:179], v[210:213], v[106:109]
	v_mfma_f32_16x16x32_bf16 v[98:101], v[168:171], v[218:221], v[98:101]
	v_mfma_f32_16x16x32_bf16 v[90:93], v[176:179], v[218:221], v[90:93]
	s_waitcnt lgkmcnt(0)
	v_mfma_f32_16x16x32_bf16 v[82:85], v[168:171], v[226:229], v[82:85]
	v_mfma_f32_16x16x32_bf16 v[74:77], v[176:179], v[226:229], v[74:77]
	s_barrier
	s_setprio 0
	s_add_i32 s28, 0, 0x1c000
	s_add_i32 s24, s52, s31
	v_add_u32_e32 v163, s28, v144
	v_lshl_add_u64 v[140:141], v[140:141], 0, s[94:95]
	s_mov_b32 m0, s24
	ds_read_b128 v[230:233], v163
	ds_read_b128 v[234:237], v163 offset:1024
	ds_read_b128 v[238:241], v163 offset:2048
	ds_read_b128 v[242:245], v163 offset:3072
	global_load_lds_dwordx4 v[140:141], off
	v_lshl_add_u64 v[140:141], v[246:247], 0, s[94:95]
	s_add_i32 m0, s24, 0x2000
	s_nop 0
	global_load_lds_dwordx4 v[140:141], off
	s_barrier
	s_setprio 1
	s_waitcnt lgkmcnt(3)
	v_mfma_f32_16x16x32_bf16 v[118:121], v[230:233], v[180:183], v[118:121]
	s_waitcnt lgkmcnt(1)
	v_mfma_f32_16x16x32_bf16 v[110:113], v[238:241], v[180:183], v[110:113]
	v_mfma_f32_16x16x32_bf16 v[102:105], v[230:233], v[206:209], v[102:105]
	v_mfma_f32_16x16x32_bf16 v[94:97], v[238:241], v[206:209], v[94:97]
	v_mfma_f32_16x16x32_bf16 v[86:89], v[230:233], v[214:217], v[86:89]
	v_mfma_f32_16x16x32_bf16 v[78:81], v[238:241], v[214:217], v[78:81]
	v_mfma_f32_16x16x32_bf16 v[70:73], v[230:233], v[222:225], v[70:73]
	v_mfma_f32_16x16x32_bf16 v[66:69], v[238:241], v[222:225], v[66:69]
	v_mfma_f32_16x16x32_bf16 v[118:121], v[234:237], v[184:187], v[118:121]
	s_waitcnt lgkmcnt(0)
	v_mfma_f32_16x16x32_bf16 v[110:113], v[242:245], v[184:187], v[110:113]
	v_mfma_f32_16x16x32_bf16 v[102:105], v[234:237], v[210:213], v[102:105]
	v_mfma_f32_16x16x32_bf16 v[94:97], v[242:245], v[210:213], v[94:97]
	v_mfma_f32_16x16x32_bf16 v[86:89], v[234:237], v[218:221], v[86:89]
	v_mfma_f32_16x16x32_bf16 v[78:81], v[242:245], v[218:221], v[78:81]
	v_mfma_f32_16x16x32_bf16 v[70:73], v[234:237], v[226:229], v[70:73]
	v_mfma_f32_16x16x32_bf16 v[66:69], v[242:245], v[226:229], v[66:69]
	s_barrier
	s_setprio 0
	s_mov_b32 m0, s44
	v_lshl_add_u64 v[140:141], v[248:249], 0, s[94:95]
	ds_read_b128 v[180:183], v162 offset:49152
	ds_read_b128 v[184:187], v162 offset:50176
	ds_read_b128 v[206:209], v162 offset:51200
	ds_read_b128 v[210:213], v162 offset:52224
	ds_read_b128 v[214:217], v162 offset:53248
	ds_read_b128 v[218:221], v162 offset:54272
	ds_read_b128 v[222:225], v162 offset:55296
	ds_read_b128 v[226:229], v162 offset:56320
	global_load_lds_dwordx4 v[140:141], off
	v_lshl_add_u64 v[140:141], v[250:251], 0, s[94:95]
	s_mov_b32 m0, s45
	s_nop 0
	global_load_lds_dwordx4 v[140:141], off
	s_barrier
	s_setprio 1
	s_waitcnt lgkmcnt(7)
	v_mfma_f32_16x16x32_bf16 v[62:65], v[164:167], v[180:183], v[62:65]
	v_mfma_f32_16x16x32_bf16 v[58:61], v[172:175], v[180:183], v[58:61]
	s_waitcnt lgkmcnt(5)
	v_mfma_f32_16x16x32_bf16 v[50:53], v[164:167], v[206:209], v[50:53]
	v_mfma_f32_16x16x32_bf16 v[42:45], v[172:175], v[206:209], v[42:45]
	s_waitcnt lgkmcnt(3)
	v_mfma_f32_16x16x32_bf16 v[34:37], v[164:167], v[214:217], v[34:37]
	v_mfma_f32_16x16x32_bf16 v[26:29], v[172:175], v[214:217], v[26:29]
	s_waitcnt lgkmcnt(1)
	v_mfma_f32_16x16x32_bf16 v[18:21], v[164:167], v[222:225], v[18:21]
	v_mfma_f32_16x16x32_bf16 v[10:13], v[172:175], v[222:225], v[10:13]
	v_mfma_f32_16x16x32_bf16 v[62:65], v[168:171], v[184:187], v[62:65]
	v_mfma_f32_16x16x32_bf16 v[58:61], v[176:179], v[184:187], v[58:61]
	v_mfma_f32_16x16x32_bf16 v[50:53], v[168:171], v[210:213], v[50:53]
	v_mfma_f32_16x16x32_bf16 v[42:45], v[176:179], v[210:213], v[42:45]
	v_mfma_f32_16x16x32_bf16 v[34:37], v[168:171], v[218:221], v[34:37]
	v_mfma_f32_16x16x32_bf16 v[26:29], v[176:179], v[218:221], v[26:29]
	s_waitcnt lgkmcnt(0)
	v_mfma_f32_16x16x32_bf16 v[18:21], v[168:171], v[226:229], v[18:21]
	v_mfma_f32_16x16x32_bf16 v[10:13], v[176:179], v[226:229], v[10:13]
	s_barrier
	s_setprio 0
	s_add_u32 s24, s26, 0xb0080
	s_addc_u32 s25, s27, 0
	s_add_i32 s26, s28, s31
	v_lshl_add_u64 v[140:141], s[24:25], 0, v[0:1]
	s_mov_b32 m0, s26
	s_nop 0
	global_load_lds_dwordx4 v[140:141], off
	v_lshl_add_u64 v[140:141], s[24:25], 0, v[130:131]
	s_add_i32 m0, s26, 0x2000
	s_nop 0
	global_load_lds_dwordx4 v[140:141], off
	s_waitcnt vmcnt(6)
	s_barrier
	s_setprio 1
	v_mfma_f32_16x16x32_bf16 v[54:57], v[230:233], v[180:183], v[54:57]
	v_mfma_f32_16x16x32_bf16 v[46:49], v[238:241], v[180:183], v[46:49]
	v_mfma_f32_16x16x32_bf16 v[38:41], v[230:233], v[206:209], v[38:41]
	v_mfma_f32_16x16x32_bf16 v[30:33], v[238:241], v[206:209], v[30:33]
	v_mfma_f32_16x16x32_bf16 v[22:25], v[230:233], v[214:217], v[22:25]
	v_mfma_f32_16x16x32_bf16 v[14:17], v[238:241], v[214:217], v[14:17]
	v_mfma_f32_16x16x32_bf16 v[6:9], v[230:233], v[222:225], v[6:9]
	v_mfma_f32_16x16x32_bf16 v[2:5], v[238:241], v[222:225], v[2:5]
	v_mfma_f32_16x16x32_bf16 v[54:57], v[234:237], v[184:187], v[54:57]
	v_mfma_f32_16x16x32_bf16 v[46:49], v[242:245], v[184:187], v[46:49]
	v_mfma_f32_16x16x32_bf16 v[38:41], v[234:237], v[210:213], v[38:41]
	v_mfma_f32_16x16x32_bf16 v[30:33], v[242:245], v[210:213], v[30:33]
	v_mfma_f32_16x16x32_bf16 v[22:25], v[234:237], v[218:221], v[22:25]
	v_mfma_f32_16x16x32_bf16 v[14:17], v[242:245], v[218:221], v[14:17]
	v_mfma_f32_16x16x32_bf16 v[6:9], v[234:237], v[226:229], v[6:9]
	v_mfma_f32_16x16x32_bf16 v[2:5], v[242:245], v[226:229], v[2:5]
	s_barrier
	s_setprio 0
	s_add_i32 s51, s51, 2
	s_add_u32 s40, s40, 0x100
	s_addc_u32 s41, s41, 0
	s_cmp_gt_u32 s51, 41
	s_mov_b64 s[24:25], s[22:23]
	s_cbranch_scc0 .LBB0_331
	v_lshl_or_b32 v140, s50, 8, v145
	v_lshl_add_u32 v164, s49, 8, v143
	v_ashrrev_i32_e32 v141, 31, v140
	v_ashrrev_i32_e32 v165, 31, v164
	v_lshl_add_u64 v[166:167], v[140:141], 1, s[20:21]
	v_lshlrev_b64 v[140:141], 11, v[164:165]
	v_lshl_add_u64 v[140:141], v[166:167], 0, v[140:141]
	v_pk_add_f32 v[128:129], v[128:129], 0 op_sel_hi:[1,0]
	v_pk_add_f32 v[126:127], v[126:127], 0 op_sel_hi:[1,0]
	v_pk_add_f32 v[168:169], v[124:125], 0 op_sel_hi:[1,0]
	v_pk_add_f32 v[124:125], v[122:123], 0 op_sel_hi:[1,0]
	v_cvt_pk_bf16_f32 v122, v126, v127
	v_cvt_pk_bf16_f32 v123, v128, v129
	v_pk_add_f32 v[118:119], v[118:119], 0 op_sel_hi:[1,0]
	v_cvt_pk_bf16_f32 v124, v124, v125
	v_cvt_pk_bf16_f32 v125, v168, v169
	global_store_dwordx4 v[140:141], v[122:125], off
	v_pk_add_f32 v[120:121], v[120:121], 0 op_sel_hi:[1,0]
	v_pk_add_f32 v[114:115], v[114:115], 0 op_sel_hi:[1,0]
	v_pk_add_f32 v[122:123], v[112:113], 0 op_sel_hi:[1,0]
	v_pk_add_f32 v[112:113], v[110:111], 0 op_sel_hi:[1,0]
	v_cvt_pk_bf16_f32 v110, v118, v119
	v_cvt_pk_bf16_f32 v111, v120, v121
	v_pk_add_f32 v[102:103], v[102:103], 0 op_sel_hi:[1,0]
	v_cvt_pk_bf16_f32 v112, v112, v113
	v_cvt_pk_bf16_f32 v113, v122, v123
	global_store_dwordx4 v[140:141], v[110:113], off offset:256
	v_pk_add_f32 v[104:105], v[104:105], 0 op_sel_hi:[1,0]
	v_pk_add_f32 v[98:99], v[98:99], 0 op_sel_hi:[1,0]
	v_or_b32_e32 v110, 16, v164
	v_ashrrev_i32_e32 v111, 31, v110
	v_lshlrev_b64 v[110:111], 11, v[110:111]
	v_lshl_add_u64 v[110:111], v[166:167], 0, v[110:111]
	v_pk_add_f32 v[112:113], v[116:117], 0 op_sel_hi:[1,0]
	v_pk_add_f32 v[116:117], v[108:109], 0 op_sel_hi:[1,0]
	v_pk_add_f32 v[108:109], v[106:107], 0 op_sel_hi:[1,0]
	v_cvt_pk_bf16_f32 v106, v114, v115
	v_cvt_pk_bf16_f32 v107, v112, v113
	v_pk_add_f32 v[86:87], v[86:87], 0 op_sel_hi:[1,0]
	v_cvt_pk_bf16_f32 v108, v108, v109
	v_cvt_pk_bf16_f32 v109, v116, v117
	global_store_dwordx4 v[110:111], v[106:109], off
	v_pk_add_f32 v[88:89], v[88:89], 0 op_sel_hi:[1,0]
	v_pk_add_f32 v[82:83], v[82:83], 0 op_sel_hi:[1,0]
	v_pk_add_f32 v[106:107], v[96:97], 0 op_sel_hi:[1,0]
	v_pk_add_f32 v[96:97], v[94:95], 0 op_sel_hi:[1,0]
	v_cvt_pk_bf16_f32 v94, v102, v103
	v_cvt_pk_bf16_f32 v95, v104, v105
	v_pk_add_f32 v[72:73], v[72:73], 0 op_sel_hi:[1,0]
	v_cvt_pk_bf16_f32 v96, v96, v97
	v_cvt_pk_bf16_f32 v97, v106, v107
	global_store_dwordx4 v[110:111], v[94:97], off offset:256
	v_pk_add_f32 v[70:71], v[70:71], 0 op_sel_hi:[1,0]
	v_pk_add_f32 v[62:63], v[62:63], 0 op_sel_hi:[1,0]
	v_or_b32_e32 v94, 32, v164
	v_ashrrev_i32_e32 v95, 31, v94
	v_lshlrev_b64 v[94:95], 11, v[94:95]
	v_lshl_add_u64 v[94:95], v[166:167], 0, v[94:95]
	v_pk_add_f32 v[96:97], v[100:101], 0 op_sel_hi:[1,0]
	v_pk_add_f32 v[100:101], v[92:93], 0 op_sel_hi:[1,0]
	v_pk_add_f32 v[92:93], v[90:91], 0 op_sel_hi:[1,0]
	v_cvt_pk_bf16_f32 v90, v98, v99
	v_cvt_pk_bf16_f32 v91, v96, v97
	v_pk_add_f32 v[64:65], v[64:65], 0 op_sel_hi:[1,0]
	v_cvt_pk_bf16_f32 v92, v92, v93
	v_cvt_pk_bf16_f32 v93, v100, v101
	global_store_dwordx4 v[94:95], v[90:93], off
	s_mov_b64 s[22:23], 0x40000
	v_pk_add_f32 v[56:57], v[56:57], 0 op_sel_hi:[1,0]
	v_pk_add_f32 v[90:91], v[80:81], 0 op_sel_hi:[1,0]
	v_pk_add_f32 v[80:81], v[78:79], 0 op_sel_hi:[1,0]
	v_cvt_pk_bf16_f32 v78, v86, v87
	v_cvt_pk_bf16_f32 v79, v88, v89
	v_pk_add_f32 v[54:55], v[54:55], 0 op_sel_hi:[1,0]
	v_cvt_pk_bf16_f32 v80, v80, v81
	v_cvt_pk_bf16_f32 v81, v90, v91
	global_store_dwordx4 v[94:95], v[78:81], off offset:256
	v_pk_add_f32 v[50:51], v[50:51], 0 op_sel_hi:[1,0]
	v_pk_add_f32 v[40:41], v[40:41], 0 op_sel_hi:[1,0]
	v_or_b32_e32 v78, 48, v164
	v_ashrrev_i32_e32 v79, 31, v78
	v_lshlrev_b64 v[78:79], 11, v[78:79]
	v_lshl_add_u64 v[78:79], v[166:167], 0, v[78:79]
	v_pk_add_f32 v[80:81], v[84:85], 0 op_sel_hi:[1,0]
	v_pk_add_f32 v[84:85], v[76:77], 0 op_sel_hi:[1,0]
	v_pk_add_f32 v[76:77], v[74:75], 0 op_sel_hi:[1,0]
	v_cvt_pk_bf16_f32 v74, v82, v83
	v_cvt_pk_bf16_f32 v75, v80, v81
	v_pk_add_f32 v[38:39], v[38:39], 0 op_sel_hi:[1,0]
	v_cvt_pk_bf16_f32 v76, v76, v77
	v_cvt_pk_bf16_f32 v77, v84, v85
	global_store_dwordx4 v[78:79], v[74:77], off
	v_pk_add_f32 v[34:35], v[34:35], 0 op_sel_hi:[1,0]
	v_pk_add_f32 v[24:25], v[24:25], 0 op_sel_hi:[1,0]
	v_pk_add_f32 v[74:75], v[68:69], 0 op_sel_hi:[1,0]
	v_pk_add_f32 v[68:69], v[66:67], 0 op_sel_hi:[1,0]
	v_cvt_pk_bf16_f32 v66, v70, v71
	v_cvt_pk_bf16_f32 v67, v72, v73
	v_pk_add_f32 v[22:23], v[22:23], 0 op_sel_hi:[1,0]
	v_cvt_pk_bf16_f32 v68, v68, v69
	v_cvt_pk_bf16_f32 v69, v74, v75
	global_store_dwordx4 v[78:79], v[66:69], off offset:256
	v_pk_add_f32 v[18:19], v[18:19], 0 op_sel_hi:[1,0]
	s_mov_b32 s50, s47
	v_pk_add_f32 v[68:69], v[60:61], 0 op_sel_hi:[1,0]
	v_pk_add_f32 v[60:61], v[58:59], 0 op_sel_hi:[1,0]
	v_cvt_pk_bf16_f32 v58, v62, v63
	v_add_co_u32_e32 v62, vcc, s67, v140
	v_cvt_pk_bf16_f32 v59, v64, v65
	v_cvt_pk_bf16_f32 v60, v60, v61
	v_cvt_pk_bf16_f32 v61, v68, v69
	v_lshl_add_u64 v[66:67], v[140:141], 0, s[22:23]
	s_nop 0
	v_addc_co_u32_e32 v63, vcc, 0, v141, vcc
	global_store_dwordx4 v[62:63], v[58:61], off
	s_mov_b64 s[22:23], 0x48000
	s_mov_b32 s49, s48
	v_pk_add_f32 v[58:59], v[48:49], 0 op_sel_hi:[1,0]
	v_pk_add_f32 v[48:49], v[46:47], 0 op_sel_hi:[1,0]
	v_cvt_pk_bf16_f32 v46, v54, v55
	v_cvt_pk_bf16_f32 v47, v56, v57
	s_mov_b64 s[24:25], s[2:3]
	v_cvt_pk_bf16_f32 v48, v48, v49
	v_cvt_pk_bf16_f32 v49, v58, v59
	global_store_dwordx4 v[66:67], v[46:49], off offset:256
	v_pk_add_f32 v[8:9], v[8:9], 0 op_sel_hi:[1,0]
	v_pk_add_f32 v[6:7], v[6:7], 0 op_sel_hi:[1,0]
	v_pk_add_f32 v[48:49], v[52:53], 0 op_sel_hi:[1,0]
	v_pk_add_f32 v[52:53], v[44:45], 0 op_sel_hi:[1,0]
	v_pk_add_f32 v[44:45], v[42:43], 0 op_sel_hi:[1,0]
	v_cvt_pk_bf16_f32 v42, v50, v51
	v_cvt_pk_bf16_f32 v43, v48, v49
	v_add_co_u32_e32 v48, vcc, s68, v140
	v_cvt_pk_bf16_f32 v44, v44, v45
	v_cvt_pk_bf16_f32 v45, v52, v53
	v_lshl_add_u64 v[46:47], v[140:141], 0, s[22:23]
	s_nop 0
	v_addc_co_u32_e32 v49, vcc, 0, v141, vcc
	global_store_dwordx4 v[48:49], v[42:45], off
	s_mov_b64 s[22:23], 0x50000
	s_nop 0
	v_pk_add_f32 v[42:43], v[32:33], 0 op_sel_hi:[1,0]
	v_pk_add_f32 v[32:33], v[30:31], 0 op_sel_hi:[1,0]
	v_cvt_pk_bf16_f32 v30, v38, v39
	v_cvt_pk_bf16_f32 v31, v40, v41
	s_nop 0
	v_cvt_pk_bf16_f32 v32, v32, v33
	v_cvt_pk_bf16_f32 v33, v42, v43
	global_store_dwordx4 v[46:47], v[30:33], off offset:256
	s_nop 1
	v_lshl_add_u64 v[30:31], v[140:141], 0, s[22:23]
	v_pk_add_f32 v[32:33], v[36:37], 0 op_sel_hi:[1,0]
	s_mov_b32 s22, 0x50000
	v_pk_add_f32 v[36:37], v[28:29], 0 op_sel_hi:[1,0]
	v_pk_add_f32 v[28:29], v[26:27], 0 op_sel_hi:[1,0]
	v_cvt_pk_bf16_f32 v26, v34, v35
	v_cvt_pk_bf16_f32 v27, v32, v33
	v_add_co_u32_e32 v32, vcc, s22, v140
	v_cvt_pk_bf16_f32 v28, v28, v29
	v_cvt_pk_bf16_f32 v29, v36, v37
	s_mov_b64 s[22:23], 0x58000
	s_nop 0
	v_addc_co_u32_e32 v33, vcc, 0, v141, vcc
	global_store_dwordx4 v[32:33], v[26:29], off
	s_nop 1
	v_pk_add_f32 v[26:27], v[16:17], 0 op_sel_hi:[1,0]
	v_pk_add_f32 v[16:17], v[14:15], 0 op_sel_hi:[1,0]
	v_cvt_pk_bf16_f32 v14, v22, v23
	v_cvt_pk_bf16_f32 v15, v24, v25
	s_nop 0
	v_cvt_pk_bf16_f32 v16, v16, v17
	v_cvt_pk_bf16_f32 v17, v26, v27
	global_store_dwordx4 v[30:31], v[14:17], off offset:256
	s_nop 1
	v_lshl_add_u64 v[14:15], v[140:141], 0, s[22:23]
	v_pk_add_f32 v[16:17], v[20:21], 0 op_sel_hi:[1,0]
	s_mov_b32 s22, 0x58000
	v_pk_add_f32 v[20:21], v[12:13], 0 op_sel_hi:[1,0]
	v_pk_add_f32 v[12:13], v[10:11], 0 op_sel_hi:[1,0]
	v_cvt_pk_bf16_f32 v10, v18, v19
	v_cvt_pk_bf16_f32 v11, v16, v17
	v_add_co_u32_e32 v16, vcc, s22, v140
	v_cvt_pk_bf16_f32 v12, v12, v13
	v_cvt_pk_bf16_f32 v13, v20, v21
	s_mov_b64 s[22:23], s[0:1]
	s_nop 0
	v_addc_co_u32_e32 v17, vcc, 0, v141, vcc
	global_store_dwordx4 v[16:17], v[10:13], off
	s_and_b64 vcc, exec, s[38:39]
	s_nop 0
	v_pk_add_f32 v[10:11], v[4:5], 0 op_sel_hi:[1,0]
	v_pk_add_f32 v[4:5], v[2:3], 0 op_sel_hi:[1,0]
	v_cvt_pk_bf16_f32 v2, v6, v7
	v_cvt_pk_bf16_f32 v3, v8, v9
	s_nop 0
	v_cvt_pk_bf16_f32 v4, v4, v5
	v_cvt_pk_bf16_f32 v5, v10, v11
	global_store_dwordx4 v[14:15], v[2:5], off offset:256
	s_cbranch_vccz .LBB0_320
	s_waitcnt vmcnt(16)
	s_cmpk_gt_u32 s30, 0xff
	s_cbranch_scc1 .LBB0_335
	s_barrier

.LBB0_360:
	s_add_u32 s44, s42, 0xfffc0080
	s_addc_u32 s45, s43, -1
	s_add_i32 s63, 0, 0x10000
	v_add_u32_e32 v0, s63, v206
	ds_read_b128 v[82:85], v0
	ds_read_b128 v[86:89], v0 offset:1024
	ds_read_b128 v[90:93], v0 offset:2048
	ds_read_b128 v[94:97], v0 offset:3072
	s_cmp_eq_u32 s62, 12
	s_cselect_b32 s47, s1, s45
	s_cselect_b32 s46, s3, s44
	s_cselect_b32 s45, s31, s61
	s_cselect_b32 s44, s35, s60
	v_lshl_add_u64 v[230:231], s[42:43], 0, v[174:175]
	s_add_i32 m0, s51, 0xc000
	ds_read_b128 v[176:179], v208
	ds_read_b128 v[180:183], v208 offset:1024
	ds_read_b128 v[184:187], v208 offset:2048
	ds_read_b128 v[210:213], v208 offset:3072
	ds_read_b128 v[214:217], v208 offset:4096
	ds_read_b128 v[218:221], v208 offset:5120
	ds_read_b128 v[222:225], v208 offset:6144
	ds_read_b128 v[226:229], v208 offset:7168
	global_load_lds_dwordx4 v[230:231], off
	v_lshl_add_u64 v[230:231], s[42:43], 0, v[172:173]
	s_add_i32 m0, s51, 0xe000
	s_nop 0
	global_load_lds_dwordx4 v[230:231], off
	s_waitcnt lgkmcnt(8)
	s_barrier
	s_setprio 1
	s_waitcnt lgkmcnt(7)
	v_mfma_f32_16x16x32_bf16 v[142:145], v[82:85], v[176:179], v[142:145]
	v_mfma_f32_16x16x32_bf16 v[138:141], v[90:93], v[176:179], v[138:141]
	s_waitcnt lgkmcnt(5)
	v_mfma_f32_16x16x32_bf16 v[126:129], v[82:85], v[184:187], v[126:129]
	v_mfma_f32_16x16x32_bf16 v[122:125], v[90:93], v[184:187], v[122:125]
	s_waitcnt lgkmcnt(3)
	v_mfma_f32_16x16x32_bf16 v[110:113], v[82:85], v[214:217], v[110:113]
	v_mfma_f32_16x16x32_bf16 v[106:109], v[90:93], v[214:217], v[106:109]
	s_waitcnt lgkmcnt(1)
	v_mfma_f32_16x16x32_bf16 v[78:81], v[82:85], v[222:225], v[78:81]
	v_mfma_f32_16x16x32_bf16 v[74:77], v[90:93], v[222:225], v[74:77]
	v_mfma_f32_16x16x32_bf16 v[142:145], v[86:89], v[180:183], v[142:145]
	v_mfma_f32_16x16x32_bf16 v[138:141], v[94:97], v[180:183], v[138:141]
	v_mfma_f32_16x16x32_bf16 v[126:129], v[86:89], v[210:213], v[126:129]
	v_mfma_f32_16x16x32_bf16 v[122:125], v[94:97], v[210:213], v[122:125]
	v_mfma_f32_16x16x32_bf16 v[110:113], v[86:89], v[218:221], v[110:113]
	v_mfma_f32_16x16x32_bf16 v[106:109], v[94:97], v[218:221], v[106:109]
	s_waitcnt lgkmcnt(0)
	v_mfma_f32_16x16x32_bf16 v[78:81], v[86:89], v[226:229], v[78:81]
	v_mfma_f32_16x16x32_bf16 v[74:77], v[94:97], v[226:229], v[74:77]
	s_barrier
	s_setprio 0
	s_add_i32 s66, 0, 0x14000
	s_add_i32 s63, s63, s50
	v_add_u32_e32 v0, s66, v206
	v_lshl_add_u64 v[246:247], s[44:45], 0, v[164:165]
	s_mov_b32 m0, s63
	ds_read_b128 v[230:233], v0
	ds_read_b128 v[234:237], v0 offset:1024
	ds_read_b128 v[238:241], v0 offset:2048
	ds_read_b128 v[242:245], v0 offset:3072
	global_load_lds_dwordx4 v[246:247], off
	v_lshl_add_u64 v[248:249], s[44:45], 0, v[168:169]
	s_add_i32 m0, s63, 0x2000
	s_nop 0
	global_load_lds_dwordx4 v[248:249], off
	s_barrier
	s_setprio 1
	s_waitcnt lgkmcnt(3)
	v_mfma_f32_16x16x32_bf16 v[134:137], v[230:233], v[176:179], v[134:137]
	s_waitcnt lgkmcnt(1)
	v_mfma_f32_16x16x32_bf16 v[130:133], v[238:241], v[176:179], v[130:133]
	v_mfma_f32_16x16x32_bf16 v[118:121], v[230:233], v[184:187], v[118:121]
	v_mfma_f32_16x16x32_bf16 v[114:117], v[238:241], v[184:187], v[114:117]
	v_mfma_f32_16x16x32_bf16 v[102:105], v[230:233], v[214:217], v[102:105]
	v_mfma_f32_16x16x32_bf16 v[98:101], v[238:241], v[214:217], v[98:101]
	v_mfma_f32_16x16x32_bf16 v[70:73], v[230:233], v[222:225], v[70:73]
	v_mfma_f32_16x16x32_bf16 v[66:69], v[238:241], v[222:225], v[66:69]
	v_mfma_f32_16x16x32_bf16 v[134:137], v[234:237], v[180:183], v[134:137]
	s_waitcnt lgkmcnt(0)
	v_mfma_f32_16x16x32_bf16 v[130:133], v[242:245], v[180:183], v[130:133]
	v_mfma_f32_16x16x32_bf16 v[118:121], v[234:237], v[210:213], v[118:121]
	v_mfma_f32_16x16x32_bf16 v[114:117], v[242:245], v[210:213], v[114:117]
	v_mfma_f32_16x16x32_bf16 v[102:105], v[234:237], v[218:221], v[102:105]
	v_mfma_f32_16x16x32_bf16 v[98:101], v[242:245], v[218:221], v[98:101]
	v_mfma_f32_16x16x32_bf16 v[70:73], v[234:237], v[226:229], v[70:73]
	v_mfma_f32_16x16x32_bf16 v[66:69], v[242:245], v[226:229], v[66:69]
	s_barrier
	s_setprio 0
	s_mov_b32 m0, s51
	v_lshl_add_u64 v[250:251], s[46:47], 0, v[162:163]
	ds_read_b128 v[176:179], v208 offset:16384
	ds_read_b128 v[180:183], v208 offset:17408
	ds_read_b128 v[184:187], v208 offset:18432
	ds_read_b128 v[210:213], v208 offset:19456
	ds_read_b128 v[214:217], v208 offset:20480
	ds_read_b128 v[218:221], v208 offset:21504
	ds_read_b128 v[222:225], v208 offset:22528
	ds_read_b128 v[226:229], v208 offset:23552
	global_load_lds_dwordx4 v[250:251], off
	v_lshl_add_u64 v[252:253], s[46:47], 0, v[166:167]
	s_mov_b32 m0, s52
	s_nop 0
	global_load_lds_dwordx4 v[252:253], off
	s_barrier
	s_setprio 1
	s_waitcnt lgkmcnt(7)
	v_mfma_f32_16x16x32_bf16 v[62:65], v[82:85], v[176:179], v[62:65]
	v_mfma_f32_16x16x32_bf16 v[58:61], v[90:93], v[176:179], v[58:61]
	s_waitcnt lgkmcnt(5)
	v_mfma_f32_16x16x32_bf16 v[46:49], v[82:85], v[184:187], v[46:49]
	v_mfma_f32_16x16x32_bf16 v[42:45], v[90:93], v[184:187], v[42:45]
	s_waitcnt lgkmcnt(3)
	v_mfma_f32_16x16x32_bf16 v[30:33], v[82:85], v[214:217], v[30:33]
	v_mfma_f32_16x16x32_bf16 v[26:29], v[90:93], v[214:217], v[26:29]
	s_waitcnt lgkmcnt(1)
	v_mfma_f32_16x16x32_bf16 v[14:17], v[82:85], v[222:225], v[14:17]
	v_mfma_f32_16x16x32_bf16 v[10:13], v[90:93], v[222:225], v[10:13]
	v_mfma_f32_16x16x32_bf16 v[62:65], v[86:89], v[180:183], v[62:65]
	v_mfma_f32_16x16x32_bf16 v[58:61], v[94:97], v[180:183], v[58:61]
	v_mfma_f32_16x16x32_bf16 v[46:49], v[86:89], v[210:213], v[46:49]
	v_mfma_f32_16x16x32_bf16 v[42:45], v[94:97], v[210:213], v[42:45]
	v_mfma_f32_16x16x32_bf16 v[30:33], v[86:89], v[218:221], v[30:33]
	v_mfma_f32_16x16x32_bf16 v[26:29], v[94:97], v[218:221], v[26:29]
	s_waitcnt lgkmcnt(0)
	v_mfma_f32_16x16x32_bf16 v[14:17], v[86:89], v[226:229], v[14:17]
	v_mfma_f32_16x16x32_bf16 v[10:13], v[94:97], v[226:229], v[10:13]
	s_barrier
	s_setprio 0
	s_add_u32 s64, s44, 0x40000
	s_addc_u32 s65, s45, 0
	s_add_i32 s63, s66, s50
	v_lshl_add_u64 v[82:83], s[64:65], 0, v[164:165]
	s_mov_b32 m0, s63
	s_nop 0
	global_load_lds_dwordx4 v[82:83], off
	v_lshl_add_u64 v[82:83], s[64:65], 0, v[168:169]
	s_add_i32 m0, s63, 0x2000
	s_nop 0
	global_load_lds_dwordx4 v[82:83], off
	s_waitcnt vmcnt(6)
	s_barrier
	s_setprio 1
	v_mfma_f32_16x16x32_bf16 v[54:57], v[230:233], v[176:179], v[54:57]
	v_mfma_f32_16x16x32_bf16 v[50:53], v[238:241], v[176:179], v[50:53]
	v_mfma_f32_16x16x32_bf16 v[38:41], v[230:233], v[184:187], v[38:41]
	v_mfma_f32_16x16x32_bf16 v[34:37], v[238:241], v[184:187], v[34:37]
	v_mfma_f32_16x16x32_bf16 v[22:25], v[230:233], v[214:217], v[22:25]
	v_mfma_f32_16x16x32_bf16 v[18:21], v[238:241], v[214:217], v[18:21]
	v_mfma_f32_16x16x32_bf16 v[6:9], v[230:233], v[222:225], v[6:9]
	v_mfma_f32_16x16x32_bf16 v[2:5], v[238:241], v[222:225], v[2:5]
	v_mfma_f32_16x16x32_bf16 v[54:57], v[234:237], v[180:183], v[54:57]
	v_mfma_f32_16x16x32_bf16 v[50:53], v[242:245], v[180:183], v[50:53]
	v_mfma_f32_16x16x32_bf16 v[38:41], v[234:237], v[210:213], v[38:41]
	v_mfma_f32_16x16x32_bf16 v[34:37], v[242:245], v[210:213], v[34:37]
	v_mfma_f32_16x16x32_bf16 v[22:25], v[234:237], v[218:221], v[22:25]
	v_mfma_f32_16x16x32_bf16 v[18:21], v[242:245], v[218:221], v[18:21]
	v_mfma_f32_16x16x32_bf16 v[6:9], v[234:237], v[226:229], v[6:9]
	v_mfma_f32_16x16x32_bf16 v[2:5], v[242:245], v[226:229], v[2:5]
	s_barrier
	s_setprio 0
	s_add_i32 s63, 0, 0x18000
	v_add_u32_e32 v0, s63, v206
	ds_read_b128 v[82:85], v0
	ds_read_b128 v[86:89], v0 offset:1024
	ds_read_b128 v[90:93], v0 offset:2048
	ds_read_b128 v[94:97], v0 offset:3072
	s_add_u32 s46, s46, 0x40000
	s_addc_u32 s47, s47, 0
	s_mov_b32 m0, s53
	v_lshl_add_u64 v[230:231], s[46:47], 0, v[162:163]
	ds_read_b128 v[176:179], v208 offset:32768
	ds_read_b128 v[180:183], v208 offset:33792
	ds_read_b128 v[184:187], v208 offset:34816
	ds_read_b128 v[210:213], v208 offset:35840
	ds_read_b128 v[214:217], v208 offset:36864
	ds_read_b128 v[218:221], v208 offset:37888
	ds_read_b128 v[222:225], v208 offset:38912
	ds_read_b128 v[226:229], v208 offset:39936
	global_load_lds_dwordx4 v[230:231], off
	v_lshl_add_u64 v[230:231], s[46:47], 0, v[166:167]
	s_mov_b32 m0, s54
	s_nop 0
	global_load_lds_dwordx4 v[230:231], off
	s_waitcnt lgkmcnt(8)
	s_barrier
	s_setprio 1
	s_waitcnt lgkmcnt(7)
	v_mfma_f32_16x16x32_bf16 v[142:145], v[82:85], v[176:179], v[142:145]
	v_mfma_f32_16x16x32_bf16 v[138:141], v[90:93], v[176:179], v[138:141]
	s_waitcnt lgkmcnt(5)
	v_mfma_f32_16x16x32_bf16 v[126:129], v[82:85], v[184:187], v[126:129]
	v_mfma_f32_16x16x32_bf16 v[122:125], v[90:93], v[184:187], v[122:125]
	s_waitcnt lgkmcnt(3)
	v_mfma_f32_16x16x32_bf16 v[110:113], v[82:85], v[214:217], v[110:113]
	v_mfma_f32_16x16x32_bf16 v[106:109], v[90:93], v[214:217], v[106:109]
	s_waitcnt lgkmcnt(1)
	v_mfma_f32_16x16x32_bf16 v[78:81], v[82:85], v[222:225], v[78:81]
	v_mfma_f32_16x16x32_bf16 v[74:77], v[90:93], v[222:225], v[74:77]
	v_mfma_f32_16x16x32_bf16 v[142:145], v[86:89], v[180:183], v[142:145]
	v_mfma_f32_16x16x32_bf16 v[138:141], v[94:97], v[180:183], v[138:141]
	v_mfma_f32_16x16x32_bf16 v[126:129], v[86:89], v[210:213], v[126:129]
	v_mfma_f32_16x16x32_bf16 v[122:125], v[94:97], v[210:213], v[122:125]
	v_mfma_f32_16x16x32_bf16 v[110:113], v[86:89], v[218:221], v[110:113]
	v_mfma_f32_16x16x32_bf16 v[106:109], v[94:97], v[218:221], v[106:109]
	s_waitcnt lgkmcnt(0)
	v_mfma_f32_16x16x32_bf16 v[78:81], v[86:89], v[226:229], v[78:81]
	v_mfma_f32_16x16x32_bf16 v[74:77], v[94:97], v[226:229], v[74:77]
	s_barrier
	s_setprio 0
	s_add_i32 s46, 0, 0x1c000
	s_add_i32 s47, s63, s50
	v_add_u32_e32 v0, s46, v206
	v_lshl_add_u64 v[246:247], v[246:247], 0, s[94:95]
	s_mov_b32 m0, s47
	ds_read_b128 v[230:233], v0
	ds_read_b128 v[234:237], v0 offset:1024
	ds_read_b128 v[238:241], v0 offset:2048
	ds_read_b128 v[242:245], v0 offset:3072
	global_load_lds_dwordx4 v[246:247], off
	v_lshl_add_u64 v[246:247], v[248:249], 0, s[94:95]
	s_add_i32 m0, s47, 0x2000
	s_nop 0
	global_load_lds_dwordx4 v[246:247], off
	s_barrier
	s_setprio 1
	s_waitcnt lgkmcnt(3)
	v_mfma_f32_16x16x32_bf16 v[134:137], v[230:233], v[176:179], v[134:137]
	s_waitcnt lgkmcnt(1)
	v_mfma_f32_16x16x32_bf16 v[130:133], v[238:241], v[176:179], v[130:133]
	v_mfma_f32_16x16x32_bf16 v[118:121], v[230:233], v[184:187], v[118:121]
	v_mfma_f32_16x16x32_bf16 v[114:117], v[238:241], v[184:187], v[114:117]
	v_mfma_f32_16x16x32_bf16 v[102:105], v[230:233], v[214:217], v[102:105]
	v_mfma_f32_16x16x32_bf16 v[98:101], v[238:241], v[214:217], v[98:101]
	v_mfma_f32_16x16x32_bf16 v[70:73], v[230:233], v[222:225], v[70:73]
	v_mfma_f32_16x16x32_bf16 v[66:69], v[238:241], v[222:225], v[66:69]
	v_mfma_f32_16x16x32_bf16 v[134:137], v[234:237], v[180:183], v[134:137]
	s_waitcnt lgkmcnt(0)
	v_mfma_f32_16x16x32_bf16 v[130:133], v[242:245], v[180:183], v[130:133]
	v_mfma_f32_16x16x32_bf16 v[118:121], v[234:237], v[210:213], v[118:121]
	v_mfma_f32_16x16x32_bf16 v[114:117], v[242:245], v[210:213], v[114:117]
	v_mfma_f32_16x16x32_bf16 v[102:105], v[234:237], v[218:221], v[102:105]
	v_mfma_f32_16x16x32_bf16 v[98:101], v[242:245], v[218:221], v[98:101]
	v_mfma_f32_16x16x32_bf16 v[70:73], v[234:237], v[226:229], v[70:73]
	v_mfma_f32_16x16x32_bf16 v[66:69], v[242:245], v[226:229], v[66:69]
	s_barrier
	s_setprio 0
	s_mov_b32 m0, s56
	v_lshl_add_u64 v[246:247], v[250:251], 0, s[94:95]
	ds_read_b128 v[176:179], v208 offset:49152
	ds_read_b128 v[180:183], v208 offset:50176
	ds_read_b128 v[184:187], v208 offset:51200
	ds_read_b128 v[210:213], v208 offset:52224
	ds_read_b128 v[214:217], v208 offset:53248
	ds_read_b128 v[218:221], v208 offset:54272
	ds_read_b128 v[222:225], v208 offset:55296
	ds_read_b128 v[226:229], v208 offset:56320
	global_load_lds_dwordx4 v[246:247], off
	v_lshl_add_u64 v[246:247], v[252:253], 0, s[94:95]
	s_mov_b32 m0, s57
	s_nop 0
	global_load_lds_dwordx4 v[246:247], off
	s_barrier
	s_setprio 1
	s_waitcnt lgkmcnt(7)
	v_mfma_f32_16x16x32_bf16 v[62:65], v[82:85], v[176:179], v[62:65]
	v_mfma_f32_16x16x32_bf16 v[58:61], v[90:93], v[176:179], v[58:61]
	s_waitcnt lgkmcnt(5)
	v_mfma_f32_16x16x32_bf16 v[46:49], v[82:85], v[184:187], v[46:49]
	v_mfma_f32_16x16x32_bf16 v[42:45], v[90:93], v[184:187], v[42:45]
	s_waitcnt lgkmcnt(3)
	v_mfma_f32_16x16x32_bf16 v[30:33], v[82:85], v[214:217], v[30:33]
	v_mfma_f32_16x16x32_bf16 v[26:29], v[90:93], v[214:217], v[26:29]
	s_waitcnt lgkmcnt(1)
	v_mfma_f32_16x16x32_bf16 v[14:17], v[82:85], v[222:225], v[14:17]
	v_mfma_f32_16x16x32_bf16 v[10:13], v[90:93], v[222:225], v[10:13]
	v_mfma_f32_16x16x32_bf16 v[62:65], v[86:89], v[180:183], v[62:65]
	v_mfma_f32_16x16x32_bf16 v[58:61], v[94:97], v[180:183], v[58:61]
	v_mfma_f32_16x16x32_bf16 v[46:49], v[86:89], v[210:213], v[46:49]
	v_mfma_f32_16x16x32_bf16 v[42:45], v[94:97], v[210:213], v[42:45]
	v_mfma_f32_16x16x32_bf16 v[30:33], v[86:89], v[218:221], v[30:33]
	v_mfma_f32_16x16x32_bf16 v[26:29], v[94:97], v[218:221], v[26:29]
	s_waitcnt lgkmcnt(0)
	v_mfma_f32_16x16x32_bf16 v[14:17], v[86:89], v[226:229], v[14:17]
	v_mfma_f32_16x16x32_bf16 v[10:13], v[94:97], v[226:229], v[10:13]
	s_barrier
	s_setprio 0
	s_add_u32 s44, s44, 0x40080
	s_addc_u32 s45, s45, 0
	s_add_i32 s46, s46, s50
	v_lshl_add_u64 v[82:83], s[44:45], 0, v[164:165]
	s_mov_b32 m0, s46
	s_nop 0
	global_load_lds_dwordx4 v[82:83], off
	v_lshl_add_u64 v[82:83], s[44:45], 0, v[168:169]
	s_add_i32 m0, s46, 0x2000
	s_nop 0
	global_load_lds_dwordx4 v[82:83], off
	s_waitcnt vmcnt(6)
	s_barrier
	s_setprio 1
	v_mfma_f32_16x16x32_bf16 v[54:57], v[230:233], v[176:179], v[54:57]
	v_mfma_f32_16x16x32_bf16 v[50:53], v[238:241], v[176:179], v[50:53]
	v_mfma_f32_16x16x32_bf16 v[38:41], v[230:233], v[184:187], v[38:41]
	v_mfma_f32_16x16x32_bf16 v[34:37], v[238:241], v[184:187], v[34:37]
	v_mfma_f32_16x16x32_bf16 v[22:25], v[230:233], v[214:217], v[22:25]
	v_mfma_f32_16x16x32_bf16 v[18:21], v[238:241], v[214:217], v[18:21]
	v_mfma_f32_16x16x32_bf16 v[6:9], v[230:233], v[222:225], v[6:9]
	v_mfma_f32_16x16x32_bf16 v[2:5], v[238:241], v[222:225], v[2:5]
	v_mfma_f32_16x16x32_bf16 v[54:57], v[234:237], v[180:183], v[54:57]
	v_mfma_f32_16x16x32_bf16 v[50:53], v[242:245], v[180:183], v[50:53]
	v_mfma_f32_16x16x32_bf16 v[38:41], v[234:237], v[210:213], v[38:41]
	v_mfma_f32_16x16x32_bf16 v[34:37], v[242:245], v[210:213], v[34:37]
	v_mfma_f32_16x16x32_bf16 v[22:25], v[234:237], v[218:221], v[22:25]
	v_mfma_f32_16x16x32_bf16 v[18:21], v[242:245], v[218:221], v[18:21]
	v_mfma_f32_16x16x32_bf16 v[6:9], v[234:237], v[226:229], v[6:9]
	v_mfma_f32_16x16x32_bf16 v[2:5], v[242:245], v[226:229], v[2:5]
	s_barrier
	s_setprio 0
	s_add_i32 s62, s62, 2
	s_add_u32 s60, s60, 0x100
	s_addc_u32 s61, s61, 0
	s_add_u32 s42, s42, 0x100
	s_addc_u32 s43, s43, 0
	s_cmp_gt_u32 s62, 13
	s_cbranch_scc0 .LBB0_360
	v_lshl_or_b32 v180, s0, 8, v207
	v_ashrrev_i32_e32 v181, 31, v180
	v_mov_b32_e32 v86, 0
	v_cndmask_b32_e64 v0, 0, 1, s[26:27]
	v_lshl_add_u64 v[176:177], v[180:181], 2, s[22:23]
	v_cmp_ne_u32_e64 s[0:1], 1, v0
	s_andn2_b64 vcc, exec, s[26:27]
	v_mov_b32_e32 v94, 0
	v_mov_b32_e32 v95, v86
	v_mov_b32_e32 v96, 0
	v_mov_b32_e32 v97, 0
	s_cbranch_vccnz .LBB0_363
	global_load_dwordx4 v[94:97], v[176:177], off

.LBB0_586:
	s_add_u32 s22, s20, 0xfffc0080
	s_addc_u32 s23, s21, -1
	s_add_i32 s48, 0, 0x10000
	v_add_u32_e32 v140, s48, v143
	ds_read_b128 v[162:165], v140
	ds_read_b128 v[166:169], v140 offset:1024
	ds_read_b128 v[170:173], v140 offset:2048
	ds_read_b128 v[174:177], v140 offset:3072
	s_cmp_eq_u32 s47, 12
	s_cselect_b32 s25, s9, s23
	s_cselect_b32 s24, s43, s22
	s_cselect_b32 s23, s1, s46
	s_cselect_b32 s22, s44, s45
	v_lshl_add_u64 v[140:141], s[20:21], 0, v[136:137]
	s_add_i32 m0, s3, 0xc000
	ds_read_b128 v[178:181], v145
	ds_read_b128 v[182:185], v145 offset:1024
	ds_read_b128 v[206:209], v145 offset:2048
	ds_read_b128 v[210:213], v145 offset:3072
	ds_read_b128 v[214:217], v145 offset:4096
	ds_read_b128 v[218:221], v145 offset:5120
	ds_read_b128 v[222:225], v145 offset:6144
	ds_read_b128 v[226:229], v145 offset:7168
	global_load_lds_dwordx4 v[140:141], off
	v_lshl_add_u64 v[140:141], s[20:21], 0, v[138:139]
	s_add_i32 m0, s3, 0xe000
	s_nop 0
	global_load_lds_dwordx4 v[140:141], off
	s_waitcnt lgkmcnt(8)
	s_barrier
	s_setprio 1
	s_waitcnt lgkmcnt(7)
	v_mfma_f32_16x16x32_bf16 v[122:125], v[162:165], v[178:181], v[122:125]
	v_mfma_f32_16x16x32_bf16 v[114:117], v[170:173], v[178:181], v[114:117]
	s_waitcnt lgkmcnt(5)
	v_mfma_f32_16x16x32_bf16 v[106:109], v[162:165], v[206:209], v[106:109]
	v_mfma_f32_16x16x32_bf16 v[98:101], v[170:173], v[206:209], v[98:101]
	s_waitcnt lgkmcnt(3)
	v_mfma_f32_16x16x32_bf16 v[90:93], v[162:165], v[214:217], v[90:93]
	v_mfma_f32_16x16x32_bf16 v[82:85], v[170:173], v[214:217], v[82:85]
	s_waitcnt lgkmcnt(1)
	v_mfma_f32_16x16x32_bf16 v[74:77], v[162:165], v[222:225], v[74:77]
	v_mfma_f32_16x16x32_bf16 v[66:69], v[170:173], v[222:225], v[66:69]
	v_mfma_f32_16x16x32_bf16 v[122:125], v[166:169], v[182:185], v[122:125]
	v_mfma_f32_16x16x32_bf16 v[114:117], v[174:177], v[182:185], v[114:117]
	v_mfma_f32_16x16x32_bf16 v[106:109], v[166:169], v[210:213], v[106:109]
	v_mfma_f32_16x16x32_bf16 v[98:101], v[174:177], v[210:213], v[98:101]
	v_mfma_f32_16x16x32_bf16 v[90:93], v[166:169], v[218:221], v[90:93]
	v_mfma_f32_16x16x32_bf16 v[82:85], v[174:177], v[218:221], v[82:85]
	s_waitcnt lgkmcnt(0)
	v_mfma_f32_16x16x32_bf16 v[74:77], v[166:169], v[226:229], v[74:77]
	v_mfma_f32_16x16x32_bf16 v[66:69], v[174:177], v[226:229], v[66:69]
	s_barrier
	s_setprio 0
	s_add_i32 s50, 0, 0x14000
	v_add_u32_e32 v140, s50, v143
	s_add_i32 s48, s48, s29
	ds_read_b128 v[230:233], v140
	ds_read_b128 v[234:237], v140 offset:1024
	ds_read_b128 v[238:241], v140 offset:2048
	ds_read_b128 v[242:245], v140 offset:3072
	v_lshl_add_u64 v[140:141], s[22:23], 0, v[0:1]
	s_mov_b32 m0, s48
	v_lshl_add_u64 v[186:187], s[22:23], 0, v[130:131]
	global_load_lds_dwordx4 v[140:141], off
	s_add_i32 m0, s48, 0x2000
	s_nop 0
	global_load_lds_dwordx4 v[186:187], off
	s_barrier
	s_setprio 1
	s_waitcnt lgkmcnt(3)
	v_mfma_f32_16x16x32_bf16 v[126:129], v[230:233], v[178:181], v[126:129]
	s_waitcnt lgkmcnt(1)
	v_mfma_f32_16x16x32_bf16 v[118:121], v[238:241], v[178:181], v[118:121]
	v_mfma_f32_16x16x32_bf16 v[110:113], v[230:233], v[206:209], v[110:113]
	v_mfma_f32_16x16x32_bf16 v[102:105], v[238:241], v[206:209], v[102:105]
	v_mfma_f32_16x16x32_bf16 v[94:97], v[230:233], v[214:217], v[94:97]
	v_mfma_f32_16x16x32_bf16 v[86:89], v[238:241], v[214:217], v[86:89]
	v_mfma_f32_16x16x32_bf16 v[78:81], v[230:233], v[222:225], v[78:81]
	v_mfma_f32_16x16x32_bf16 v[70:73], v[238:241], v[222:225], v[70:73]
	v_mfma_f32_16x16x32_bf16 v[126:129], v[234:237], v[182:185], v[126:129]
	s_waitcnt lgkmcnt(0)
	v_mfma_f32_16x16x32_bf16 v[118:121], v[242:245], v[182:185], v[118:121]
	v_mfma_f32_16x16x32_bf16 v[110:113], v[234:237], v[210:213], v[110:113]
	v_mfma_f32_16x16x32_bf16 v[102:105], v[242:245], v[210:213], v[102:105]
	v_mfma_f32_16x16x32_bf16 v[94:97], v[234:237], v[218:221], v[94:97]
	v_mfma_f32_16x16x32_bf16 v[86:89], v[242:245], v[218:221], v[86:89]
	v_mfma_f32_16x16x32_bf16 v[78:81], v[234:237], v[226:229], v[78:81]
	v_mfma_f32_16x16x32_bf16 v[70:73], v[242:245], v[226:229], v[70:73]
	s_barrier
	s_setprio 0
	s_mov_b32 m0, s3
	v_lshl_add_u64 v[246:247], s[24:25], 0, v[134:135]
	ds_read_b128 v[178:181], v145 offset:16384
	ds_read_b128 v[182:185], v145 offset:17408
	ds_read_b128 v[206:209], v145 offset:18432
	ds_read_b128 v[210:213], v145 offset:19456
	ds_read_b128 v[214:217], v145 offset:20480
	ds_read_b128 v[218:221], v145 offset:21504
	ds_read_b128 v[222:225], v145 offset:22528
	ds_read_b128 v[226:229], v145 offset:23552
	global_load_lds_dwordx4 v[246:247], off
	v_lshl_add_u64 v[248:249], s[24:25], 0, v[132:133]
	s_mov_b32 m0, s31
	s_nop 0
	global_load_lds_dwordx4 v[248:249], off
	s_barrier
	s_setprio 1
	s_waitcnt lgkmcnt(7)
	v_mfma_f32_16x16x32_bf16 v[58:61], v[162:165], v[178:181], v[58:61]
	v_mfma_f32_16x16x32_bf16 v[50:53], v[170:173], v[178:181], v[50:53]
	s_waitcnt lgkmcnt(5)
	v_mfma_f32_16x16x32_bf16 v[42:45], v[162:165], v[206:209], v[42:45]
	v_mfma_f32_16x16x32_bf16 v[34:37], v[170:173], v[206:209], v[34:37]
	s_waitcnt lgkmcnt(3)
	v_mfma_f32_16x16x32_bf16 v[26:29], v[162:165], v[214:217], v[26:29]
	v_mfma_f32_16x16x32_bf16 v[18:21], v[170:173], v[214:217], v[18:21]
	s_waitcnt lgkmcnt(1)
	v_mfma_f32_16x16x32_bf16 v[10:13], v[162:165], v[222:225], v[10:13]
	v_mfma_f32_16x16x32_bf16 v[6:9], v[170:173], v[222:225], v[6:9]
	v_mfma_f32_16x16x32_bf16 v[58:61], v[166:169], v[182:185], v[58:61]
	v_mfma_f32_16x16x32_bf16 v[50:53], v[174:177], v[182:185], v[50:53]
	v_mfma_f32_16x16x32_bf16 v[42:45], v[166:169], v[210:213], v[42:45]
	v_mfma_f32_16x16x32_bf16 v[34:37], v[174:177], v[210:213], v[34:37]
	v_mfma_f32_16x16x32_bf16 v[26:29], v[166:169], v[218:221], v[26:29]
	v_mfma_f32_16x16x32_bf16 v[18:21], v[174:177], v[218:221], v[18:21]
	s_waitcnt lgkmcnt(0)
	v_mfma_f32_16x16x32_bf16 v[10:13], v[166:169], v[226:229], v[10:13]
	v_mfma_f32_16x16x32_bf16 v[6:9], v[174:177], v[226:229], v[6:9]
	s_barrier
	s_setprio 0
	s_add_u32 s48, s22, 0x40000
	s_addc_u32 s49, s23, 0
	s_add_i32 s50, s50, s29
	v_lshl_add_u64 v[162:163], s[48:49], 0, v[0:1]
	s_mov_b32 m0, s50
	s_nop 0
	global_load_lds_dwordx4 v[162:163], off
	v_lshl_add_u64 v[162:163], s[48:49], 0, v[130:131]
	s_add_i32 m0, s50, 0x2000
	s_nop 0
	global_load_lds_dwordx4 v[162:163], off
	s_waitcnt vmcnt(6)
	s_barrier
	s_setprio 1
	v_mfma_f32_16x16x32_bf16 v[62:65], v[230:233], v[178:181], v[62:65]
	v_mfma_f32_16x16x32_bf16 v[54:57], v[238:241], v[178:181], v[54:57]
	v_mfma_f32_16x16x32_bf16 v[46:49], v[230:233], v[206:209], v[46:49]
	v_mfma_f32_16x16x32_bf16 v[38:41], v[238:241], v[206:209], v[38:41]
	v_mfma_f32_16x16x32_bf16 v[30:33], v[230:233], v[214:217], v[30:33]
	v_mfma_f32_16x16x32_bf16 v[22:25], v[238:241], v[214:217], v[22:25]
	v_mfma_f32_16x16x32_bf16 v[14:17], v[230:233], v[222:225], v[14:17]
	v_mfma_f32_16x16x32_bf16 v[2:5], v[238:241], v[222:225], v[2:5]
	v_mfma_f32_16x16x32_bf16 v[62:65], v[234:237], v[182:185], v[62:65]
	v_mfma_f32_16x16x32_bf16 v[54:57], v[242:245], v[182:185], v[54:57]
	v_mfma_f32_16x16x32_bf16 v[46:49], v[234:237], v[210:213], v[46:49]
	v_mfma_f32_16x16x32_bf16 v[38:41], v[242:245], v[210:213], v[38:41]
	v_mfma_f32_16x16x32_bf16 v[30:33], v[234:237], v[218:221], v[30:33]
	v_mfma_f32_16x16x32_bf16 v[22:25], v[242:245], v[218:221], v[22:25]
	v_mfma_f32_16x16x32_bf16 v[14:17], v[234:237], v[226:229], v[14:17]
	v_mfma_f32_16x16x32_bf16 v[2:5], v[242:245], v[226:229], v[2:5]
	s_barrier
	s_setprio 0
	s_add_i32 s48, 0, 0x18000
	v_add_u32_e32 v174, s48, v143
	ds_read_b128 v[162:165], v174
	ds_read_b128 v[166:169], v174 offset:1024
	ds_read_b128 v[170:173], v174 offset:2048
	ds_read_b128 v[174:177], v174 offset:3072
	s_add_u32 s24, s24, 0x40000
	s_addc_u32 s25, s25, 0
	s_mov_b32 m0, s34
	v_lshl_add_u64 v[230:231], s[24:25], 0, v[134:135]
	ds_read_b128 v[178:181], v145 offset:32768
	ds_read_b128 v[182:185], v145 offset:33792
	ds_read_b128 v[206:209], v145 offset:34816
	ds_read_b128 v[210:213], v145 offset:35840
	ds_read_b128 v[214:217], v145 offset:36864
	ds_read_b128 v[218:221], v145 offset:37888
	ds_read_b128 v[222:225], v145 offset:38912
	ds_read_b128 v[226:229], v145 offset:39936
	global_load_lds_dwordx4 v[230:231], off
	v_lshl_add_u64 v[230:231], s[24:25], 0, v[132:133]
	s_mov_b32 m0, s35
	s_nop 0
	global_load_lds_dwordx4 v[230:231], off
	s_waitcnt lgkmcnt(8)
	s_barrier
	s_setprio 1
	s_waitcnt lgkmcnt(7)
	v_mfma_f32_16x16x32_bf16 v[122:125], v[162:165], v[178:181], v[122:125]
	v_mfma_f32_16x16x32_bf16 v[114:117], v[170:173], v[178:181], v[114:117]
	s_waitcnt lgkmcnt(5)
	v_mfma_f32_16x16x32_bf16 v[106:109], v[162:165], v[206:209], v[106:109]
	v_mfma_f32_16x16x32_bf16 v[98:101], v[170:173], v[206:209], v[98:101]
	s_waitcnt lgkmcnt(3)
	v_mfma_f32_16x16x32_bf16 v[90:93], v[162:165], v[214:217], v[90:93]
	v_mfma_f32_16x16x32_bf16 v[82:85], v[170:173], v[214:217], v[82:85]
	s_waitcnt lgkmcnt(1)
	v_mfma_f32_16x16x32_bf16 v[74:77], v[162:165], v[222:225], v[74:77]
	v_mfma_f32_16x16x32_bf16 v[66:69], v[170:173], v[222:225], v[66:69]
	v_mfma_f32_16x16x32_bf16 v[122:125], v[166:169], v[182:185], v[122:125]
	v_mfma_f32_16x16x32_bf16 v[114:117], v[174:177], v[182:185], v[114:117]
	v_mfma_f32_16x16x32_bf16 v[106:109], v[166:169], v[210:213], v[106:109]
	v_mfma_f32_16x16x32_bf16 v[98:101], v[174:177], v[210:213], v[98:101]
	v_mfma_f32_16x16x32_bf16 v[90:93], v[166:169], v[218:221], v[90:93]
	v_mfma_f32_16x16x32_bf16 v[82:85], v[174:177], v[218:221], v[82:85]
	s_waitcnt lgkmcnt(0)
	v_mfma_f32_16x16x32_bf16 v[74:77], v[166:169], v[226:229], v[74:77]
	v_mfma_f32_16x16x32_bf16 v[66:69], v[174:177], v[226:229], v[66:69]
	s_barrier
	s_setprio 0
	s_add_i32 s24, 0, 0x1c000
	s_add_i32 s25, s48, s29
	v_add_u32_e32 v205, s24, v143
	v_lshl_add_u64 v[140:141], v[140:141], 0, s[94:95]
	s_mov_b32 m0, s25
	ds_read_b128 v[230:233], v205
	ds_read_b128 v[234:237], v205 offset:1024
	ds_read_b128 v[238:241], v205 offset:2048
	ds_read_b128 v[242:245], v205 offset:3072
	global_load_lds_dwordx4 v[140:141], off
	v_lshl_add_u64 v[140:141], v[186:187], 0, s[94:95]
	s_add_i32 m0, s25, 0x2000
	s_nop 0
	global_load_lds_dwordx4 v[140:141], off
	s_barrier
	s_setprio 1
	s_waitcnt lgkmcnt(3)
	v_mfma_f32_16x16x32_bf16 v[126:129], v[230:233], v[178:181], v[126:129]
	s_waitcnt lgkmcnt(1)
	v_mfma_f32_16x16x32_bf16 v[118:121], v[238:241], v[178:181], v[118:121]
	v_mfma_f32_16x16x32_bf16 v[110:113], v[230:233], v[206:209], v[110:113]
	v_mfma_f32_16x16x32_bf16 v[102:105], v[238:241], v[206:209], v[102:105]
	v_mfma_f32_16x16x32_bf16 v[94:97], v[230:233], v[214:217], v[94:97]
	v_mfma_f32_16x16x32_bf16 v[86:89], v[238:241], v[214:217], v[86:89]
	v_mfma_f32_16x16x32_bf16 v[78:81], v[230:233], v[222:225], v[78:81]
	v_mfma_f32_16x16x32_bf16 v[70:73], v[238:241], v[222:225], v[70:73]
	v_mfma_f32_16x16x32_bf16 v[126:129], v[234:237], v[182:185], v[126:129]
	s_waitcnt lgkmcnt(0)
	v_mfma_f32_16x16x32_bf16 v[118:121], v[242:245], v[182:185], v[118:121]
	v_mfma_f32_16x16x32_bf16 v[110:113], v[234:237], v[210:213], v[110:113]
	v_mfma_f32_16x16x32_bf16 v[102:105], v[242:245], v[210:213], v[102:105]
	v_mfma_f32_16x16x32_bf16 v[94:97], v[234:237], v[218:221], v[94:97]
	v_mfma_f32_16x16x32_bf16 v[86:89], v[242:245], v[218:221], v[86:89]
	v_mfma_f32_16x16x32_bf16 v[78:81], v[234:237], v[226:229], v[78:81]
	v_mfma_f32_16x16x32_bf16 v[70:73], v[242:245], v[226:229], v[70:73]
	s_barrier
	s_setprio 0
	s_mov_b32 m0, s37
	v_lshl_add_u64 v[140:141], v[246:247], 0, s[94:95]
	ds_read_b128 v[178:181], v145 offset:49152
	ds_read_b128 v[182:185], v145 offset:50176
	ds_read_b128 v[206:209], v145 offset:51200
	ds_read_b128 v[210:213], v145 offset:52224
	ds_read_b128 v[214:217], v145 offset:53248
	ds_read_b128 v[218:221], v145 offset:54272
	ds_read_b128 v[222:225], v145 offset:55296
	ds_read_b128 v[226:229], v145 offset:56320
	global_load_lds_dwordx4 v[140:141], off
	v_lshl_add_u64 v[140:141], v[248:249], 0, s[94:95]
	s_mov_b32 m0, s40
	s_nop 0
	global_load_lds_dwordx4 v[140:141], off
	s_barrier
	s_setprio 1
	s_waitcnt lgkmcnt(7)
	v_mfma_f32_16x16x32_bf16 v[58:61], v[162:165], v[178:181], v[58:61]
	v_mfma_f32_16x16x32_bf16 v[50:53], v[170:173], v[178:181], v[50:53]
	s_waitcnt lgkmcnt(5)
	v_mfma_f32_16x16x32_bf16 v[42:45], v[162:165], v[206:209], v[42:45]
	v_mfma_f32_16x16x32_bf16 v[34:37], v[170:173], v[206:209], v[34:37]
	s_waitcnt lgkmcnt(3)
	v_mfma_f32_16x16x32_bf16 v[26:29], v[162:165], v[214:217], v[26:29]
	v_mfma_f32_16x16x32_bf16 v[18:21], v[170:173], v[214:217], v[18:21]
	s_waitcnt lgkmcnt(1)
	v_mfma_f32_16x16x32_bf16 v[10:13], v[162:165], v[222:225], v[10:13]
	v_mfma_f32_16x16x32_bf16 v[6:9], v[170:173], v[222:225], v[6:9]
	v_mfma_f32_16x16x32_bf16 v[58:61], v[166:169], v[182:185], v[58:61]
	v_mfma_f32_16x16x32_bf16 v[50:53], v[174:177], v[182:185], v[50:53]
	v_mfma_f32_16x16x32_bf16 v[42:45], v[166:169], v[210:213], v[42:45]
	v_mfma_f32_16x16x32_bf16 v[34:37], v[174:177], v[210:213], v[34:37]
	v_mfma_f32_16x16x32_bf16 v[26:29], v[166:169], v[218:221], v[26:29]
	v_mfma_f32_16x16x32_bf16 v[18:21], v[174:177], v[218:221], v[18:21]
	s_waitcnt lgkmcnt(0)
	v_mfma_f32_16x16x32_bf16 v[10:13], v[166:169], v[226:229], v[10:13]
	v_mfma_f32_16x16x32_bf16 v[6:9], v[174:177], v[226:229], v[6:9]
	s_barrier
	s_setprio 0
	s_add_u32 s22, s22, 0x40080
	s_addc_u32 s23, s23, 0
	s_add_i32 s24, s24, s29
	v_lshl_add_u64 v[140:141], s[22:23], 0, v[0:1]
	s_mov_b32 m0, s24
	s_nop 0
	global_load_lds_dwordx4 v[140:141], off
	v_lshl_add_u64 v[140:141], s[22:23], 0, v[130:131]
	s_add_i32 m0, s24, 0x2000
	s_nop 0
	global_load_lds_dwordx4 v[140:141], off
	s_waitcnt vmcnt(6)
	s_barrier
	s_setprio 1
	v_mfma_f32_16x16x32_bf16 v[62:65], v[230:233], v[178:181], v[62:65]
	v_mfma_f32_16x16x32_bf16 v[54:57], v[238:241], v[178:181], v[54:57]
	v_mfma_f32_16x16x32_bf16 v[46:49], v[230:233], v[206:209], v[46:49]
	v_mfma_f32_16x16x32_bf16 v[38:41], v[238:241], v[206:209], v[38:41]
	v_mfma_f32_16x16x32_bf16 v[30:33], v[230:233], v[214:217], v[30:33]
	v_mfma_f32_16x16x32_bf16 v[22:25], v[238:241], v[214:217], v[22:25]
	v_mfma_f32_16x16x32_bf16 v[14:17], v[230:233], v[222:225], v[14:17]
	v_mfma_f32_16x16x32_bf16 v[2:5], v[238:241], v[222:225], v[2:5]
	v_mfma_f32_16x16x32_bf16 v[62:65], v[234:237], v[182:185], v[62:65]
	v_mfma_f32_16x16x32_bf16 v[54:57], v[242:245], v[182:185], v[54:57]
	v_mfma_f32_16x16x32_bf16 v[46:49], v[234:237], v[210:213], v[46:49]
	v_mfma_f32_16x16x32_bf16 v[38:41], v[242:245], v[210:213], v[38:41]
	v_mfma_f32_16x16x32_bf16 v[30:33], v[234:237], v[218:221], v[30:33]
	v_mfma_f32_16x16x32_bf16 v[22:25], v[242:245], v[218:221], v[22:25]
	v_mfma_f32_16x16x32_bf16 v[14:17], v[234:237], v[226:229], v[14:17]
	v_mfma_f32_16x16x32_bf16 v[2:5], v[242:245], v[226:229], v[2:5]
	s_barrier
	s_setprio 0
	s_add_i32 s47, s47, 2
	s_add_u32 s20, s20, 0x100
	s_addc_u32 s21, s21, 0
	s_add_u32 s45, s45, 0x100
	s_addc_u32 s46, s46, 0
	s_cmp_gt_u32 s47, 13
	s_cbranch_scc0 .LBB0_586
	v_pk_mul_f32 v[164:165], v[122:123], s[4:5] op_sel_hi:[1,0]
	v_pk_mul_f32 v[122:123], v[122:123], v[126:127]
	v_pk_mul_f32 v[126:127], v[114:115], s[4:5] op_sel_hi:[1,0]
	v_pk_mul_f32 v[114:115], v[114:115], v[118:119]
	v_exp_f32_e32 v126, v126
	v_exp_f32_e32 v127, v127
	v_pk_mul_f32 v[128:129], v[124:125], v[128:129]
	v_pk_mul_f32 v[124:125], v[124:125], s[4:5] op_sel_hi:[1,0]
	v_exp_f32_e32 v164, v164
	v_pk_add_f32 v[126:127], v[126:127], 1.0 op_sel_hi:[1,0]
	v_exp_f32_e32 v165, v165
	v_rcp_f32_e32 v126, v126
	v_rcp_f32_e32 v127, v127
	v_exp_f32_e32 v124, v124
	v_exp_f32_e32 v125, v125
	v_pk_add_f32 v[164:165], v[164:165], 1.0 op_sel_hi:[1,0]
	v_pk_mul_f32 v[118:119], v[126:127], v[114:115]
	v_pk_mul_f32 v[114:115], v[116:117], s[4:5] op_sel_hi:[1,0]
	v_pk_add_f32 v[124:125], v[124:125], 1.0 op_sel_hi:[1,0]
	v_exp_f32_e32 v114, v114
	v_exp_f32_e32 v115, v115
	v_rcp_f32_e32 v164, v164
	v_rcp_f32_e32 v165, v165
	v_rcp_f32_e32 v124, v124
	v_pk_add_f32 v[114:115], v[114:115], 1.0 op_sel_hi:[1,0]
	v_rcp_f32_e32 v125, v125
	v_rcp_f32_e32 v114, v114
	v_rcp_f32_e32 v115, v115
	v_lshl_or_b32 v140, s42, 7, v144
	v_ashrrev_i32_e32 v141, 31, v140
	v_lshl_add_u32 v162, s2, 8, v142
	v_lshl_add_u64 v[140:141], v[140:141], 1, s[14:15]
	v_pk_mul_f32 v[120:121], v[116:117], v[120:121]
	v_pk_mul_f32 v[122:123], v[164:165], v[122:123]
	v_pk_mul_f32 v[124:125], v[124:125], v[128:129]
	v_pk_mul_f32 v[120:121], v[114:115], v[120:121]
	v_mad_i64_i32 v[126:127], s[20:21], v162, s91, v[140:141]
	v_cvt_pk_bf16_f32 v114, v122, v123
	v_cvt_pk_bf16_f32 v115, v124, v125
	v_cvt_pk_bf16_f32 v116, v118, v119
	v_cvt_pk_bf16_f32 v117, v120, v121
	global_store_dwordx4 v[126:127], v[114:117], off
	v_pk_mul_f32 v[112:113], v[108:109], v[112:113]
	v_pk_mul_f32 v[108:109], v[108:109], s[4:5] op_sel_hi:[1,0]
	v_pk_mul_f32 v[114:115], v[106:107], s[4:5] op_sel_hi:[1,0]
	v_pk_mul_f32 v[106:107], v[106:107], v[110:111]
	v_pk_mul_f32 v[110:111], v[98:99], s[4:5] op_sel_hi:[1,0]
	v_pk_mul_f32 v[98:99], v[98:99], v[102:103]
	v_exp_f32_e32 v110, v110
	v_exp_f32_e32 v111, v111
	v_exp_f32_e32 v114, v114
	v_exp_f32_e32 v115, v115
	v_exp_f32_e32 v108, v108
	v_pk_add_f32 v[110:111], v[110:111], 1.0 op_sel_hi:[1,0]
	v_exp_f32_e32 v109, v109
	v_rcp_f32_e32 v110, v110
	v_rcp_f32_e32 v111, v111
	v_pk_add_f32 v[114:115], v[114:115], 1.0 op_sel_hi:[1,0]
	v_pk_add_f32 v[108:109], v[108:109], 1.0 op_sel_hi:[1,0]
	v_rcp_f32_e32 v114, v114
	v_pk_mul_f32 v[102:103], v[110:111], v[98:99]
	v_pk_mul_f32 v[98:99], v[100:101], s[4:5] op_sel_hi:[1,0]
	v_rcp_f32_e32 v115, v115
	v_exp_f32_e32 v98, v98
	v_exp_f32_e32 v99, v99
	v_rcp_f32_e32 v108, v108
	v_rcp_f32_e32 v109, v109
	v_or_b32_e32 v116, 16, v162
	v_pk_add_f32 v[98:99], v[98:99], 1.0 op_sel_hi:[1,0]
	v_pk_mul_f32 v[104:105], v[100:101], v[104:105]
	v_rcp_f32_e32 v98, v98
	v_rcp_f32_e32 v99, v99
	v_pk_mul_f32 v[106:107], v[114:115], v[106:107]
	v_pk_mul_f32 v[108:109], v[108:109], v[112:113]
	v_mad_i64_i32 v[110:111], s[20:21], v116, s91, v[140:141]
	v_pk_mul_f32 v[104:105], v[98:99], v[104:105]
	v_cvt_pk_bf16_f32 v98, v106, v107
	v_cvt_pk_bf16_f32 v99, v108, v109
	v_cvt_pk_bf16_f32 v100, v102, v103
	v_pk_mul_f32 v[96:97], v[92:93], v[96:97]
	v_cvt_pk_bf16_f32 v101, v104, v105
	global_store_dwordx4 v[110:111], v[98:101], off
	v_pk_mul_f32 v[92:93], v[92:93], s[4:5] op_sel_hi:[1,0]
	v_pk_mul_f32 v[88:89], v[84:85], v[88:89]
	v_pk_mul_f32 v[98:99], v[90:91], s[4:5] op_sel_hi:[1,0]
	v_pk_mul_f32 v[90:91], v[90:91], v[94:95]
	v_pk_mul_f32 v[94:95], v[82:83], s[4:5] op_sel_hi:[1,0]
	v_pk_mul_f32 v[82:83], v[82:83], v[86:87]
	v_exp_f32_e32 v94, v94
	v_exp_f32_e32 v95, v95
	v_exp_f32_e32 v98, v98
	v_exp_f32_e32 v99, v99
	v_exp_f32_e32 v92, v92
	v_pk_add_f32 v[94:95], v[94:95], 1.0 op_sel_hi:[1,0]
	v_exp_f32_e32 v93, v93
	v_rcp_f32_e32 v94, v94
	v_rcp_f32_e32 v95, v95
	v_pk_add_f32 v[98:99], v[98:99], 1.0 op_sel_hi:[1,0]
	v_pk_add_f32 v[92:93], v[92:93], 1.0 op_sel_hi:[1,0]
	v_rcp_f32_e32 v98, v98
	v_pk_mul_f32 v[86:87], v[94:95], v[82:83]
	v_pk_mul_f32 v[82:83], v[84:85], s[4:5] op_sel_hi:[1,0]
	v_rcp_f32_e32 v99, v99
	v_exp_f32_e32 v82, v82
	v_exp_f32_e32 v83, v83
	v_rcp_f32_e32 v92, v92
	v_rcp_f32_e32 v93, v93
	v_or_b32_e32 v100, 32, v162
	v_pk_add_f32 v[82:83], v[82:83], 1.0 op_sel_hi:[1,0]
	v_pk_mul_f32 v[90:91], v[98:99], v[90:91]
	v_rcp_f32_e32 v82, v82
	v_rcp_f32_e32 v83, v83
	v_pk_mul_f32 v[92:93], v[92:93], v[96:97]
	v_mad_i64_i32 v[94:95], s[20:21], v100, s91, v[140:141]
	v_pk_mul_f32 v[88:89], v[82:83], v[88:89]
	v_cvt_pk_bf16_f32 v82, v90, v91
	v_cvt_pk_bf16_f32 v83, v92, v93
	v_cvt_pk_bf16_f32 v84, v86, v87
	v_pk_mul_f32 v[80:81], v[76:77], v[80:81]
	v_cvt_pk_bf16_f32 v85, v88, v89
	global_store_dwordx4 v[94:95], v[82:85], off
	v_pk_mul_f32 v[76:77], v[76:77], s[4:5] op_sel_hi:[1,0]
	v_pk_mul_f32 v[72:73], v[68:69], v[72:73]
	v_pk_mul_f32 v[82:83], v[74:75], s[4:5] op_sel_hi:[1,0]
	v_pk_mul_f32 v[74:75], v[74:75], v[78:79]
	v_pk_mul_f32 v[78:79], v[66:67], s[4:5] op_sel_hi:[1,0]
	v_pk_mul_f32 v[66:67], v[66:67], v[70:71]
	v_exp_f32_e32 v78, v78
	v_exp_f32_e32 v79, v79
	v_exp_f32_e32 v82, v82
	v_exp_f32_e32 v83, v83
	v_exp_f32_e32 v76, v76
	v_pk_add_f32 v[78:79], v[78:79], 1.0 op_sel_hi:[1,0]
	v_exp_f32_e32 v77, v77
	v_rcp_f32_e32 v78, v78
	v_rcp_f32_e32 v79, v79
	v_pk_add_f32 v[82:83], v[82:83], 1.0 op_sel_hi:[1,0]
	v_pk_add_f32 v[76:77], v[76:77], 1.0 op_sel_hi:[1,0]
	v_rcp_f32_e32 v82, v82
	v_pk_mul_f32 v[70:71], v[78:79], v[66:67]
	v_pk_mul_f32 v[66:67], v[68:69], s[4:5] op_sel_hi:[1,0]
	v_rcp_f32_e32 v83, v83
	v_exp_f32_e32 v66, v66
	v_exp_f32_e32 v67, v67
	v_rcp_f32_e32 v76, v76
	v_rcp_f32_e32 v77, v77
	v_or_b32_e32 v84, 48, v162
	v_pk_add_f32 v[66:67], v[66:67], 1.0 op_sel_hi:[1,0]
	v_pk_mul_f32 v[74:75], v[82:83], v[74:75]
	v_rcp_f32_e32 v66, v66
	v_rcp_f32_e32 v67, v67
	v_pk_mul_f32 v[76:77], v[76:77], v[80:81]
	v_mad_i64_i32 v[78:79], s[20:21], v84, s91, v[140:141]
	v_pk_mul_f32 v[72:73], v[66:67], v[72:73]
	v_cvt_pk_bf16_f32 v66, v74, v75
	v_cvt_pk_bf16_f32 v67, v76, v77
	v_cvt_pk_bf16_f32 v68, v70, v71
	v_pk_mul_f32 v[64:65], v[60:61], v[64:65]
	v_cvt_pk_bf16_f32 v69, v72, v73
	global_store_dwordx4 v[78:79], v[66:69], off
	v_pk_mul_f32 v[60:61], v[60:61], s[4:5] op_sel_hi:[1,0]
	v_pk_mul_f32 v[56:57], v[52:53], v[56:57]
	v_pk_mul_f32 v[66:67], v[58:59], s[4:5] op_sel_hi:[1,0]
	v_pk_mul_f32 v[58:59], v[58:59], v[62:63]
	v_pk_mul_f32 v[62:63], v[50:51], s[4:5] op_sel_hi:[1,0]
	v_pk_mul_f32 v[50:51], v[50:51], v[54:55]
	v_exp_f32_e32 v62, v62
	v_exp_f32_e32 v63, v63
	v_exp_f32_e32 v66, v66
	v_exp_f32_e32 v67, v67
	v_exp_f32_e32 v60, v60
	v_pk_add_f32 v[62:63], v[62:63], 1.0 op_sel_hi:[1,0]
	v_exp_f32_e32 v61, v61
	v_rcp_f32_e32 v62, v62
	v_rcp_f32_e32 v63, v63
	v_pk_add_f32 v[66:67], v[66:67], 1.0 op_sel_hi:[1,0]
	v_pk_add_f32 v[60:61], v[60:61], 1.0 op_sel_hi:[1,0]
	v_rcp_f32_e32 v66, v66
	v_pk_mul_f32 v[54:55], v[62:63], v[50:51]
	v_pk_mul_f32 v[50:51], v[52:53], s[4:5] op_sel_hi:[1,0]
	v_rcp_f32_e32 v67, v67
	v_exp_f32_e32 v50, v50
	v_exp_f32_e32 v51, v51
	v_rcp_f32_e32 v60, v60
	v_rcp_f32_e32 v61, v61
	v_add_u32_e32 v68, 0x80, v162
	v_pk_add_f32 v[50:51], v[50:51], 1.0 op_sel_hi:[1,0]
	v_pk_mul_f32 v[58:59], v[66:67], v[58:59]
	v_rcp_f32_e32 v50, v50
	v_rcp_f32_e32 v51, v51
	v_pk_mul_f32 v[60:61], v[60:61], v[64:65]
	v_mad_i64_i32 v[62:63], s[20:21], v68, s91, v[140:141]
	v_pk_mul_f32 v[56:57], v[50:51], v[56:57]
	v_cvt_pk_bf16_f32 v50, v58, v59
	v_cvt_pk_bf16_f32 v51, v60, v61
	v_cvt_pk_bf16_f32 v52, v54, v55
	v_pk_mul_f32 v[48:49], v[44:45], v[48:49]
	v_cvt_pk_bf16_f32 v53, v56, v57
	global_store_dwordx4 v[62:63], v[50:53], off
	v_pk_mul_f32 v[44:45], v[44:45], s[4:5] op_sel_hi:[1,0]
	v_pk_mul_f32 v[40:41], v[36:37], v[40:41]
	v_pk_mul_f32 v[50:51], v[42:43], s[4:5] op_sel_hi:[1,0]
	v_pk_mul_f32 v[42:43], v[42:43], v[46:47]
	v_pk_mul_f32 v[46:47], v[34:35], s[4:5] op_sel_hi:[1,0]
	v_pk_mul_f32 v[34:35], v[34:35], v[38:39]
	v_exp_f32_e32 v46, v46
	v_exp_f32_e32 v47, v47
	v_exp_f32_e32 v50, v50
	v_exp_f32_e32 v51, v51
	v_exp_f32_e32 v44, v44
	v_pk_add_f32 v[46:47], v[46:47], 1.0 op_sel_hi:[1,0]
	v_exp_f32_e32 v45, v45
	v_rcp_f32_e32 v46, v46
	v_rcp_f32_e32 v47, v47
	v_pk_add_f32 v[50:51], v[50:51], 1.0 op_sel_hi:[1,0]
	v_pk_add_f32 v[44:45], v[44:45], 1.0 op_sel_hi:[1,0]
	v_rcp_f32_e32 v50, v50
	v_pk_mul_f32 v[38:39], v[46:47], v[34:35]
	v_pk_mul_f32 v[34:35], v[36:37], s[4:5] op_sel_hi:[1,0]
	v_rcp_f32_e32 v51, v51
	v_exp_f32_e32 v34, v34
	v_exp_f32_e32 v35, v35
	v_rcp_f32_e32 v44, v44
	v_rcp_f32_e32 v45, v45
	v_add_u32_e32 v52, 0x90, v162
	v_pk_add_f32 v[34:35], v[34:35], 1.0 op_sel_hi:[1,0]
	v_pk_mul_f32 v[42:43], v[50:51], v[42:43]
	v_rcp_f32_e32 v34, v34
	v_rcp_f32_e32 v35, v35
	v_pk_mul_f32 v[44:45], v[44:45], v[48:49]
	v_mad_i64_i32 v[46:47], s[20:21], v52, s91, v[140:141]
	v_pk_mul_f32 v[40:41], v[34:35], v[40:41]
	v_cvt_pk_bf16_f32 v34, v42, v43
	v_cvt_pk_bf16_f32 v35, v44, v45
	v_cvt_pk_bf16_f32 v36, v38, v39
	v_pk_mul_f32 v[32:33], v[28:29], v[32:33]
	v_cvt_pk_bf16_f32 v37, v40, v41
	global_store_dwordx4 v[46:47], v[34:37], off
	v_pk_mul_f32 v[28:29], v[28:29], s[4:5] op_sel_hi:[1,0]
	v_pk_mul_f32 v[24:25], v[20:21], v[24:25]
	v_pk_mul_f32 v[34:35], v[26:27], s[4:5] op_sel_hi:[1,0]
	v_pk_mul_f32 v[26:27], v[26:27], v[30:31]
	v_pk_mul_f32 v[30:31], v[18:19], s[4:5] op_sel_hi:[1,0]
	v_pk_mul_f32 v[18:19], v[18:19], v[22:23]
	v_exp_f32_e32 v30, v30
	v_exp_f32_e32 v31, v31
	v_exp_f32_e32 v34, v34
	v_exp_f32_e32 v35, v35
	v_exp_f32_e32 v28, v28
	v_pk_add_f32 v[30:31], v[30:31], 1.0 op_sel_hi:[1,0]
	v_exp_f32_e32 v29, v29
	v_rcp_f32_e32 v30, v30
	v_rcp_f32_e32 v31, v31
	v_pk_add_f32 v[34:35], v[34:35], 1.0 op_sel_hi:[1,0]
	v_pk_add_f32 v[28:29], v[28:29], 1.0 op_sel_hi:[1,0]
	v_rcp_f32_e32 v34, v34
	v_pk_mul_f32 v[22:23], v[30:31], v[18:19]
	v_pk_mul_f32 v[18:19], v[20:21], s[4:5] op_sel_hi:[1,0]
	v_rcp_f32_e32 v35, v35
	v_exp_f32_e32 v18, v18
	v_exp_f32_e32 v19, v19
	v_rcp_f32_e32 v28, v28
	v_rcp_f32_e32 v29, v29
	v_add_u32_e32 v36, 0xa0, v162
	v_pk_add_f32 v[18:19], v[18:19], 1.0 op_sel_hi:[1,0]
	v_pk_mul_f32 v[26:27], v[34:35], v[26:27]
	v_rcp_f32_e32 v18, v18
	v_rcp_f32_e32 v19, v19
	v_pk_mul_f32 v[28:29], v[28:29], v[32:33]
	v_mad_i64_i32 v[30:31], s[20:21], v36, s91, v[140:141]
	v_pk_mul_f32 v[24:25], v[18:19], v[24:25]
	v_cvt_pk_bf16_f32 v18, v26, v27
	v_cvt_pk_bf16_f32 v19, v28, v29
	v_cvt_pk_bf16_f32 v20, v22, v23
	v_pk_mul_f32 v[2:3], v[6:7], v[2:3]
	v_cvt_pk_bf16_f32 v21, v24, v25
	global_store_dwordx4 v[30:31], v[18:21], off
	v_pk_mul_f32 v[16:17], v[12:13], v[16:17]
	v_pk_mul_f32 v[12:13], v[12:13], s[4:5] op_sel_hi:[1,0]
	v_pk_mul_f32 v[18:19], v[10:11], s[4:5] op_sel_hi:[1,0]
	v_pk_mul_f32 v[10:11], v[10:11], v[14:15]
	v_pk_mul_f32 v[14:15], v[6:7], s[4:5] op_sel_hi:[1,0]
	v_exp_f32_e32 v18, v18
	v_exp_f32_e32 v14, v14
	v_exp_f32_e32 v15, v15
	v_exp_f32_e32 v19, v19
	v_exp_f32_e32 v12, v12
	v_exp_f32_e32 v13, v13
	v_pk_add_f32 v[14:15], v[14:15], 1.0 op_sel_hi:[1,0]
	v_pk_add_f32 v[18:19], v[18:19], 1.0 op_sel_hi:[1,0]
	v_rcp_f32_e32 v14, v14
	v_rcp_f32_e32 v15, v15
	v_pk_add_f32 v[12:13], v[12:13], 1.0 op_sel_hi:[1,0]
	v_rcp_f32_e32 v18, v18
	v_rcp_f32_e32 v19, v19
	v_pk_mul_f32 v[6:7], v[14:15], v[2:3]
	v_pk_mul_f32 v[2:3], v[8:9], s[4:5] op_sel_hi:[1,0]
	v_rcp_f32_e32 v12, v12
	v_exp_f32_e32 v2, v2
	v_exp_f32_e32 v3, v3
	v_rcp_f32_e32 v13, v13
	v_add_u32_e32 v20, 0xb0, v162
	v_mad_i64_i32 v[14:15], s[20:21], v20, s91, v[140:141]
	v_pk_add_f32 v[2:3], v[2:3], 1.0 op_sel_hi:[1,0]
	v_pk_mul_f32 v[4:5], v[8:9], v[4:5]
	v_rcp_f32_e32 v2, v2
	v_rcp_f32_e32 v3, v3
	s_and_b64 vcc, exec, s[38:39]
	s_mov_b32 s42, s0
	s_mov_b32 s2, s8
	s_mov_b64 s[22:23], s[18:19]
	s_mov_b64 s[20:21], s[16:17]
	v_pk_mul_f32 v[10:11], v[18:19], v[10:11]
	v_pk_mul_f32 v[12:13], v[12:13], v[16:17]
	v_pk_mul_f32 v[8:9], v[2:3], v[4:5]
	v_cvt_pk_bf16_f32 v2, v10, v11
	v_cvt_pk_bf16_f32 v3, v12, v13
	v_cvt_pk_bf16_f32 v4, v6, v7
	s_nop 0
	v_cvt_pk_bf16_f32 v5, v8, v9
	global_store_dwordx4 v[14:15], v[2:5], off
	s_cbranch_vccz .LBB0_579
	s_waitcnt vmcnt(0)
	s_cmpk_gt_u32 s26, 0xff
	s_cbranch_scc1 .LBB0_590
	s_barrier
